# K-loop: s_barrier moved 4 MFMAs early with s_setprio 2 for the tail (early handover between wave halves)
# baseline (speedup 1.0000x reference)
;     __device__ float mid(int row) const { return rg(row) / ra(row); }
; #define PG8_STAGE(bufoff, gbase, voff) do { const char* gb_ = (const char*)(gbase); asm volatile("" : "+s"(gb_));     \
;         _Pragma("unroll") for (int _i = 0; _i < 2; ++_i) \
;         __builtin_amdgcn_global_load_lds((const unsigned*)(gb_ + (voff)[_i]), (PG8_LAS unsigned*)(lds + (bufoff) + ldsw + _i * 8192), 16, 0, 0); } while (0)
; #define PG8_BAR __builtin_amdgcn_s_barrier()
; template <class Epi, class Sched, bool ALIGN_EPI = false, bool SP2 = false>
; __device__ __forceinline__ void gemm_phase(PG8_LAS unsigned char* lds, const Gemm g, const Sched& S, const Epi& E, int wid0) {
;     ...
;         for (int t = 0; t < nt; t += 2) {
;             const bool last = (t == nt - 2);
;             const char* a1 = cA + (size_t)(t + 1) * kstep;
;             const char* a2 = last ? nA : cA + (size_t)(t + 2) * kstep; const char* b2 = last ? nB : cB + (size_t)(t + 2) * kstep;
;             const char* a3 = a2 + kstep; const char* b3 = b2 + kstep;
;             if (last && has_next) S.a_ready(nxt);
;             if constexpr (Epi::HAS_MID) { if (t == Epi::MID_T) E.mid(acc, cur, wr, fr); }
;             unsigned vA_[2] = {voffA[0], voffA[1]}, vB_[2] = {voffB[0], voffB[1]};
;             asm volatile("" : "+v"(vA_[0]), "+v"(vA_[1]), "+v"(vB_[0]), "+v"(vB_[1]));
;             if constexpr (SP2) {
;             PG8_LDB(B0, 0, 0); PG8_LDB(B1, 0, 1); PG8_SCHED; PG8_LDA(At, 0, 0); PG8_STAGE(PG8_SA(1, 1), a1 + hstepA, vA_);
;             PG8_WAIT_V(8); PG8_WAIT_L(0); PG8_BAR; PG8_MMA(0, 0, At, B0); PG8_MMA(0, 1, At, B1); PG8_BAR; PG8_SCHED;
;             PG8_LDA(At, 0, 1); PG8_STAGE(PG8_SB(0, 0), b2, vB_); PG8_STAGE(PG8_SB(0, 1), b2 + hstep, vB_); PG8_STAGE(PG8_SA(0, 0), a2, vA_);
;             PG8_WAIT_V(8); PG8_WAIT_L(0); PG8_BAR; PG8_MMA(1, 0, At, B0); PG8_MMA(1, 1, At, B1); PG8_BAR; PG8_SCHED;
;             PG8_LDB(B0, 1, 0); PG8_LDB(B1, 1, 1); PG8_SCHED; PG8_LDA(At, 1, 0); PG8_STAGE(PG8_SA(0, 1), a2 + hstepA, vA_);
;             PG8_WAIT_V(8); PG8_WAIT_L(0); PG8_BAR; PG8_MMA(0, 0, At, B0); PG8_MMA(0, 1, At, B1); PG8_BAR; PG8_SCHED;
;             PG8_LDA(At, 1, 1); PG8_STAGE(PG8_SB(1, 0), b3, vB_); PG8_STAGE(PG8_SB(1, 1), b3 + hstep, vB_); PG8_STAGE(PG8_SA(1, 0), a3, vA_);
;             PG8_WAIT_V(8); PG8_WAIT_L(0); PG8_BAR; PG8_MMA(1, 0, At, B0); PG8_MMA(1, 1, At, B1); PG8_BAR; PG8_SCHED;
.LBB13_358:
	v_mov_b32_e32 v8, v174
	v_mov_b32_e32 v220, v200
	v_mov_b32_e32 v221, v176
	v_mov_b32_e32 v222, v178
	ds_read_b128 v[82:85], v201
	ds_read_b128 v[90:93], v201 offset:1024
	ds_read_b128 v[94:97], v201 offset:2048
	ds_read_b128 v[102:105], v201 offset:3072
	ds_read_b128 v[158:161], v202
	ds_read_b128 v[162:165], v202 offset:1024
	ds_read_b128 v[166:169], v202 offset:2048
	ds_read_b128 v[170:173], v202 offset:3072
	s_add_u32 s8, s2, 0x100
	s_addc_u32 s9, s3, 0
	s_cmp_eq_u32 s82, 12
	s_cselect_b32 s58, s78, s8
	s_cselect_b32 s59, s47, s9
	s_cselect_b32 s12, s79, s80
	s_cselect_b32 s13, s49, s81
	s_add_u32 s10, s58, 0x80
	s_addc_u32 s11, s59, 0
	s_add_u32 s2, s2, 0x40080
	s_addc_u32 s3, s3, 0
	s_add_i32 m0, s57, 0xc000
	ds_read_b128 v[180:183], v203
	ds_read_b128 v[184:187], v203 offset:1024
	ds_read_b128 v[188:191], v203 offset:2048
	ds_read_b128 v[192:195], v203 offset:3072
	ds_read_b128 v[204:207], v203 offset:4096
	ds_read_b128 v[208:211], v203 offset:5120
	ds_read_b128 v[212:215], v203 offset:6144
	ds_read_b128 v[216:219], v203 offset:7168
	s_nop 0
	global_load_lds_dwordx4 v8, s[2:3]
	s_add_i32 m0, s57, 0xe000
	s_nop 0
	global_load_lds_dwordx4 v221, s[2:3]
	s_waitcnt vmcnt(8)
	s_waitcnt lgkmcnt(0)
	s_barrier
	s_setprio 1
	s_waitcnt lgkmcnt(0)
	v_mfma_f32_16x16x32_bf16 v[154:157], v[82:85], v[180:183], v[154:157]
	v_mfma_f32_16x16x32_bf16 v[150:153], v[94:97], v[180:183], v[150:153]
	v_mfma_f32_16x16x32_bf16 v[138:141], v[82:85], v[188:191], v[138:141]
	v_mfma_f32_16x16x32_bf16 v[134:137], v[94:97], v[188:191], v[134:137]
	v_mfma_f32_16x16x32_bf16 v[122:125], v[82:85], v[204:207], v[122:125]
	v_mfma_f32_16x16x32_bf16 v[118:121], v[94:97], v[204:207], v[118:121]
	v_mfma_f32_16x16x32_bf16 v[106:109], v[82:85], v[212:215], v[106:109]
	v_mfma_f32_16x16x32_bf16 v[98:101], v[94:97], v[212:215], v[98:101]
	v_mfma_f32_16x16x32_bf16 v[154:157], v[90:93], v[184:187], v[154:157]
	v_mfma_f32_16x16x32_bf16 v[150:153], v[102:105], v[184:187], v[150:153]
	v_mfma_f32_16x16x32_bf16 v[138:141], v[90:93], v[192:195], v[138:141]
	v_mfma_f32_16x16x32_bf16 v[134:137], v[102:105], v[192:195], v[134:137]
	v_mfma_f32_16x16x32_bf16 v[122:125], v[90:93], v[208:211], v[122:125]
	v_mfma_f32_16x16x32_bf16 v[118:121], v[102:105], v[208:211], v[118:121]
	v_mfma_f32_16x16x32_bf16 v[106:109], v[90:93], v[216:219], v[106:109]
	v_mfma_f32_16x16x32_bf16 v[98:101], v[102:105], v[216:219], v[98:101]
	s_setprio 0
	s_setprio 1
	v_mfma_f32_16x16x32_bf16 v[146:149], v[158:161], v[180:183], v[146:149]
	v_mfma_f32_16x16x32_bf16 v[142:145], v[166:169], v[180:183], v[142:145]
	v_mfma_f32_16x16x32_bf16 v[130:133], v[158:161], v[188:191], v[130:133]
	v_mfma_f32_16x16x32_bf16 v[126:129], v[166:169], v[188:191], v[126:129]
	v_mfma_f32_16x16x32_bf16 v[114:117], v[158:161], v[204:207], v[114:117]
	v_mfma_f32_16x16x32_bf16 v[110:113], v[166:169], v[204:207], v[110:113]
	v_mfma_f32_16x16x32_bf16 v[86:89], v[158:161], v[212:215], v[86:89]
	v_mfma_f32_16x16x32_bf16 v[78:81], v[166:169], v[212:215], v[78:81]
	v_mfma_f32_16x16x32_bf16 v[146:149], v[162:165], v[184:187], v[146:149]
	v_mfma_f32_16x16x32_bf16 v[142:145], v[170:173], v[184:187], v[142:145]
	v_mfma_f32_16x16x32_bf16 v[130:133], v[162:165], v[192:195], v[130:133]
	v_mfma_f32_16x16x32_bf16 v[126:129], v[170:173], v[192:195], v[126:129]
	s_setprio 2
	s_barrier
	v_mfma_f32_16x16x32_bf16 v[114:117], v[162:165], v[208:211], v[114:117]
	v_mfma_f32_16x16x32_bf16 v[110:113], v[170:173], v[208:211], v[110:113]
	v_mfma_f32_16x16x32_bf16 v[86:89], v[162:165], v[216:219], v[86:89]
	v_mfma_f32_16x16x32_bf16 v[78:81], v[170:173], v[216:219], v[78:81]
	s_setprio 0
	s_add_i32 s83, s74, s55
	s_mov_b64 s[2:3], s[12:13]
	s_mov_b32 m0, s83
	ds_read_b128 v[180:183], v203 offset:16384
	ds_read_b128 v[184:187], v203 offset:17408
	ds_read_b128 v[188:191], v203 offset:18432
	ds_read_b128 v[192:195], v203 offset:19456
	ds_read_b128 v[204:207], v203 offset:20480
	ds_read_b128 v[208:211], v203 offset:21504
	ds_read_b128 v[212:215], v203 offset:22528
	ds_read_b128 v[216:219], v203 offset:23552
	s_nop 0
	global_load_lds_dwordx4 v220, s[2:3]
	s_add_i32 m0, s83, 0x2000
	s_nop 0
	global_load_lds_dwordx4 v222, s[2:3]
	s_add_u32 s2, s12, 0x40000
	s_addc_u32 s3, s13, 0
	s_add_i32 s83, s75, s55
	s_mov_b32 m0, s83
	s_nop 0
	global_load_lds_dwordx4 v220, s[2:3]
	s_add_i32 m0, s83, 0x2000
	s_nop 0
	global_load_lds_dwordx4 v222, s[2:3]
	s_mov_b64 s[2:3], s[58:59]
	s_mov_b32 m0, s57
	s_nop 0
	global_load_lds_dwordx4 v8, s[2:3]
	s_mov_b32 m0, s63
	s_nop 0
	global_load_lds_dwordx4 v221, s[2:3]
	s_waitcnt vmcnt(8)
	s_waitcnt lgkmcnt(0)
	s_barrier
	s_setprio 1
	s_waitcnt lgkmcnt(0)
	v_mfma_f32_16x16x32_bf16 v[74:77], v[82:85], v[180:183], v[74:77]
	v_mfma_f32_16x16x32_bf16 v[70:73], v[94:97], v[180:183], v[70:73]
	v_mfma_f32_16x16x32_bf16 v[58:61], v[82:85], v[188:191], v[58:61]
	v_mfma_f32_16x16x32_bf16 v[54:57], v[94:97], v[188:191], v[54:57]
	v_mfma_f32_16x16x32_bf16 v[42:45], v[82:85], v[204:207], v[42:45]
	v_mfma_f32_16x16x32_bf16 v[38:41], v[94:97], v[204:207], v[38:41]
	v_mfma_f32_16x16x32_bf16 v[26:29], v[82:85], v[212:215], v[26:29]
	v_mfma_f32_16x16x32_bf16 v[22:25], v[94:97], v[212:215], v[22:25]
	v_mfma_f32_16x16x32_bf16 v[74:77], v[90:93], v[184:187], v[74:77]
	v_mfma_f32_16x16x32_bf16 v[70:73], v[102:105], v[184:187], v[70:73]
	v_mfma_f32_16x16x32_bf16 v[58:61], v[90:93], v[192:195], v[58:61]
	v_mfma_f32_16x16x32_bf16 v[54:57], v[102:105], v[192:195], v[54:57]
	v_mfma_f32_16x16x32_bf16 v[42:45], v[90:93], v[208:211], v[42:45]
	v_mfma_f32_16x16x32_bf16 v[38:41], v[102:105], v[208:211], v[38:41]
	v_mfma_f32_16x16x32_bf16 v[26:29], v[90:93], v[216:219], v[26:29]
	v_mfma_f32_16x16x32_bf16 v[22:25], v[102:105], v[216:219], v[22:25]
	s_setprio 0
	s_setprio 1
	v_mfma_f32_16x16x32_bf16 v[66:69], v[158:161], v[180:183], v[66:69]
	v_mfma_f32_16x16x32_bf16 v[62:65], v[166:169], v[180:183], v[62:65]
	v_mfma_f32_16x16x32_bf16 v[50:53], v[158:161], v[188:191], v[50:53]
	v_mfma_f32_16x16x32_bf16 v[46:49], v[166:169], v[188:191], v[46:49]
	v_mfma_f32_16x16x32_bf16 v[34:37], v[158:161], v[204:207], v[34:37]
	v_mfma_f32_16x16x32_bf16 v[30:33], v[166:169], v[204:207], v[30:33]
	v_mfma_f32_16x16x32_bf16 v[18:21], v[158:161], v[212:215], v[18:21]
	v_mfma_f32_16x16x32_bf16 v[14:17], v[166:169], v[212:215], v[14:17]
	v_mfma_f32_16x16x32_bf16 v[66:69], v[162:165], v[184:187], v[66:69]
	v_mfma_f32_16x16x32_bf16 v[62:65], v[170:173], v[184:187], v[62:65]
	v_mfma_f32_16x16x32_bf16 v[50:53], v[162:165], v[192:195], v[50:53]
	v_mfma_f32_16x16x32_bf16 v[46:49], v[170:173], v[192:195], v[46:49]
	s_setprio 2
	s_barrier
; #define PG8_STAGE(bufoff, gbase, voff) do { const char* gb_ = (const char*)(gbase); asm volatile("" : "+s"(gb_));     \
;         _Pragma("unroll") for (int _i = 0; _i < 2; ++_i) \
;         __builtin_amdgcn_global_load_lds((const unsigned*)(gb_ + (voff)[_i]), (PG8_LAS unsigned*)(lds + (bufoff) + ldsw + _i * 8192), 16, 0, 0); } while (0)
; #define PG8_LDA(dst, b, h) do { _Pragma("unroll") for (int m = 0; m < 4; ++m) _Pragma("unroll") for (int k = 0; k < 2; ++k) dst[m][k] = *(const PG8_LAS bf16x8*)(lds + PG8_SA(b, h) + aoff + m * 2048 + k * 1024); } while (0)
; #define PG8_LDB(dst, b, h) do { _Pragma("unroll") for (int n = 0; n < 2; ++n) _Pragma("unroll") for (int k = 0; k < 2; ++k) dst[n][k] = *(const PG8_LAS bf16x8*)(lds + PG8_SB(b, h) + boff + n * 2048 + k * 1024); } while (0)
; #define PG8_MMA(ai, bj, At, Bt) do { __builtin_amdgcn_s_setprio(1); _Pragma("unroll") for (int m = 0; m < 4; ++m) _Pragma("unroll") for (int n = 0; n < 2; ++n) _Pragma("unroll") for (int k = 0; k < 2; ++k) \
;         acc[ai][bj][m][n] = __builtin_amdgcn_mfma_f32_16x16x32_bf16(Bt[n][k], At[m][k], acc[ai][bj][m][n], 0, 0, 0); __builtin_amdgcn_s_setprio(0); } while (0)
; #define PG8_WAIT_V(n) asm volatile("s_waitcnt vmcnt(" #n ")" ::: "memory")
; #define PG8_WAIT_L(n) asm volatile("s_waitcnt lgkmcnt(" #n ")" ::: "memory")
; #define PG8_BAR __builtin_amdgcn_s_barrier()
; #define PG8_SCHED __builtin_amdgcn_sched_barrier(0)
; template <class Epi, class Sched, bool ALIGN_EPI = false, bool SP2 = false>
; __device__ __forceinline__ void gemm_phase(PG8_LAS unsigned char* lds, const Gemm g, const Sched& S, const Epi& E, int wid0) {
;     ...
;             PG8_LDB(B0, 0, 0); PG8_LDB(B1, 0, 1); PG8_SCHED; PG8_LDA(At, 0, 0); PG8_STAGE(PG8_SA(1, 1), a1 + hstepA, vA_);
;             PG8_WAIT_V(8); PG8_WAIT_L(0); PG8_BAR; PG8_MMA(0, 0, At, B0); PG8_MMA(0, 1, At, B1); PG8_BAR; PG8_SCHED;
;             PG8_LDA(At, 0, 1); PG8_STAGE(PG8_SB(0, 0), b2, vB_); PG8_STAGE(PG8_SB(0, 1), b2 + hstep, vB_); PG8_STAGE(PG8_SA(0, 0), a2, vA_);
;             PG8_WAIT_V(8); PG8_WAIT_L(0); PG8_BAR; PG8_MMA(1, 0, At, B0); PG8_MMA(1, 1, At, B1); PG8_BAR; PG8_SCHED;
;             PG8_LDB(B0, 1, 0); PG8_LDB(B1, 1, 1); PG8_SCHED; PG8_LDA(At, 1, 0); PG8_STAGE(PG8_SA(0, 1), a2 + hstepA, vA_);
;             PG8_WAIT_V(8); PG8_WAIT_L(0); PG8_BAR; PG8_MMA(0, 0, At, B0); PG8_MMA(0, 1, At, B1); PG8_BAR; PG8_SCHED;
	v_mfma_f32_16x16x32_bf16 v[34:37], v[162:165], v[208:211], v[34:37]
	v_mfma_f32_16x16x32_bf16 v[30:33], v[170:173], v[208:211], v[30:33]
	v_mfma_f32_16x16x32_bf16 v[18:21], v[162:165], v[216:219], v[18:21]
	v_mfma_f32_16x16x32_bf16 v[14:17], v[170:173], v[216:219], v[14:17]
	s_setprio 0
	s_add_i32 s83, 0, 0x18000
	s_add_i32 s84, 0, 0x1c000
	v_add_u32_e32 v102, s83, v175
	v_add_u32_e32 v170, s84, v175
	ds_read_b128 v[82:85], v102
	ds_read_b128 v[90:93], v102 offset:1024
	ds_read_b128 v[94:97], v102 offset:2048
	ds_read_b128 v[102:105], v102 offset:3072
	ds_read_b128 v[158:161], v170
	ds_read_b128 v[162:165], v170 offset:1024
	ds_read_b128 v[166:169], v170 offset:2048
	ds_read_b128 v[170:173], v170 offset:3072
	s_add_u32 s2, s58, 0x40000
	s_addc_u32 s3, s59, 0
	s_mov_b32 m0, s64
	ds_read_b128 v[180:183], v203 offset:32768
	ds_read_b128 v[184:187], v203 offset:33792
	ds_read_b128 v[188:191], v203 offset:34816
	ds_read_b128 v[192:195], v203 offset:35840
	ds_read_b128 v[204:207], v203 offset:36864
	ds_read_b128 v[208:211], v203 offset:37888
	ds_read_b128 v[212:215], v203 offset:38912
	ds_read_b128 v[216:219], v203 offset:39936
	s_nop 0
	global_load_lds_dwordx4 v8, s[2:3]
	s_mov_b32 m0, s65
	s_nop 0
	global_load_lds_dwordx4 v221, s[2:3]
	s_waitcnt vmcnt(8)
	s_waitcnt lgkmcnt(0)
	s_barrier
	s_setprio 1
	s_waitcnt lgkmcnt(0)
	v_mfma_f32_16x16x32_bf16 v[154:157], v[82:85], v[180:183], v[154:157]
	v_mfma_f32_16x16x32_bf16 v[150:153], v[94:97], v[180:183], v[150:153]
	v_mfma_f32_16x16x32_bf16 v[138:141], v[82:85], v[188:191], v[138:141]
	v_mfma_f32_16x16x32_bf16 v[134:137], v[94:97], v[188:191], v[134:137]
	v_mfma_f32_16x16x32_bf16 v[122:125], v[82:85], v[204:207], v[122:125]
	v_mfma_f32_16x16x32_bf16 v[118:121], v[94:97], v[204:207], v[118:121]
	v_mfma_f32_16x16x32_bf16 v[106:109], v[82:85], v[212:215], v[106:109]
	v_mfma_f32_16x16x32_bf16 v[98:101], v[94:97], v[212:215], v[98:101]
	v_mfma_f32_16x16x32_bf16 v[154:157], v[90:93], v[184:187], v[154:157]
	v_mfma_f32_16x16x32_bf16 v[150:153], v[102:105], v[184:187], v[150:153]
	v_mfma_f32_16x16x32_bf16 v[138:141], v[90:93], v[192:195], v[138:141]
	v_mfma_f32_16x16x32_bf16 v[134:137], v[102:105], v[192:195], v[134:137]
	v_mfma_f32_16x16x32_bf16 v[122:125], v[90:93], v[208:211], v[122:125]
	v_mfma_f32_16x16x32_bf16 v[118:121], v[102:105], v[208:211], v[118:121]
	v_mfma_f32_16x16x32_bf16 v[106:109], v[90:93], v[216:219], v[106:109]
	v_mfma_f32_16x16x32_bf16 v[98:101], v[102:105], v[216:219], v[98:101]
	s_setprio 0
	s_setprio 1
	v_mfma_f32_16x16x32_bf16 v[146:149], v[158:161], v[180:183], v[146:149]
	v_mfma_f32_16x16x32_bf16 v[142:145], v[166:169], v[180:183], v[142:145]
	v_mfma_f32_16x16x32_bf16 v[130:133], v[158:161], v[188:191], v[130:133]
	v_mfma_f32_16x16x32_bf16 v[126:129], v[166:169], v[188:191], v[126:129]
	v_mfma_f32_16x16x32_bf16 v[114:117], v[158:161], v[204:207], v[114:117]
	v_mfma_f32_16x16x32_bf16 v[110:113], v[166:169], v[204:207], v[110:113]
	v_mfma_f32_16x16x32_bf16 v[86:89], v[158:161], v[212:215], v[86:89]
	v_mfma_f32_16x16x32_bf16 v[78:81], v[166:169], v[212:215], v[78:81]
	v_mfma_f32_16x16x32_bf16 v[146:149], v[162:165], v[184:187], v[146:149]
	v_mfma_f32_16x16x32_bf16 v[142:145], v[170:173], v[184:187], v[142:145]
	v_mfma_f32_16x16x32_bf16 v[130:133], v[162:165], v[192:195], v[130:133]
	v_mfma_f32_16x16x32_bf16 v[126:129], v[170:173], v[192:195], v[126:129]
	s_setprio 2
	s_barrier
; #define PG8_STAGE(bufoff, gbase, voff) do { const char* gb_ = (const char*)(gbase); asm volatile("" : "+s"(gb_));     \
;         _Pragma("unroll") for (int _i = 0; _i < 2; ++_i) \
;         __builtin_amdgcn_global_load_lds((const unsigned*)(gb_ + (voff)[_i]), (PG8_LAS unsigned*)(lds + (bufoff) + ldsw + _i * 8192), 16, 0, 0); } while (0)
; #define PG8_LDA(dst, b, h) do { _Pragma("unroll") for (int m = 0; m < 4; ++m) _Pragma("unroll") for (int k = 0; k < 2; ++k) dst[m][k] = *(const PG8_LAS bf16x8*)(lds + PG8_SA(b, h) + aoff + m * 2048 + k * 1024); } while (0)
; #define PG8_LDB(dst, b, h) do { _Pragma("unroll") for (int n = 0; n < 2; ++n) _Pragma("unroll") for (int k = 0; k < 2; ++k) dst[n][k] = *(const PG8_LAS bf16x8*)(lds + PG8_SB(b, h) + boff + n * 2048 + k * 1024); } while (0)
; #define PG8_WAIT_V(n) asm volatile("s_waitcnt vmcnt(" #n ")" ::: "memory")
; #define PG8_WAIT_L(n) asm volatile("s_waitcnt lgkmcnt(" #n ")" ::: "memory")
; #define PG8_BAR __builtin_amdgcn_s_barrier()
; #define PG8_SCHED __builtin_amdgcn_sched_barrier(0)
; template <class Epi, class Sched, bool ALIGN_EPI = false, bool SP2 = false>
; __device__ __forceinline__ void gemm_phase(PG8_LAS unsigned char* lds, const Gemm g, const Sched& S, const Epi& E, int wid0) {
;     ...
;             PG8_LDB(B0, 0, 0); PG8_LDB(B1, 0, 1); PG8_SCHED; PG8_LDA(At, 0, 0); PG8_STAGE(PG8_SA(1, 1), a1 + hstepA, vA_);
;             PG8_WAIT_V(8); PG8_WAIT_L(0); PG8_BAR; PG8_MMA(0, 0, At, B0); PG8_MMA(0, 1, At, B1); PG8_BAR; PG8_SCHED;
;             PG8_LDA(At, 0, 1); PG8_STAGE(PG8_SB(0, 0), b2, vB_); PG8_STAGE(PG8_SB(0, 1), b2 + hstep, vB_); PG8_STAGE(PG8_SA(0, 0), a2, vA_);
;             PG8_WAIT_V(8); PG8_WAIT_L(0); PG8_BAR; PG8_MMA(1, 0, At, B0); PG8_MMA(1, 1, At, B1); PG8_BAR; PG8_SCHED;
;             PG8_LDB(B0, 1, 0); PG8_LDB(B1, 1, 1); PG8_SCHED; PG8_LDA(At, 1, 0); PG8_STAGE(PG8_SA(0, 1), a2 + hstepA, vA_);
;             PG8_WAIT_V(8); PG8_WAIT_L(0); PG8_BAR; PG8_MMA(0, 0, At, B0); PG8_MMA(0, 1, At, B1); PG8_BAR; PG8_SCHED;
;             PG8_LDA(At, 1, 1); PG8_STAGE(PG8_SB(1, 0), b3, vB_); PG8_STAGE(PG8_SB(1, 1), b3 + hstep, vB_); PG8_STAGE(PG8_SA(1, 0), a3, vA_);
;             PG8_WAIT_V(8); PG8_WAIT_L(0); PG8_BAR; PG8_MMA(1, 0, At, B0); PG8_MMA(1, 1, At, B1); PG8_BAR; PG8_SCHED;
;     ...
;         if constexpr (ALIGN_EPI) { if (wr == 0) PG8_BAR; }
	v_mfma_f32_16x16x32_bf16 v[114:117], v[162:165], v[208:211], v[114:117]
	v_mfma_f32_16x16x32_bf16 v[110:113], v[170:173], v[208:211], v[110:113]
	v_mfma_f32_16x16x32_bf16 v[86:89], v[162:165], v[216:219], v[86:89]
	v_mfma_f32_16x16x32_bf16 v[78:81], v[170:173], v[216:219], v[78:81]
	s_setprio 0
	s_add_u32 s2, s12, 0x80
	s_addc_u32 s3, s13, 0
	s_add_i32 s58, s83, s55
	s_mov_b32 m0, s58
	ds_read_b128 v[180:183], v203 offset:49152
	ds_read_b128 v[184:187], v203 offset:50176
	ds_read_b128 v[188:191], v203 offset:51200
	ds_read_b128 v[192:195], v203 offset:52224
	ds_read_b128 v[204:207], v203 offset:53248
	ds_read_b128 v[208:211], v203 offset:54272
	ds_read_b128 v[212:215], v203 offset:55296
	ds_read_b128 v[216:219], v203 offset:56320
	s_nop 0
	global_load_lds_dwordx4 v220, s[2:3]
	s_add_i32 m0, s58, 0x2000
	s_nop 0
	global_load_lds_dwordx4 v222, s[2:3]
	s_add_u32 s2, s12, 0x40080
	s_addc_u32 s3, s13, 0
	s_add_i32 s12, s84, s55
	s_mov_b32 m0, s12
	s_nop 0
	global_load_lds_dwordx4 v220, s[2:3]
	s_add_i32 m0, s12, 0x2000
	s_nop 0
	global_load_lds_dwordx4 v222, s[2:3]
	s_mov_b32 m0, s68
	s_nop 0
	global_load_lds_dwordx4 v8, s[10:11]
	s_mov_b32 m0, s69
	s_nop 0
	global_load_lds_dwordx4 v221, s[10:11]
	s_waitcnt vmcnt(8)
	s_waitcnt lgkmcnt(0)
	s_barrier
	s_setprio 1
	s_waitcnt lgkmcnt(0)
	v_mfma_f32_16x16x32_bf16 v[74:77], v[82:85], v[180:183], v[74:77]
	v_mfma_f32_16x16x32_bf16 v[70:73], v[94:97], v[180:183], v[70:73]
	v_mfma_f32_16x16x32_bf16 v[58:61], v[82:85], v[188:191], v[58:61]
	v_mfma_f32_16x16x32_bf16 v[54:57], v[94:97], v[188:191], v[54:57]
	v_mfma_f32_16x16x32_bf16 v[42:45], v[82:85], v[204:207], v[42:45]
	v_mfma_f32_16x16x32_bf16 v[38:41], v[94:97], v[204:207], v[38:41]
	v_mfma_f32_16x16x32_bf16 v[26:29], v[82:85], v[212:215], v[26:29]
	v_mfma_f32_16x16x32_bf16 v[22:25], v[94:97], v[212:215], v[22:25]
	v_mfma_f32_16x16x32_bf16 v[74:77], v[90:93], v[184:187], v[74:77]
	v_mfma_f32_16x16x32_bf16 v[70:73], v[102:105], v[184:187], v[70:73]
	v_mfma_f32_16x16x32_bf16 v[58:61], v[90:93], v[192:195], v[58:61]
	v_mfma_f32_16x16x32_bf16 v[54:57], v[102:105], v[192:195], v[54:57]
	v_mfma_f32_16x16x32_bf16 v[42:45], v[90:93], v[208:211], v[42:45]
	v_mfma_f32_16x16x32_bf16 v[38:41], v[102:105], v[208:211], v[38:41]
	v_mfma_f32_16x16x32_bf16 v[26:29], v[90:93], v[216:219], v[26:29]
	v_mfma_f32_16x16x32_bf16 v[22:25], v[102:105], v[216:219], v[22:25]
	s_setprio 0
	s_setprio 1
	v_mfma_f32_16x16x32_bf16 v[66:69], v[158:161], v[180:183], v[66:69]
	v_mfma_f32_16x16x32_bf16 v[62:65], v[166:169], v[180:183], v[62:65]
	v_mfma_f32_16x16x32_bf16 v[50:53], v[158:161], v[188:191], v[50:53]
	v_mfma_f32_16x16x32_bf16 v[46:49], v[166:169], v[188:191], v[46:49]
	v_mfma_f32_16x16x32_bf16 v[34:37], v[158:161], v[204:207], v[34:37]
	v_mfma_f32_16x16x32_bf16 v[30:33], v[166:169], v[204:207], v[30:33]
	v_mfma_f32_16x16x32_bf16 v[18:21], v[158:161], v[212:215], v[18:21]
	v_mfma_f32_16x16x32_bf16 v[14:17], v[166:169], v[212:215], v[14:17]
	v_mfma_f32_16x16x32_bf16 v[66:69], v[162:165], v[184:187], v[66:69]
	v_mfma_f32_16x16x32_bf16 v[62:65], v[170:173], v[184:187], v[62:65]
	v_mfma_f32_16x16x32_bf16 v[50:53], v[162:165], v[192:195], v[50:53]
	v_mfma_f32_16x16x32_bf16 v[46:49], v[170:173], v[192:195], v[46:49]
	s_setprio 2
	s_barrier
	v_mfma_f32_16x16x32_bf16 v[34:37], v[162:165], v[208:211], v[34:37]
	v_mfma_f32_16x16x32_bf16 v[30:33], v[170:173], v[208:211], v[30:33]
	v_mfma_f32_16x16x32_bf16 v[18:21], v[162:165], v[216:219], v[18:21]
	v_mfma_f32_16x16x32_bf16 v[14:17], v[170:173], v[216:219], v[14:17]
	s_setprio 0
	s_add_i32 s82, s82, 2
	s_add_u32 s80, s80, 0x100
	s_addc_u32 s81, s81, 0
	s_cmp_gt_u32 s82, 13
	s_mov_b64 s[2:3], s[8:9]
	s_cbranch_scc0 .LBB13_358
	s_and_b64 vcc, exec, s[42:43]
	s_cbranch_vccz .LBB13_361
	s_barrier

;     __device__ float mid(int row) const { return rg(row) / ra(row); }
;     __device__ __forceinline__ bool next(int i, Unit& u) const { return map(rank + i * nloc, u); }
; #define PG8_LDA(dst, b, h) do { _Pragma("unroll") for (int m = 0; m < 4; ++m) _Pragma("unroll") for (int k = 0; k < 2; ++k) dst[m][k] = *(const PG8_LAS bf16x8*)(lds + PG8_SA(b, h) + aoff + m * 2048 + k * 1024); } while (0)
; template <class Epi, class Sched, bool ALIGN_EPI = false, bool SP2 = false>
; __device__ __forceinline__ void gemm_phase(PG8_LAS unsigned char* lds, const Gemm g, const Sched& S, const Epi& E, int wid0) {
;     ...
;         const bool has_next = S.next(ui + 1, nxt); nxt.ui = ui + 1;
;         if constexpr (Epi::HAS_PRE) E.pre_finish(lds, cur, tid, pq0, pq1, pq2);
;         const char* nA = has_next ? (const char*)g.A + (size_t)nxt.pm * tstepA : cA; const char* nB = has_next ? (const char*)g.Bt + (size_t)nxt.pn * tstep : cB;
; #pragma nounroll
;         for (int t = 0; t < nt; t += 2) {
;             const bool last = (t == nt - 2);
;             const char* a1 = cA + (size_t)(t + 1) * kstep;
;             const char* a2 = last ? nA : cA + (size_t)(t + 2) * kstep; const char* b2 = last ? nB : cB + (size_t)(t + 2) * kstep;
;             const char* a3 = a2 + kstep; const char* b3 = b2 + kstep;
;             if (last && has_next) S.a_ready(nxt);
;             if constexpr (Epi::HAS_MID) { if (t == Epi::MID_T) E.mid(acc, cur, wr, fr); }
;             unsigned vA_[2] = {voffA[0], voffA[1]}, vB_[2] = {voffB[0], voffB[1]};
;             asm volatile("" : "+v"(vA_[0]), "+v"(vA_[1]), "+v"(vB_[0]), "+v"(vB_[1]));
;             if constexpr (SP2) {
;             PG8_LDB(B0, 0, 0); PG8_LDB(B1, 0, 1); PG8_SCHED; PG8_LDA(At, 0, 0); PG8_STAGE(PG8_SA(1, 1), a1 + hstepA, vA_);
;             PG8_WAIT_V(8); PG8_WAIT_L(0); PG8_BAR; PG8_MMA(0, 0, At, B0); PG8_MMA(0, 1, At, B1); PG8_BAR; PG8_SCHED;
;             PG8_LDA(At, 0, 1); PG8_STAGE(PG8_SB(0, 0), b2, vB_); PG8_STAGE(PG8_SB(0, 1), b2 + hstep, vB_); PG8_STAGE(PG8_SA(0, 0), a2, vA_);
;             PG8_WAIT_V(8); PG8_WAIT_L(0); PG8_BAR; PG8_MMA(1, 0, At, B0); PG8_MMA(1, 1, At, B1); PG8_BAR; PG8_SCHED;
;             PG8_LDB(B0, 1, 0); PG8_LDB(B1, 1, 1); PG8_SCHED; PG8_LDA(At, 1, 0); PG8_STAGE(PG8_SA(0, 1), a2 + hstepA, vA_);
;             PG8_WAIT_V(8); PG8_WAIT_L(0); PG8_BAR; PG8_MMA(0, 0, At, B0); PG8_MMA(0, 1, At, B1); PG8_BAR; PG8_SCHED;
.LBB13_542:
	s_add_u32 s40, s28, s36
	s_addc_u32 s41, s29, s37
	s_add_u32 s42, s40, 0x100
	s_addc_u32 s43, s41, 0
	s_and_b64 s[38:39], s[34:35], exec
	s_cselect_b32 s43, s5, s43
	s_cselect_b32 s42, s7, s42
	s_add_u32 s36, s26, s36
	s_addc_u32 s37, s27, s37
	s_add_u32 s38, s36, 0x100
	s_addc_u32 s39, s37, 0
	s_add_u32 s36, s42, 0x80
	s_addc_u32 s37, s43, 0
	s_and_b64 s[34:35], s[34:35], exec
	s_cselect_b32 s45, s17, s39
	s_cselect_b32 s44, s19, s38
	s_add_u32 s48, s40, 0x10080
	s_addc_u32 s49, s41, 0
	s_add_i32 s76, s64, s50
	v_mov_b32_e32 v158, v156
	v_mov_b32_e32 v183, v163
	v_mov_b32_e32 v212, v160
	v_mov_b32_e32 v213, v162
	s_add_i32 m0, s55, 0xc000
	s_add_i32 s79, s55, 0xe000
	s_add_i32 s74, s76, 0x2000
	ds_read_b128 v[72:75], v172
	ds_read_b128 v[92:95], v172 offset:1024
	ds_read_b128 v[112:115], v172 offset:2048
	ds_read_b128 v[132:135], v172 offset:3072
	ds_read_b128 v[144:147], v173
	ds_read_b128 v[148:151], v173 offset:1024
	ds_read_b128 v[152:155], v173 offset:2048
	ds_read_b128 v[164:167], v173 offset:3072
	s_add_u32 s46, s44, 0x10000
	s_addc_u32 s47, s45, 0
	s_add_i32 s75, s65, s50
	s_add_i32 s73, s75, 0x2000
	s_add_i32 s72, 0, 0x18000
	s_add_i32 s71, 0, 0x1c000
	s_add_u32 s40, s42, 0x10000
	s_addc_u32 s41, s43, 0
	s_add_u32 s38, s44, 0x80
	s_addc_u32 s39, s45, 0
	s_add_i32 s70, s72, s50
	s_add_i32 s69, s70, 0x2000
	s_add_u32 s34, s44, 0x10080
	s_addc_u32 s35, s45, 0
	s_add_i32 s78, s71, s50
	s_add_i32 s77, s78, 0x2000
	ds_read_b128 v[168:171], v174
	ds_read_b128 v[184:187], v174 offset:1024
	ds_read_b128 v[188:191], v174 offset:2048
	ds_read_b128 v[192:195], v174 offset:3072
	ds_read_b128 v[196:199], v174 offset:4096
	ds_read_b128 v[200:203], v174 offset:5120
	ds_read_b128 v[204:207], v174 offset:6144
	ds_read_b128 v[208:211], v174 offset:7168
	s_nop 0
	global_load_lds_dwordx4 v158, s[48:49]
	s_mov_b32 m0, s79
	s_nop 0
	global_load_lds_dwordx4 v212, s[48:49]
	s_waitcnt vmcnt(8)
	s_waitcnt lgkmcnt(0)
	s_barrier
	s_setprio 1
	s_waitcnt lgkmcnt(0)
	v_mfma_f32_16x16x32_bf16 v[140:143], v[72:75], v[168:171], v[140:143]
	v_mfma_f32_16x16x32_bf16 v[136:139], v[112:115], v[168:171], v[136:139]
	v_mfma_f32_16x16x32_bf16 v[120:123], v[72:75], v[188:191], v[120:123]
	v_mfma_f32_16x16x32_bf16 v[116:119], v[112:115], v[188:191], v[116:119]
	v_mfma_f32_16x16x32_bf16 v[100:103], v[72:75], v[196:199], v[100:103]
	v_mfma_f32_16x16x32_bf16 v[96:99], v[112:115], v[196:199], v[96:99]
	v_mfma_f32_16x16x32_bf16 v[80:83], v[72:75], v[204:207], v[80:83]
	v_mfma_f32_16x16x32_bf16 v[76:79], v[112:115], v[204:207], v[76:79]
	v_mfma_f32_16x16x32_bf16 v[140:143], v[92:95], v[184:187], v[140:143]
	v_mfma_f32_16x16x32_bf16 v[136:139], v[132:135], v[184:187], v[136:139]
	v_mfma_f32_16x16x32_bf16 v[120:123], v[92:95], v[192:195], v[120:123]
	v_mfma_f32_16x16x32_bf16 v[116:119], v[132:135], v[192:195], v[116:119]
	v_mfma_f32_16x16x32_bf16 v[100:103], v[92:95], v[200:203], v[100:103]
	v_mfma_f32_16x16x32_bf16 v[96:99], v[132:135], v[200:203], v[96:99]
	v_mfma_f32_16x16x32_bf16 v[80:83], v[92:95], v[208:211], v[80:83]
	v_mfma_f32_16x16x32_bf16 v[76:79], v[132:135], v[208:211], v[76:79]
	s_setprio 0
	s_setprio 1
	v_mfma_f32_16x16x32_bf16 v[128:131], v[144:147], v[168:171], v[128:131]
	v_mfma_f32_16x16x32_bf16 v[124:127], v[152:155], v[168:171], v[124:127]
	v_mfma_f32_16x16x32_bf16 v[108:111], v[144:147], v[188:191], v[108:111]
	v_mfma_f32_16x16x32_bf16 v[104:107], v[152:155], v[188:191], v[104:107]
	v_mfma_f32_16x16x32_bf16 v[88:91], v[144:147], v[196:199], v[88:91]
	v_mfma_f32_16x16x32_bf16 v[84:87], v[152:155], v[196:199], v[84:87]
	v_mfma_f32_16x16x32_bf16 v[68:71], v[144:147], v[204:207], v[68:71]
	v_mfma_f32_16x16x32_bf16 v[64:67], v[152:155], v[204:207], v[64:67]
	v_mfma_f32_16x16x32_bf16 v[128:131], v[148:151], v[184:187], v[128:131]
	v_mfma_f32_16x16x32_bf16 v[124:127], v[164:167], v[184:187], v[124:127]
	v_mfma_f32_16x16x32_bf16 v[108:111], v[148:151], v[192:195], v[108:111]
	v_mfma_f32_16x16x32_bf16 v[104:107], v[164:167], v[192:195], v[104:107]
	s_setprio 2
	s_barrier
	v_mfma_f32_16x16x32_bf16 v[88:91], v[148:151], v[200:203], v[88:91]
	v_mfma_f32_16x16x32_bf16 v[84:87], v[164:167], v[200:203], v[84:87]
	v_mfma_f32_16x16x32_bf16 v[68:71], v[148:151], v[208:211], v[68:71]
	v_mfma_f32_16x16x32_bf16 v[64:67], v[164:167], v[208:211], v[64:67]
	s_setprio 0
	s_mov_b32 m0, s76
	ds_read_b128 v[168:171], v174 offset:16384
	ds_read_b128 v[184:187], v174 offset:17408
	ds_read_b128 v[188:191], v174 offset:18432
	ds_read_b128 v[192:195], v174 offset:19456
	ds_read_b128 v[196:199], v174 offset:20480
	ds_read_b128 v[200:203], v174 offset:21504
	ds_read_b128 v[204:207], v174 offset:22528
	ds_read_b128 v[208:211], v174 offset:23552
	s_nop 0
	global_load_lds_dwordx4 v183, s[44:45]
	s_mov_b32 m0, s74
	s_nop 0
	global_load_lds_dwordx4 v213, s[44:45]
	s_mov_b32 m0, s75
	s_nop 0
	global_load_lds_dwordx4 v183, s[46:47]
	s_mov_b32 m0, s73
	s_nop 0
	global_load_lds_dwordx4 v213, s[46:47]
	s_mov_b32 m0, s55
	s_nop 0
	global_load_lds_dwordx4 v158, s[42:43]
	s_mov_b32 m0, s56
	s_nop 0
	global_load_lds_dwordx4 v212, s[42:43]
	s_waitcnt vmcnt(8)
	s_waitcnt lgkmcnt(0)
	s_barrier
; #define PG8_STAGE(bufoff, gbase, voff) do { const char* gb_ = (const char*)(gbase); asm volatile("" : "+s"(gb_));     \
;         _Pragma("unroll") for (int _i = 0; _i < 2; ++_i) \
;         __builtin_amdgcn_global_load_lds((const unsigned*)(gb_ + (voff)[_i]), (PG8_LAS unsigned*)(lds + (bufoff) + ldsw + _i * 8192), 16, 0, 0); } while (0)
; #define PG8_LDA(dst, b, h) do { _Pragma("unroll") for (int m = 0; m < 4; ++m) _Pragma("unroll") for (int k = 0; k < 2; ++k) dst[m][k] = *(const PG8_LAS bf16x8*)(lds + PG8_SA(b, h) + aoff + m * 2048 + k * 1024); } while (0)
; #define PG8_LDB(dst, b, h) do { _Pragma("unroll") for (int n = 0; n < 2; ++n) _Pragma("unroll") for (int k = 0; k < 2; ++k) dst[n][k] = *(const PG8_LAS bf16x8*)(lds + PG8_SB(b, h) + boff + n * 2048 + k * 1024); } while (0)
; #define PG8_MMA(ai, bj, At, Bt) do { __builtin_amdgcn_s_setprio(1); _Pragma("unroll") for (int m = 0; m < 4; ++m) _Pragma("unroll") for (int n = 0; n < 2; ++n) _Pragma("unroll") for (int k = 0; k < 2; ++k) \
;         acc[ai][bj][m][n] = __builtin_amdgcn_mfma_f32_16x16x32_bf16(Bt[n][k], At[m][k], acc[ai][bj][m][n], 0, 0, 0); __builtin_amdgcn_s_setprio(0); } while (0)
; #define PG8_WAIT_V(n) asm volatile("s_waitcnt vmcnt(" #n ")" ::: "memory")
; #define PG8_WAIT_L(n) asm volatile("s_waitcnt lgkmcnt(" #n ")" ::: "memory")
; #define PG8_BAR __builtin_amdgcn_s_barrier()
; #define PG8_SCHED __builtin_amdgcn_sched_barrier(0)
; template <class Epi, class Sched, bool ALIGN_EPI = false, bool SP2 = false>
; __device__ __forceinline__ void gemm_phase(PG8_LAS unsigned char* lds, const Gemm g, const Sched& S, const Epi& E, int wid0) {
;     ...
;             PG8_WAIT_V(8); PG8_WAIT_L(0); PG8_BAR; PG8_MMA(0, 0, At, B0); PG8_MMA(0, 1, At, B1); PG8_BAR; PG8_SCHED;
;             PG8_LDA(At, 0, 1); PG8_STAGE(PG8_SB(0, 0), b2, vB_); PG8_STAGE(PG8_SB(0, 1), b2 + hstep, vB_); PG8_STAGE(PG8_SA(0, 0), a2, vA_);
;             PG8_WAIT_V(8); PG8_WAIT_L(0); PG8_BAR; PG8_MMA(1, 0, At, B0); PG8_MMA(1, 1, At, B1); PG8_BAR; PG8_SCHED;
;             PG8_LDB(B0, 1, 0); PG8_LDB(B1, 1, 1); PG8_SCHED; PG8_LDA(At, 1, 0); PG8_STAGE(PG8_SA(0, 1), a2 + hstepA, vA_);
;             PG8_WAIT_V(8); PG8_WAIT_L(0); PG8_BAR; PG8_MMA(0, 0, At, B0); PG8_MMA(0, 1, At, B1); PG8_BAR; PG8_SCHED;
	s_setprio 1
	s_waitcnt lgkmcnt(0)
	v_mfma_f32_16x16x32_bf16 v[60:63], v[72:75], v[168:171], v[60:63]
	v_mfma_f32_16x16x32_bf16 v[56:59], v[112:115], v[168:171], v[56:59]
	v_mfma_f32_16x16x32_bf16 v[44:47], v[72:75], v[188:191], v[44:47]
	v_mfma_f32_16x16x32_bf16 v[40:43], v[112:115], v[188:191], v[40:43]
	v_mfma_f32_16x16x32_bf16 v[28:31], v[72:75], v[196:199], v[28:31]
	v_mfma_f32_16x16x32_bf16 v[24:27], v[112:115], v[196:199], v[24:27]
	v_mfma_f32_16x16x32_bf16 v[12:15], v[72:75], v[204:207], v[12:15]
	v_mfma_f32_16x16x32_bf16 v[8:11], v[112:115], v[204:207], v[8:11]
	v_mfma_f32_16x16x32_bf16 v[60:63], v[92:95], v[184:187], v[60:63]
	v_mfma_f32_16x16x32_bf16 v[56:59], v[132:135], v[184:187], v[56:59]
	v_mfma_f32_16x16x32_bf16 v[44:47], v[92:95], v[192:195], v[44:47]
	v_mfma_f32_16x16x32_bf16 v[40:43], v[132:135], v[192:195], v[40:43]
	v_mfma_f32_16x16x32_bf16 v[28:31], v[92:95], v[200:203], v[28:31]
	v_mfma_f32_16x16x32_bf16 v[24:27], v[132:135], v[200:203], v[24:27]
	v_mfma_f32_16x16x32_bf16 v[12:15], v[92:95], v[208:211], v[12:15]
	v_mfma_f32_16x16x32_bf16 v[8:11], v[132:135], v[208:211], v[8:11]
	s_setprio 0
	s_setprio 1
	v_mfma_f32_16x16x32_bf16 v[52:55], v[144:147], v[168:171], v[52:55]
	v_mfma_f32_16x16x32_bf16 v[48:51], v[152:155], v[168:171], v[48:51]
	v_mfma_f32_16x16x32_bf16 v[36:39], v[144:147], v[188:191], v[36:39]
	v_mfma_f32_16x16x32_bf16 v[32:35], v[152:155], v[188:191], v[32:35]
	v_mfma_f32_16x16x32_bf16 v[20:23], v[144:147], v[196:199], v[20:23]
	v_mfma_f32_16x16x32_bf16 v[16:19], v[152:155], v[196:199], v[16:19]
	v_mfma_f32_16x16x32_bf16 v[4:7], v[144:147], v[204:207], v[4:7]
	v_mfma_f32_16x16x32_bf16 v[0:3], v[152:155], v[204:207], v[0:3]
	v_mfma_f32_16x16x32_bf16 v[52:55], v[148:151], v[184:187], v[52:55]
	v_mfma_f32_16x16x32_bf16 v[48:51], v[164:167], v[184:187], v[48:51]
	v_mfma_f32_16x16x32_bf16 v[36:39], v[148:151], v[192:195], v[36:39]
	v_mfma_f32_16x16x32_bf16 v[32:35], v[164:167], v[192:195], v[32:35]
	s_setprio 2
	s_barrier
	v_mfma_f32_16x16x32_bf16 v[20:23], v[148:151], v[200:203], v[20:23]
	v_mfma_f32_16x16x32_bf16 v[16:19], v[164:167], v[200:203], v[16:19]
	v_mfma_f32_16x16x32_bf16 v[4:7], v[148:151], v[208:211], v[4:7]
	v_mfma_f32_16x16x32_bf16 v[0:3], v[164:167], v[208:211], v[0:3]
	s_setprio 0
	v_add_u32_e32 v132, s72, v157
	v_add_u32_e32 v164, s71, v157
	ds_read_b128 v[72:75], v132
	ds_read_b128 v[92:95], v132 offset:1024
	ds_read_b128 v[112:115], v132 offset:2048
	ds_read_b128 v[132:135], v132 offset:3072
	ds_read_b128 v[144:147], v164
	ds_read_b128 v[148:151], v164 offset:1024
	ds_read_b128 v[152:155], v164 offset:2048
	ds_read_b128 v[164:167], v164 offset:3072
	s_mov_b32 m0, s57
	ds_read_b128 v[168:171], v174 offset:32768
	ds_read_b128 v[184:187], v174 offset:33792
	ds_read_b128 v[188:191], v174 offset:34816
	ds_read_b128 v[192:195], v174 offset:35840
	ds_read_b128 v[196:199], v174 offset:36864
	ds_read_b128 v[200:203], v174 offset:37888
	ds_read_b128 v[204:207], v174 offset:38912
	ds_read_b128 v[208:211], v174 offset:39936
	s_nop 0
	global_load_lds_dwordx4 v158, s[40:41]
	s_mov_b32 m0, s58
	s_nop 0
	global_load_lds_dwordx4 v212, s[40:41]
	s_waitcnt vmcnt(8)
	s_waitcnt lgkmcnt(0)
	s_barrier
	s_setprio 1
	s_waitcnt lgkmcnt(0)
	v_mfma_f32_16x16x32_bf16 v[140:143], v[72:75], v[168:171], v[140:143]
	v_mfma_f32_16x16x32_bf16 v[136:139], v[112:115], v[168:171], v[136:139]
	v_mfma_f32_16x16x32_bf16 v[120:123], v[72:75], v[188:191], v[120:123]
	v_mfma_f32_16x16x32_bf16 v[116:119], v[112:115], v[188:191], v[116:119]
	v_mfma_f32_16x16x32_bf16 v[100:103], v[72:75], v[196:199], v[100:103]
	v_mfma_f32_16x16x32_bf16 v[96:99], v[112:115], v[196:199], v[96:99]
	v_mfma_f32_16x16x32_bf16 v[80:83], v[72:75], v[204:207], v[80:83]
	v_mfma_f32_16x16x32_bf16 v[76:79], v[112:115], v[204:207], v[76:79]
	v_mfma_f32_16x16x32_bf16 v[140:143], v[92:95], v[184:187], v[140:143]
	v_mfma_f32_16x16x32_bf16 v[136:139], v[132:135], v[184:187], v[136:139]
	v_mfma_f32_16x16x32_bf16 v[120:123], v[92:95], v[192:195], v[120:123]
	v_mfma_f32_16x16x32_bf16 v[116:119], v[132:135], v[192:195], v[116:119]
	v_mfma_f32_16x16x32_bf16 v[100:103], v[92:95], v[200:203], v[100:103]
	v_mfma_f32_16x16x32_bf16 v[96:99], v[132:135], v[200:203], v[96:99]
	v_mfma_f32_16x16x32_bf16 v[80:83], v[92:95], v[208:211], v[80:83]
	v_mfma_f32_16x16x32_bf16 v[76:79], v[132:135], v[208:211], v[76:79]
	s_setprio 0
	s_setprio 1
	v_mfma_f32_16x16x32_bf16 v[128:131], v[144:147], v[168:171], v[128:131]
	v_mfma_f32_16x16x32_bf16 v[124:127], v[152:155], v[168:171], v[124:127]
	v_mfma_f32_16x16x32_bf16 v[108:111], v[144:147], v[188:191], v[108:111]
	v_mfma_f32_16x16x32_bf16 v[104:107], v[152:155], v[188:191], v[104:107]
	v_mfma_f32_16x16x32_bf16 v[88:91], v[144:147], v[196:199], v[88:91]
	v_mfma_f32_16x16x32_bf16 v[84:87], v[152:155], v[196:199], v[84:87]
	v_mfma_f32_16x16x32_bf16 v[68:71], v[144:147], v[204:207], v[68:71]
	v_mfma_f32_16x16x32_bf16 v[64:67], v[152:155], v[204:207], v[64:67]
	v_mfma_f32_16x16x32_bf16 v[128:131], v[148:151], v[184:187], v[128:131]
	v_mfma_f32_16x16x32_bf16 v[124:127], v[164:167], v[184:187], v[124:127]
	v_mfma_f32_16x16x32_bf16 v[108:111], v[148:151], v[192:195], v[108:111]
	v_mfma_f32_16x16x32_bf16 v[104:107], v[164:167], v[192:195], v[104:107]
	s_setprio 2
	s_barrier
; #define PG8_STAGE(bufoff, gbase, voff) do { const char* gb_ = (const char*)(gbase); asm volatile("" : "+s"(gb_));     \
;         _Pragma("unroll") for (int _i = 0; _i < 2; ++_i) \
;         __builtin_amdgcn_global_load_lds((const unsigned*)(gb_ + (voff)[_i]), (PG8_LAS unsigned*)(lds + (bufoff) + ldsw + _i * 8192), 16, 0, 0); } while (0)
; #define PG8_LDA(dst, b, h) do { _Pragma("unroll") for (int m = 0; m < 4; ++m) _Pragma("unroll") for (int k = 0; k < 2; ++k) dst[m][k] = *(const PG8_LAS bf16x8*)(lds + PG8_SA(b, h) + aoff + m * 2048 + k * 1024); } while (0)
; #define PG8_MMA(ai, bj, At, Bt) do { __builtin_amdgcn_s_setprio(1); _Pragma("unroll") for (int m = 0; m < 4; ++m) _Pragma("unroll") for (int n = 0; n < 2; ++n) _Pragma("unroll") for (int k = 0; k < 2; ++k) \
;         acc[ai][bj][m][n] = __builtin_amdgcn_mfma_f32_16x16x32_bf16(Bt[n][k], At[m][k], acc[ai][bj][m][n], 0, 0, 0); __builtin_amdgcn_s_setprio(0); } while (0)
; #define PG8_WAIT_V(n) asm volatile("s_waitcnt vmcnt(" #n ")" ::: "memory")
; #define PG8_WAIT_L(n) asm volatile("s_waitcnt lgkmcnt(" #n ")" ::: "memory")
; #define PG8_BAR __builtin_amdgcn_s_barrier()
; #define PG8_SCHED __builtin_amdgcn_sched_barrier(0)
; template <class Epi, class Sched, bool ALIGN_EPI = false, bool SP2 = false>
; __device__ __forceinline__ void gemm_phase(PG8_LAS unsigned char* lds, const Gemm g, const Sched& S, const Epi& E, int wid0) {
;     ...
;             PG8_WAIT_V(8); PG8_WAIT_L(0); PG8_BAR; PG8_MMA(0, 0, At, B0); PG8_MMA(0, 1, At, B1); PG8_BAR; PG8_SCHED;
;             PG8_LDA(At, 1, 1); PG8_STAGE(PG8_SB(1, 0), b3, vB_); PG8_STAGE(PG8_SB(1, 1), b3 + hstep, vB_); PG8_STAGE(PG8_SA(1, 0), a3, vA_);
;             PG8_WAIT_V(8); PG8_WAIT_L(0); PG8_BAR; PG8_MMA(1, 0, At, B0); PG8_MMA(1, 1, At, B1); PG8_BAR; PG8_SCHED;
	v_mfma_f32_16x16x32_bf16 v[88:91], v[148:151], v[200:203], v[88:91]
	v_mfma_f32_16x16x32_bf16 v[84:87], v[164:167], v[200:203], v[84:87]
	v_mfma_f32_16x16x32_bf16 v[68:71], v[148:151], v[208:211], v[68:71]
	v_mfma_f32_16x16x32_bf16 v[64:67], v[164:167], v[208:211], v[64:67]
	s_setprio 0
	s_mov_b32 m0, s70
	ds_read_b128 v[168:171], v174 offset:49152
	ds_read_b128 v[184:187], v174 offset:50176
	ds_read_b128 v[188:191], v174 offset:51200
	ds_read_b128 v[192:195], v174 offset:52224
	ds_read_b128 v[196:199], v174 offset:53248
	ds_read_b128 v[200:203], v174 offset:54272
	ds_read_b128 v[204:207], v174 offset:55296
	ds_read_b128 v[208:211], v174 offset:56320
	s_nop 0
	global_load_lds_dwordx4 v183, s[38:39]
	s_mov_b32 m0, s69
	s_nop 0
	global_load_lds_dwordx4 v213, s[38:39]
	s_mov_b32 m0, s78
	s_nop 0
	global_load_lds_dwordx4 v183, s[34:35]
	s_mov_b32 m0, s77
	s_nop 0
	global_load_lds_dwordx4 v213, s[34:35]
	s_mov_b32 m0, s62
	s_nop 0
	global_load_lds_dwordx4 v158, s[36:37]
	s_mov_b32 m0, s63
	s_nop 0
	global_load_lds_dwordx4 v212, s[36:37]
	s_waitcnt vmcnt(8)
	s_waitcnt lgkmcnt(0)
	s_barrier
	s_setprio 1
	s_waitcnt lgkmcnt(0)
	v_mfma_f32_16x16x32_bf16 v[60:63], v[72:75], v[168:171], v[60:63]
	v_mfma_f32_16x16x32_bf16 v[56:59], v[112:115], v[168:171], v[56:59]
	v_mfma_f32_16x16x32_bf16 v[44:47], v[72:75], v[188:191], v[44:47]
	v_mfma_f32_16x16x32_bf16 v[40:43], v[112:115], v[188:191], v[40:43]
	v_mfma_f32_16x16x32_bf16 v[28:31], v[72:75], v[196:199], v[28:31]
	v_mfma_f32_16x16x32_bf16 v[24:27], v[112:115], v[196:199], v[24:27]
	v_mfma_f32_16x16x32_bf16 v[12:15], v[72:75], v[204:207], v[12:15]
	v_mfma_f32_16x16x32_bf16 v[8:11], v[112:115], v[204:207], v[8:11]
	v_mfma_f32_16x16x32_bf16 v[60:63], v[92:95], v[184:187], v[60:63]
	v_mfma_f32_16x16x32_bf16 v[56:59], v[132:135], v[184:187], v[56:59]
	v_mfma_f32_16x16x32_bf16 v[44:47], v[92:95], v[192:195], v[44:47]
	v_mfma_f32_16x16x32_bf16 v[40:43], v[132:135], v[192:195], v[40:43]
	v_mfma_f32_16x16x32_bf16 v[28:31], v[92:95], v[200:203], v[28:31]
	v_mfma_f32_16x16x32_bf16 v[24:27], v[132:135], v[200:203], v[24:27]
	v_mfma_f32_16x16x32_bf16 v[12:15], v[92:95], v[208:211], v[12:15]
	v_mfma_f32_16x16x32_bf16 v[8:11], v[132:135], v[208:211], v[8:11]
	s_setprio 0
	s_setprio 1
	v_mfma_f32_16x16x32_bf16 v[52:55], v[144:147], v[168:171], v[52:55]
	v_mfma_f32_16x16x32_bf16 v[48:51], v[152:155], v[168:171], v[48:51]
	v_mfma_f32_16x16x32_bf16 v[36:39], v[144:147], v[188:191], v[36:39]
	v_mfma_f32_16x16x32_bf16 v[32:35], v[152:155], v[188:191], v[32:35]
	v_mfma_f32_16x16x32_bf16 v[20:23], v[144:147], v[196:199], v[20:23]
	v_mfma_f32_16x16x32_bf16 v[16:19], v[152:155], v[196:199], v[16:19]
	v_mfma_f32_16x16x32_bf16 v[4:7], v[144:147], v[204:207], v[4:7]
	v_mfma_f32_16x16x32_bf16 v[0:3], v[152:155], v[204:207], v[0:3]
	v_mfma_f32_16x16x32_bf16 v[52:55], v[148:151], v[184:187], v[52:55]
	v_mfma_f32_16x16x32_bf16 v[48:51], v[164:167], v[184:187], v[48:51]
	v_mfma_f32_16x16x32_bf16 v[36:39], v[148:151], v[192:195], v[36:39]
	v_mfma_f32_16x16x32_bf16 v[32:35], v[164:167], v[192:195], v[32:35]
	s_setprio 2
	s_barrier
	v_mfma_f32_16x16x32_bf16 v[20:23], v[148:151], v[200:203], v[20:23]
	v_mfma_f32_16x16x32_bf16 v[16:19], v[164:167], v[200:203], v[16:19]
	v_mfma_f32_16x16x32_bf16 v[4:7], v[148:151], v[208:211], v[4:7]
	v_mfma_f32_16x16x32_bf16 v[0:3], v[164:167], v[208:211], v[0:3]
	s_setprio 0
	s_andn2_b64 vcc, exec, s[30:31]
	s_mov_b64 s[34:35], -1
	s_mov_b64 s[30:31], 0
	s_mov_b64 s[36:37], 0x100
	s_cbranch_vccz .LBB13_542
	s_and_b64 vcc, exec, s[14:15]
	s_cbranch_vccz .LBB13_545
	s_barrier

;     __device__ float mid(int row) const { return rg(row) / ra(row); }
; #define PG8_STAGE(bufoff, gbase, voff) do { const char* gb_ = (const char*)(gbase); asm volatile("" : "+s"(gb_));     \
;         _Pragma("unroll") for (int _i = 0; _i < 2; ++_i) \
;         __builtin_amdgcn_global_load_lds((const unsigned*)(gb_ + (voff)[_i]), (PG8_LAS unsigned*)(lds + (bufoff) + ldsw + _i * 8192), 16, 0, 0); } while (0)
; #define PG8_LDA(dst, b, h) do { _Pragma("unroll") for (int m = 0; m < 4; ++m) _Pragma("unroll") for (int k = 0; k < 2; ++k) dst[m][k] = *(const PG8_LAS bf16x8*)(lds + PG8_SA(b, h) + aoff + m * 2048 + k * 1024); } while (0)
; #define PG8_WAIT_V(n) asm volatile("s_waitcnt vmcnt(" #n ")" ::: "memory")
; template <class Epi, class Sched, bool ALIGN_EPI = false, bool SP2 = false>
; __device__ __forceinline__ void gemm_phase(PG8_LAS unsigned char* lds, const Gemm g, const Sched& S, const Epi& E, int wid0) {
;     ...
;         for (int t = 0; t < nt; t += 2) {
;             const bool last = (t == nt - 2);
;             const char* a1 = cA + (size_t)(t + 1) * kstep;
;             const char* a2 = last ? nA : cA + (size_t)(t + 2) * kstep; const char* b2 = last ? nB : cB + (size_t)(t + 2) * kstep;
;             const char* a3 = a2 + kstep; const char* b3 = b2 + kstep;
;             if (last && has_next) S.a_ready(nxt);
;             if constexpr (Epi::HAS_MID) { if (t == Epi::MID_T) E.mid(acc, cur, wr, fr); }
;             unsigned vA_[2] = {voffA[0], voffA[1]}, vB_[2] = {voffB[0], voffB[1]};
;             asm volatile("" : "+v"(vA_[0]), "+v"(vA_[1]), "+v"(vB_[0]), "+v"(vB_[1]));
;             if constexpr (SP2) {
;             PG8_LDB(B0, 0, 0); PG8_LDB(B1, 0, 1); PG8_SCHED; PG8_LDA(At, 0, 0); PG8_STAGE(PG8_SA(1, 1), a1 + hstepA, vA_);
;             PG8_WAIT_V(8); PG8_WAIT_L(0); PG8_BAR; PG8_MMA(0, 0, At, B0); PG8_MMA(0, 1, At, B1); PG8_BAR; PG8_SCHED;
;             PG8_LDA(At, 0, 1); PG8_STAGE(PG8_SB(0, 0), b2, vB_); PG8_STAGE(PG8_SB(0, 1), b2 + hstep, vB_); PG8_STAGE(PG8_SA(0, 0), a2, vA_);
;             PG8_WAIT_V(8); PG8_WAIT_L(0); PG8_BAR; PG8_MMA(1, 0, At, B0); PG8_MMA(1, 1, At, B1); PG8_BAR; PG8_SCHED;
;             PG8_LDB(B0, 1, 0); PG8_LDB(B1, 1, 1); PG8_SCHED; PG8_LDA(At, 1, 0); PG8_STAGE(PG8_SA(0, 1), a2 + hstepA, vA_);
;             PG8_WAIT_V(8); PG8_WAIT_L(0); PG8_BAR; PG8_MMA(0, 0, At, B0); PG8_MMA(0, 1, At, B1); PG8_BAR; PG8_SCHED;
.LBB13_652:
	s_ashr_i32 s19, s18, 31
	s_lshl_b64 s[22:23], s[18:19], 16
	s_add_u32 s22, s17, s22
	s_addc_u32 s23, s33, s23
	s_and_b64 s[26:27], s[24:25], exec
	s_cselect_b32 s41, s23, s37
	s_cselect_b32 s40, s22, s36
	s_ashr_i32 s21, s20, 31
	s_lshl_b64 s[26:27], s[20:21], 16
	s_add_u32 s26, s42, s26
	s_addc_u32 s27, s43, s27
	s_add_u32 s30, s40, 0x80
	s_addc_u32 s31, s41, 0
	s_add_u32 s56, s36, 0x8080
	s_addc_u32 s57, s37, 0
	v_mov_b32_e32 v144, v132
	v_mov_b32_e32 v145, v134
	v_mov_b32_e32 v147, v128
	v_mov_b32_e32 v236, v130
	s_add_u32 s38, s40, 0x8000
	ds_read_b128 v[0:3], v133
	ds_read_b128 v[4:7], v133 offset:1024
	ds_read_b128 v[8:11], v133 offset:2048
	ds_read_b128 v[12:15], v133 offset:3072
	ds_read_b128 v[16:19], v135
	ds_read_b128 v[20:23], v135 offset:1024
	ds_read_b128 v[24:27], v135 offset:2048
	ds_read_b128 v[28:31], v135 offset:3072
	s_addc_u32 s39, s41, 0
	s_and_b64 s[36:37], s[24:25], exec
	s_cselect_b32 s34, s26, s34
	s_cselect_b32 s35, s27, s35
	s_add_u32 s58, s34, 0x8000
	s_addc_u32 s59, s35, 0
	s_add_u32 s36, s34, 0x80
	s_addc_u32 s37, s35, 0
	s_add_i32 m0, s29, 0xc000
	ds_read_b128 v[32:35], v146
	ds_read_b128 v[36:39], v146 offset:1024
	ds_read_b128 v[40:43], v146 offset:2048
	ds_read_b128 v[44:47], v146 offset:3072
	ds_read_b128 v[48:51], v146 offset:4096
	ds_read_b128 v[52:55], v146 offset:5120
	ds_read_b128 v[56:59], v146 offset:6144
	ds_read_b128 v[60:63], v146 offset:7168
	s_nop 0
	global_load_lds_dwordx4 v147, s[56:57]
	s_add_i32 m0, s29, 0xe000
	s_nop 0
	global_load_lds_dwordx4 v144, s[56:57]
	s_waitcnt vmcnt(8)
	s_waitcnt lgkmcnt(0)
	s_barrier
	s_setprio 1
	s_waitcnt lgkmcnt(0)
	v_mfma_f32_16x16x32_bf16 v[88:91], v[0:3], v[56:59], 0
	v_mfma_f32_16x16x32_bf16 v[64:67], v[0:3], v[32:35], 0
	v_mfma_f32_16x16x32_bf16 v[68:71], v[8:11], v[32:35], 0
	v_mfma_f32_16x16x32_bf16 v[72:75], v[0:3], v[40:43], 0
	v_mfma_f32_16x16x32_bf16 v[76:79], v[8:11], v[40:43], 0
	v_mfma_f32_16x16x32_bf16 v[80:83], v[0:3], v[48:51], 0
	v_mfma_f32_16x16x32_bf16 v[84:87], v[8:11], v[48:51], 0
	v_mfma_f32_16x16x32_bf16 v[96:99], v[4:7], v[60:63], v[88:91]
	v_mfma_f32_16x16x32_bf16 v[88:91], v[8:11], v[56:59], 0
	v_mfma_f32_16x16x32_bf16 v[64:67], v[4:7], v[36:39], v[64:67]
	v_mfma_f32_16x16x32_bf16 v[68:71], v[12:15], v[36:39], v[68:71]
	v_mfma_f32_16x16x32_bf16 v[72:75], v[4:7], v[44:47], v[72:75]
	v_mfma_f32_16x16x32_bf16 v[76:79], v[12:15], v[44:47], v[76:79]
	v_mfma_f32_16x16x32_bf16 v[80:83], v[4:7], v[52:55], v[80:83]
	v_mfma_f32_16x16x32_bf16 v[84:87], v[12:15], v[52:55], v[84:87]
	v_mfma_f32_16x16x32_bf16 v[100:103], v[12:15], v[60:63], v[88:91]
	s_setprio 0
	s_setprio 1
	v_mfma_f32_16x16x32_bf16 v[88:91], v[16:19], v[32:35], 0
	v_mfma_f32_16x16x32_bf16 v[32:35], v[24:27], v[32:35], 0
	v_mfma_f32_16x16x32_bf16 v[120:123], v[20:23], v[36:39], v[88:91]
	v_mfma_f32_16x16x32_bf16 v[32:35], v[28:31], v[36:39], v[32:35]
	v_mfma_f32_16x16x32_bf16 v[36:39], v[16:19], v[40:43], 0
	v_mfma_f32_16x16x32_bf16 v[40:43], v[24:27], v[40:43], 0
	v_mfma_f32_16x16x32_bf16 v[36:39], v[20:23], v[44:47], v[36:39]
	v_mfma_f32_16x16x32_bf16 v[40:43], v[28:31], v[44:47], v[40:43]
	v_mfma_f32_16x16x32_bf16 v[44:47], v[16:19], v[48:51], 0
	v_mfma_f32_16x16x32_bf16 v[48:51], v[24:27], v[48:51], 0
	v_mfma_f32_16x16x32_bf16 v[44:47], v[20:23], v[52:55], v[44:47]
	v_mfma_f32_16x16x32_bf16 v[48:51], v[28:31], v[52:55], v[48:51]
	s_setprio 2
	s_barrier
	v_mfma_f32_16x16x32_bf16 v[52:55], v[16:19], v[56:59], 0
	v_mfma_f32_16x16x32_bf16 v[56:59], v[24:27], v[56:59], 0
	v_mfma_f32_16x16x32_bf16 v[52:55], v[20:23], v[60:63], v[52:55]
	v_mfma_f32_16x16x32_bf16 v[56:59], v[28:31], v[60:63], v[56:59]
	s_setprio 0
	s_add_i32 s7, s53, s15
	s_mov_b64 s[56:57], s[34:35]
	s_mov_b32 m0, s7
	ds_read_b128 v[60:63], v146 offset:16384
	ds_read_b128 v[88:91], v146 offset:17408
	ds_read_b128 v[92:95], v146 offset:18432
	ds_read_b128 v[104:107], v146 offset:19456
	ds_read_b128 v[108:111], v146 offset:20480
	ds_read_b128 v[112:115], v146 offset:21504
	ds_read_b128 v[116:119], v146 offset:22528
	ds_read_b128 v[124:127], v146 offset:23552
	s_nop 0
	global_load_lds_dwordx4 v236, s[56:57]
	s_add_i32 m0, s7, 0x2000
	s_add_i32 s7, s54, s15
	global_load_lds_dwordx4 v145, s[56:57]
	s_mov_b32 m0, s7
	s_nop 0
	global_load_lds_dwordx4 v236, s[58:59]
	s_add_i32 m0, s7, 0x2000
	s_nop 0
	global_load_lds_dwordx4 v145, s[58:59]
	s_mov_b32 m0, s29
	s_nop 0
	global_load_lds_dwordx4 v147, s[40:41]
	s_mov_b32 m0, s44
	s_nop 0
	global_load_lds_dwordx4 v144, s[40:41]
	s_waitcnt vmcnt(8)
	s_waitcnt lgkmcnt(0)
	s_barrier
	s_setprio 1
	s_waitcnt lgkmcnt(0)
	v_mfma_f32_16x16x32_bf16 v[136:139], v[0:3], v[60:63], 0
	v_mfma_f32_16x16x32_bf16 v[148:151], v[0:3], v[92:95], 0
	v_mfma_f32_16x16x32_bf16 v[156:159], v[0:3], v[108:111], 0
	v_mfma_f32_16x16x32_bf16 v[0:3], v[0:3], v[116:119], 0
	v_mfma_f32_16x16x32_bf16 v[136:139], v[4:7], v[88:91], v[136:139]
	v_mfma_f32_16x16x32_bf16 v[148:151], v[4:7], v[104:107], v[148:151]
	v_mfma_f32_16x16x32_bf16 v[156:159], v[4:7], v[112:115], v[156:159]
	v_mfma_f32_16x16x32_bf16 v[0:3], v[4:7], v[124:127], v[0:3]
	v_mfma_f32_16x16x32_bf16 v[4:7], v[8:11], v[116:119], 0
	v_mfma_f32_16x16x32_bf16 v[140:143], v[8:11], v[60:63], 0
	v_mfma_f32_16x16x32_bf16 v[152:155], v[8:11], v[92:95], 0
	v_mfma_f32_16x16x32_bf16 v[160:163], v[8:11], v[108:111], 0
	v_mfma_f32_16x16x32_bf16 v[4:7], v[12:15], v[124:127], v[4:7]
	v_mfma_f32_16x16x32_bf16 v[140:143], v[12:15], v[88:91], v[140:143]
	v_mfma_f32_16x16x32_bf16 v[152:155], v[12:15], v[104:107], v[152:155]
	v_mfma_f32_16x16x32_bf16 v[160:163], v[12:15], v[112:115], v[160:163]
	s_setprio 0
	s_setprio 1
	v_mfma_f32_16x16x32_bf16 v[8:11], v[16:19], v[60:63], 0
	v_mfma_f32_16x16x32_bf16 v[164:167], v[20:23], v[88:91], v[8:11]
	v_mfma_f32_16x16x32_bf16 v[8:11], v[24:27], v[60:63], 0
	v_mfma_f32_16x16x32_bf16 v[168:171], v[28:31], v[88:91], v[8:11]
	v_mfma_f32_16x16x32_bf16 v[8:11], v[16:19], v[92:95], 0
	v_mfma_f32_16x16x32_bf16 v[172:175], v[20:23], v[104:107], v[8:11]
	v_mfma_f32_16x16x32_bf16 v[8:11], v[24:27], v[92:95], 0
	v_mfma_f32_16x16x32_bf16 v[176:179], v[28:31], v[104:107], v[8:11]
	v_mfma_f32_16x16x32_bf16 v[8:11], v[16:19], v[108:111], 0
	v_mfma_f32_16x16x32_bf16 v[180:183], v[20:23], v[112:115], v[8:11]
	v_mfma_f32_16x16x32_bf16 v[8:11], v[24:27], v[108:111], 0
	v_mfma_f32_16x16x32_bf16 v[184:187], v[28:31], v[112:115], v[8:11]
	s_setprio 2
	s_barrier
; #define PG8_STAGE(bufoff, gbase, voff) do { const char* gb_ = (const char*)(gbase); asm volatile("" : "+s"(gb_));     \
;         _Pragma("unroll") for (int _i = 0; _i < 2; ++_i) \
;         __builtin_amdgcn_global_load_lds((const unsigned*)(gb_ + (voff)[_i]), (PG8_LAS unsigned*)(lds + (bufoff) + ldsw + _i * 8192), 16, 0, 0); } while (0)
; #define PG8_LDA(dst, b, h) do { _Pragma("unroll") for (int m = 0; m < 4; ++m) _Pragma("unroll") for (int k = 0; k < 2; ++k) dst[m][k] = *(const PG8_LAS bf16x8*)(lds + PG8_SA(b, h) + aoff + m * 2048 + k * 1024); } while (0)
; #define PG8_LDB(dst, b, h) do { _Pragma("unroll") for (int n = 0; n < 2; ++n) _Pragma("unroll") for (int k = 0; k < 2; ++k) dst[n][k] = *(const PG8_LAS bf16x8*)(lds + PG8_SB(b, h) + boff + n * 2048 + k * 1024); } while (0)
; #define PG8_MMA(ai, bj, At, Bt) do { __builtin_amdgcn_s_setprio(1); _Pragma("unroll") for (int m = 0; m < 4; ++m) _Pragma("unroll") for (int n = 0; n < 2; ++n) _Pragma("unroll") for (int k = 0; k < 2; ++k) \
;         acc[ai][bj][m][n] = __builtin_amdgcn_mfma_f32_16x16x32_bf16(Bt[n][k], At[m][k], acc[ai][bj][m][n], 0, 0, 0); __builtin_amdgcn_s_setprio(0); } while (0)
; #define PG8_WAIT_V(n) asm volatile("s_waitcnt vmcnt(" #n ")" ::: "memory")
; #define PG8_WAIT_L(n) asm volatile("s_waitcnt lgkmcnt(" #n ")" ::: "memory")
; #define PG8_BAR __builtin_amdgcn_s_barrier()
; #define PG8_SCHED __builtin_amdgcn_sched_barrier(0)
; template <class Epi, class Sched, bool ALIGN_EPI = false, bool SP2 = false>
; __device__ __forceinline__ void gemm_phase(PG8_LAS unsigned char* lds, const Gemm g, const Sched& S, const Epi& E, int wid0) {
;     ...
;             PG8_WAIT_V(8); PG8_WAIT_L(0); PG8_BAR; PG8_MMA(1, 0, At, B0); PG8_MMA(1, 1, At, B1); PG8_BAR; PG8_SCHED;
;             PG8_LDB(B0, 1, 0); PG8_LDB(B1, 1, 1); PG8_SCHED; PG8_LDA(At, 1, 0); PG8_STAGE(PG8_SA(0, 1), a2 + hstepA, vA_);
;             PG8_WAIT_V(8); PG8_WAIT_L(0); PG8_BAR; PG8_MMA(0, 0, At, B0); PG8_MMA(0, 1, At, B1); PG8_BAR; PG8_SCHED;
;             PG8_LDA(At, 1, 1); PG8_STAGE(PG8_SB(1, 0), b3, vB_); PG8_STAGE(PG8_SB(1, 1), b3 + hstep, vB_); PG8_STAGE(PG8_SA(1, 0), a3, vA_);
;             PG8_WAIT_V(8); PG8_WAIT_L(0); PG8_BAR; PG8_MMA(1, 0, At, B0); PG8_MMA(1, 1, At, B1); PG8_BAR; PG8_SCHED;
;     ...
;         if constexpr (ALIGN_EPI) { if (wr == 0) PG8_BAR; }
	v_mfma_f32_16x16x32_bf16 v[8:11], v[16:19], v[116:119], 0
	v_mfma_f32_16x16x32_bf16 v[188:191], v[20:23], v[124:127], v[8:11]
	v_mfma_f32_16x16x32_bf16 v[8:11], v[24:27], v[116:119], 0
	v_mfma_f32_16x16x32_bf16 v[192:195], v[28:31], v[124:127], v[8:11]
	s_setprio 0
	s_add_i32 s7, 0, 0x18000
	s_add_i32 s19, 0, 0x1c000
	v_add_u32_e32 v20, s7, v129
	v_add_u32_e32 v24, s19, v129
	s_nop 1
	ds_read_b128 v[8:11], v20
	ds_read_b128 v[12:15], v20 offset:1024
	ds_read_b128 v[16:19], v20 offset:2048
	ds_read_b128 v[20:23], v20 offset:3072
	ds_read_b128 v[196:199], v24
	ds_read_b128 v[200:203], v24 offset:1024
	ds_read_b128 v[204:207], v24 offset:2048
	ds_read_b128 v[208:211], v24 offset:3072
	s_mov_b32 m0, s45
	ds_read_b128 v[24:27], v146 offset:32768
	ds_read_b128 v[28:31], v146 offset:33792
	ds_read_b128 v[60:63], v146 offset:34816
	ds_read_b128 v[212:215], v146 offset:35840
	ds_read_b128 v[216:219], v146 offset:36864
	ds_read_b128 v[220:223], v146 offset:37888
	ds_read_b128 v[224:227], v146 offset:38912
	ds_read_b128 v[228:231], v146 offset:39936
	s_nop 0
	global_load_lds_dwordx4 v147, s[38:39]
	s_mov_b32 m0, s46
	s_nop 0
	global_load_lds_dwordx4 v144, s[38:39]
	s_waitcnt vmcnt(8)
	s_waitcnt lgkmcnt(0)
	s_barrier
	s_setprio 1
	s_waitcnt lgkmcnt(0)
	v_mfma_f32_16x16x32_bf16 v[64:67], v[8:11], v[24:27], v[64:67]
	v_mfma_f32_16x16x32_bf16 v[112:115], v[12:15], v[28:31], v[64:67]
	v_mfma_f32_16x16x32_bf16 v[64:67], v[16:19], v[24:27], v[68:71]
	v_mfma_f32_16x16x32_bf16 v[116:119], v[20:23], v[28:31], v[64:67]
	v_mfma_f32_16x16x32_bf16 v[64:67], v[8:11], v[60:63], v[72:75]
	v_mfma_f32_16x16x32_bf16 v[108:111], v[12:15], v[212:215], v[64:67]
	v_mfma_f32_16x16x32_bf16 v[64:67], v[16:19], v[60:63], v[76:79]
	v_mfma_f32_16x16x32_bf16 v[104:107], v[20:23], v[212:215], v[64:67]
	v_mfma_f32_16x16x32_bf16 v[64:67], v[8:11], v[216:219], v[80:83]
	v_mfma_f32_16x16x32_bf16 v[92:95], v[12:15], v[220:223], v[64:67]
	v_mfma_f32_16x16x32_bf16 v[64:67], v[16:19], v[216:219], v[84:87]
	v_mfma_f32_16x16x32_bf16 v[88:91], v[20:23], v[220:223], v[64:67]
	v_mfma_f32_16x16x32_bf16 v[64:67], v[8:11], v[224:227], v[96:99]
	v_mfma_f32_16x16x32_bf16 v[76:79], v[12:15], v[228:231], v[64:67]
	v_mfma_f32_16x16x32_bf16 v[64:67], v[16:19], v[224:227], v[100:103]
	v_mfma_f32_16x16x32_bf16 v[72:75], v[20:23], v[228:231], v[64:67]
	s_setprio 0
	s_setprio 1
	v_mfma_f32_16x16x32_bf16 v[64:67], v[196:199], v[24:27], v[120:123]
	v_mfma_f32_16x16x32_bf16 v[24:27], v[204:207], v[24:27], v[32:35]
	v_mfma_f32_16x16x32_bf16 v[124:127], v[208:211], v[28:31], v[24:27]
	v_mfma_f32_16x16x32_bf16 v[24:27], v[196:199], v[60:63], v[36:39]
	v_mfma_f32_16x16x32_bf16 v[100:103], v[200:203], v[212:215], v[24:27]
	v_mfma_f32_16x16x32_bf16 v[24:27], v[204:207], v[60:63], v[40:43]
	v_mfma_f32_16x16x32_bf16 v[96:99], v[208:211], v[212:215], v[24:27]
	v_mfma_f32_16x16x32_bf16 v[24:27], v[196:199], v[216:219], v[44:47]
	v_mfma_f32_16x16x32_bf16 v[84:87], v[200:203], v[220:223], v[24:27]
	v_mfma_f32_16x16x32_bf16 v[24:27], v[204:207], v[216:219], v[48:51]
	v_mfma_f32_16x16x32_bf16 v[80:83], v[208:211], v[220:223], v[24:27]
	v_mfma_f32_16x16x32_bf16 v[24:27], v[196:199], v[224:227], v[52:55]
	s_setprio 2
	s_barrier
	v_mfma_f32_16x16x32_bf16 v[68:71], v[200:203], v[228:231], v[24:27]
	v_mfma_f32_16x16x32_bf16 v[24:27], v[204:207], v[224:227], v[56:59]
	v_mfma_f32_16x16x32_bf16 v[120:123], v[200:203], v[28:31], v[64:67]
	v_mfma_f32_16x16x32_bf16 v[64:67], v[208:211], v[228:231], v[24:27]
	s_setprio 0
	s_add_i32 s7, s7, s15
	s_mov_b32 m0, s7
	ds_read_b128 v[32:35], v146 offset:49152
	ds_read_b128 v[36:39], v146 offset:50176
	ds_read_b128 v[212:215], v146 offset:51200
	ds_read_b128 v[216:219], v146 offset:52224
	ds_read_b128 v[220:223], v146 offset:53248
	ds_read_b128 v[224:227], v146 offset:54272
	ds_read_b128 v[228:231], v146 offset:55296
	ds_read_b128 v[232:235], v146 offset:56320
	s_nop 0
	global_load_lds_dwordx4 v236, s[36:37]
	s_add_i32 m0, s7, 0x2000
	s_add_u32 s34, s34, 0x8080
	s_addc_u32 s35, s35, 0
	s_add_i32 s7, s19, s15
	global_load_lds_dwordx4 v145, s[36:37]
	s_mov_b32 m0, s7
	s_nop 0
	global_load_lds_dwordx4 v236, s[34:35]
	s_add_i32 m0, s7, 0x2000
	s_nop 0
	global_load_lds_dwordx4 v145, s[34:35]
	s_mov_b32 m0, s48
	s_nop 0
	global_load_lds_dwordx4 v147, s[30:31]
	s_mov_b32 m0, s49
	s_nop 0
	global_load_lds_dwordx4 v144, s[30:31]
	s_waitcnt vmcnt(8)
	s_waitcnt lgkmcnt(0)
	s_barrier
	s_setprio 1
	s_waitcnt lgkmcnt(0)
	v_mfma_f32_16x16x32_bf16 v[24:27], v[8:11], v[32:35], v[136:139]
	v_mfma_f32_16x16x32_bf16 v[60:63], v[12:15], v[36:39], v[24:27]
	v_mfma_f32_16x16x32_bf16 v[24:27], v[16:19], v[32:35], v[140:143]
	v_mfma_f32_16x16x32_bf16 v[56:59], v[20:23], v[36:39], v[24:27]
	v_mfma_f32_16x16x32_bf16 v[24:27], v[8:11], v[212:215], v[148:151]
	v_mfma_f32_16x16x32_bf16 v[44:47], v[12:15], v[216:219], v[24:27]
	v_mfma_f32_16x16x32_bf16 v[24:27], v[16:19], v[212:215], v[152:155]
	v_mfma_f32_16x16x32_bf16 v[40:43], v[20:23], v[216:219], v[24:27]
	v_mfma_f32_16x16x32_bf16 v[24:27], v[8:11], v[220:223], v[156:159]
	v_mfma_f32_16x16x32_bf16 v[0:3], v[8:11], v[228:231], v[0:3]
	v_mfma_f32_16x16x32_bf16 v[28:31], v[12:15], v[224:227], v[24:27]
	v_mfma_f32_16x16x32_bf16 v[24:27], v[16:19], v[220:223], v[160:163]
	v_mfma_f32_16x16x32_bf16 v[12:15], v[12:15], v[232:235], v[0:3]
	v_mfma_f32_16x16x32_bf16 v[0:3], v[16:19], v[228:231], v[4:7]
	v_mfma_f32_16x16x32_bf16 v[24:27], v[20:23], v[224:227], v[24:27]
	v_mfma_f32_16x16x32_bf16 v[8:11], v[20:23], v[232:235], v[0:3]
	s_setprio 0
	s_setprio 1
	v_mfma_f32_16x16x32_bf16 v[0:3], v[196:199], v[32:35], v[164:167]
	v_mfma_f32_16x16x32_bf16 v[52:55], v[200:203], v[36:39], v[0:3]
	v_mfma_f32_16x16x32_bf16 v[0:3], v[204:207], v[32:35], v[168:171]
	v_mfma_f32_16x16x32_bf16 v[48:51], v[208:211], v[36:39], v[0:3]
	v_mfma_f32_16x16x32_bf16 v[0:3], v[196:199], v[212:215], v[172:175]
	v_mfma_f32_16x16x32_bf16 v[36:39], v[200:203], v[216:219], v[0:3]
	v_mfma_f32_16x16x32_bf16 v[0:3], v[204:207], v[212:215], v[176:179]
	v_mfma_f32_16x16x32_bf16 v[32:35], v[208:211], v[216:219], v[0:3]
	v_mfma_f32_16x16x32_bf16 v[0:3], v[196:199], v[220:223], v[180:183]
	v_mfma_f32_16x16x32_bf16 v[20:23], v[200:203], v[224:227], v[0:3]
	v_mfma_f32_16x16x32_bf16 v[0:3], v[204:207], v[220:223], v[184:187]
	v_mfma_f32_16x16x32_bf16 v[16:19], v[208:211], v[224:227], v[0:3]
	s_setprio 2
	s_barrier
	v_mfma_f32_16x16x32_bf16 v[0:3], v[196:199], v[228:231], v[188:191]
	v_mfma_f32_16x16x32_bf16 v[4:7], v[200:203], v[232:235], v[0:3]
	v_mfma_f32_16x16x32_bf16 v[0:3], v[204:207], v[228:231], v[192:195]
	v_mfma_f32_16x16x32_bf16 v[0:3], v[208:211], v[232:235], v[0:3]
	s_setprio 0
	s_andn2_b64 vcc, exec, s[10:11]
	s_cbranch_vccnz .LBB13_654
	s_barrier

;     __device__ float mid(int row) const { return rg(row) / ra(row); }
;     __device__ __forceinline__ bool next(int i, Unit& u) const { return map(rank + i * nloc, u); }
; #define PG8_LDA(dst, b, h) do { _Pragma("unroll") for (int m = 0; m < 4; ++m) _Pragma("unroll") for (int k = 0; k < 2; ++k) dst[m][k] = *(const PG8_LAS bf16x8*)(lds + PG8_SA(b, h) + aoff + m * 2048 + k * 1024); } while (0)
; template <class Epi, class Sched, bool ALIGN_EPI = false, bool SP2 = false>
; __device__ __forceinline__ void gemm_phase(PG8_LAS unsigned char* lds, const Gemm g, const Sched& S, const Epi& E, int wid0) {
;     ...
;         const bool has_next = S.next(ui + 1, nxt); nxt.ui = ui + 1;
;         if constexpr (Epi::HAS_PRE) E.pre_finish(lds, cur, tid, pq0, pq1, pq2);
;         const char* nA = has_next ? (const char*)g.A + (size_t)nxt.pm * tstepA : cA; const char* nB = has_next ? (const char*)g.Bt + (size_t)nxt.pn * tstep : cB;
; #pragma nounroll
;         for (int t = 0; t < nt; t += 2) {
;             const bool last = (t == nt - 2);
;             const char* a1 = cA + (size_t)(t + 1) * kstep;
;             const char* a2 = last ? nA : cA + (size_t)(t + 2) * kstep; const char* b2 = last ? nB : cB + (size_t)(t + 2) * kstep;
;             const char* a3 = a2 + kstep; const char* b3 = b2 + kstep;
;             if (last && has_next) S.a_ready(nxt);
;             if constexpr (Epi::HAS_MID) { if (t == Epi::MID_T) E.mid(acc, cur, wr, fr); }
;             unsigned vA_[2] = {voffA[0], voffA[1]}, vB_[2] = {voffB[0], voffB[1]};
;             asm volatile("" : "+v"(vA_[0]), "+v"(vA_[1]), "+v"(vB_[0]), "+v"(vB_[1]));
;             if constexpr (SP2) {
;             PG8_LDB(B0, 0, 0); PG8_LDB(B1, 0, 1); PG8_SCHED; PG8_LDA(At, 0, 0); PG8_STAGE(PG8_SA(1, 1), a1 + hstepA, vA_);
;             PG8_WAIT_V(8); PG8_WAIT_L(0); PG8_BAR; PG8_MMA(0, 0, At, B0); PG8_MMA(0, 1, At, B1); PG8_BAR; PG8_SCHED;
;             PG8_LDA(At, 0, 1); PG8_STAGE(PG8_SB(0, 0), b2, vB_); PG8_STAGE(PG8_SB(0, 1), b2 + hstep, vB_); PG8_STAGE(PG8_SA(0, 0), a2, vA_);
;             PG8_WAIT_V(8); PG8_WAIT_L(0); PG8_BAR; PG8_MMA(1, 0, At, B0); PG8_MMA(1, 1, At, B1); PG8_BAR; PG8_SCHED;
;             PG8_LDB(B0, 1, 0); PG8_LDB(B1, 1, 1); PG8_SCHED; PG8_LDA(At, 1, 0); PG8_STAGE(PG8_SA(0, 1), a2 + hstepA, vA_);
;             PG8_WAIT_V(8); PG8_WAIT_L(0); PG8_BAR; PG8_MMA(0, 0, At, B0); PG8_MMA(0, 1, At, B1); PG8_BAR; PG8_SCHED;
.LBB13_942:
	v_mov_b32_e32 v9, v160
	v_mov_b32_e32 v154, v162
	v_mov_b32_e32 v155, v156
	v_mov_b32_e32 v166, v158
	v_add_u32_e32 v10, s64, v157
	ds_read_b128 v[142:145], v10
	ds_read_b128 v[146:149], v10 offset:1024
	ds_read_b128 v[150:153], v10 offset:2048
	ds_read_b128 v[168:171], v10 offset:3072
	v_add_u32_e32 v10, s65, v157
	s_add_u32 s6, s42, 0x100
	ds_read_b128 v[172:175], v10
	ds_read_b128 v[176:179], v10 offset:1024
	ds_read_b128 v[180:183], v10 offset:2048
	ds_read_b128 v[184:187], v10 offset:3072
	s_addc_u32 s7, s43, 0
	s_cmp_eq_u32 s70, 12
	s_cselect_b32 s50, s35, s6
	s_cselect_b32 s51, s29, s7
	s_cselect_b32 s45, s31, s69
	s_cselect_b32 s44, s67, s68
	s_add_u32 s46, s50, 0x80
	s_addc_u32 s47, s51, 0
	s_add_u32 s48, s44, 0x80
	s_addc_u32 s49, s45, 0
	s_add_u32 s42, s42, 0x80080
	s_addc_u32 s43, s43, 0
	s_add_i32 m0, s13, 0xc000
	ds_read_b128 v[188:191], v167
	ds_read_b128 v[192:195], v167 offset:1024
	ds_read_b128 v[196:199], v167 offset:2048
	ds_read_b128 v[200:203], v167 offset:3072
	ds_read_b128 v[204:207], v167 offset:4096
	ds_read_b128 v[208:211], v167 offset:5120
	ds_read_b128 v[212:215], v167 offset:6144
	ds_read_b128 v[216:219], v167 offset:7168
	s_nop 0
	global_load_lds_dwordx4 v155, s[42:43]
	s_add_i32 m0, s13, 0xe000
	s_nop 0
	global_load_lds_dwordx4 v9, s[42:43]
	s_waitcnt vmcnt(8)
	s_waitcnt lgkmcnt(0)
	s_barrier
	s_setprio 1
	s_waitcnt lgkmcnt(0)
	v_mfma_f32_16x16x32_bf16 v[136:139], v[142:145], v[188:191], v[136:139]
	v_mfma_f32_16x16x32_bf16 v[132:135], v[150:153], v[188:191], v[132:135]
	v_mfma_f32_16x16x32_bf16 v[128:131], v[142:145], v[196:199], v[128:131]
	v_mfma_f32_16x16x32_bf16 v[124:127], v[150:153], v[196:199], v[124:127]
	v_mfma_f32_16x16x32_bf16 v[120:123], v[142:145], v[204:207], v[120:123]
	v_mfma_f32_16x16x32_bf16 v[116:119], v[150:153], v[204:207], v[116:119]
	v_mfma_f32_16x16x32_bf16 v[112:115], v[142:145], v[212:215], v[112:115]
	v_mfma_f32_16x16x32_bf16 v[108:111], v[150:153], v[212:215], v[108:111]
	v_mfma_f32_16x16x32_bf16 v[136:139], v[146:149], v[192:195], v[136:139]
	v_mfma_f32_16x16x32_bf16 v[132:135], v[168:171], v[192:195], v[132:135]
	v_mfma_f32_16x16x32_bf16 v[128:131], v[146:149], v[200:203], v[128:131]
	v_mfma_f32_16x16x32_bf16 v[124:127], v[168:171], v[200:203], v[124:127]
	v_mfma_f32_16x16x32_bf16 v[120:123], v[146:149], v[208:211], v[120:123]
	v_mfma_f32_16x16x32_bf16 v[116:119], v[168:171], v[208:211], v[116:119]
	v_mfma_f32_16x16x32_bf16 v[112:115], v[146:149], v[216:219], v[112:115]
	v_mfma_f32_16x16x32_bf16 v[108:111], v[168:171], v[216:219], v[108:111]
	s_setprio 0
	s_setprio 1
	v_mfma_f32_16x16x32_bf16 v[72:75], v[172:175], v[188:191], v[72:75]
	v_mfma_f32_16x16x32_bf16 v[68:71], v[180:183], v[188:191], v[68:71]
	v_mfma_f32_16x16x32_bf16 v[64:67], v[172:175], v[196:199], v[64:67]
	v_mfma_f32_16x16x32_bf16 v[60:63], v[180:183], v[196:199], v[60:63]
	v_mfma_f32_16x16x32_bf16 v[56:59], v[172:175], v[204:207], v[56:59]
	v_mfma_f32_16x16x32_bf16 v[52:55], v[180:183], v[204:207], v[52:55]
	v_mfma_f32_16x16x32_bf16 v[48:51], v[172:175], v[212:215], v[48:51]
	v_mfma_f32_16x16x32_bf16 v[44:47], v[180:183], v[212:215], v[44:47]
	v_mfma_f32_16x16x32_bf16 v[72:75], v[176:179], v[192:195], v[72:75]
	v_mfma_f32_16x16x32_bf16 v[68:71], v[184:187], v[192:195], v[68:71]
	v_mfma_f32_16x16x32_bf16 v[64:67], v[176:179], v[200:203], v[64:67]
	v_mfma_f32_16x16x32_bf16 v[60:63], v[184:187], v[200:203], v[60:63]
	s_setprio 2
	s_barrier
	v_mfma_f32_16x16x32_bf16 v[56:59], v[176:179], v[208:211], v[56:59]
	v_mfma_f32_16x16x32_bf16 v[52:55], v[184:187], v[208:211], v[52:55]
	v_mfma_f32_16x16x32_bf16 v[48:51], v[176:179], v[216:219], v[48:51]
	v_mfma_f32_16x16x32_bf16 v[44:47], v[184:187], v[216:219], v[44:47]
	s_setprio 0
	s_add_i32 s71, s64, s27
	s_mov_b64 s[42:43], s[44:45]
	s_mov_b32 m0, s71
	ds_read_b128 v[188:191], v167 offset:16384
	ds_read_b128 v[192:195], v167 offset:17408
	ds_read_b128 v[196:199], v167 offset:18432
	ds_read_b128 v[200:203], v167 offset:19456
	ds_read_b128 v[204:207], v167 offset:20480
	ds_read_b128 v[208:211], v167 offset:21504
	ds_read_b128 v[212:215], v167 offset:22528
	ds_read_b128 v[216:219], v167 offset:23552
	s_nop 0
	global_load_lds_dwordx4 v166, s[42:43]
	s_add_i32 m0, s71, 0x2000
	s_nop 0
	global_load_lds_dwordx4 v154, s[42:43]
	s_add_u32 s42, s44, 0x40000
	s_addc_u32 s43, s45, 0
	s_add_i32 s71, s65, s27
	s_mov_b32 m0, s71
	s_nop 0
	global_load_lds_dwordx4 v166, s[42:43]
	s_add_i32 m0, s71, 0x2000
	s_nop 0
	global_load_lds_dwordx4 v154, s[42:43]
	s_mov_b64 s[42:43], s[50:51]
	s_mov_b32 m0, s13
	s_nop 0
	global_load_lds_dwordx4 v155, s[42:43]
	s_mov_b32 m0, s53
	s_nop 0
	global_load_lds_dwordx4 v9, s[42:43]
	s_waitcnt vmcnt(8)
	s_waitcnt lgkmcnt(0)
	s_barrier
; #define PG8_STAGE(bufoff, gbase, voff) do { const char* gb_ = (const char*)(gbase); asm volatile("" : "+s"(gb_));     \
;         _Pragma("unroll") for (int _i = 0; _i < 2; ++_i) \
;         __builtin_amdgcn_global_load_lds((const unsigned*)(gb_ + (voff)[_i]), (PG8_LAS unsigned*)(lds + (bufoff) + ldsw + _i * 8192), 16, 0, 0); } while (0)
; #define PG8_LDA(dst, b, h) do { _Pragma("unroll") for (int m = 0; m < 4; ++m) _Pragma("unroll") for (int k = 0; k < 2; ++k) dst[m][k] = *(const PG8_LAS bf16x8*)(lds + PG8_SA(b, h) + aoff + m * 2048 + k * 1024); } while (0)
; #define PG8_LDB(dst, b, h) do { _Pragma("unroll") for (int n = 0; n < 2; ++n) _Pragma("unroll") for (int k = 0; k < 2; ++k) dst[n][k] = *(const PG8_LAS bf16x8*)(lds + PG8_SB(b, h) + boff + n * 2048 + k * 1024); } while (0)
; #define PG8_MMA(ai, bj, At, Bt) do { __builtin_amdgcn_s_setprio(1); _Pragma("unroll") for (int m = 0; m < 4; ++m) _Pragma("unroll") for (int n = 0; n < 2; ++n) _Pragma("unroll") for (int k = 0; k < 2; ++k) \
;         acc[ai][bj][m][n] = __builtin_amdgcn_mfma_f32_16x16x32_bf16(Bt[n][k], At[m][k], acc[ai][bj][m][n], 0, 0, 0); __builtin_amdgcn_s_setprio(0); } while (0)
; #define PG8_WAIT_V(n) asm volatile("s_waitcnt vmcnt(" #n ")" ::: "memory")
; #define PG8_WAIT_L(n) asm volatile("s_waitcnt lgkmcnt(" #n ")" ::: "memory")
; #define PG8_BAR __builtin_amdgcn_s_barrier()
; #define PG8_SCHED __builtin_amdgcn_sched_barrier(0)
; template <class Epi, class Sched, bool ALIGN_EPI = false, bool SP2 = false>
; __device__ __forceinline__ void gemm_phase(PG8_LAS unsigned char* lds, const Gemm g, const Sched& S, const Epi& E, int wid0) {
;     ...
;             PG8_WAIT_V(8); PG8_WAIT_L(0); PG8_BAR; PG8_MMA(0, 0, At, B0); PG8_MMA(0, 1, At, B1); PG8_BAR; PG8_SCHED;
;             PG8_LDA(At, 0, 1); PG8_STAGE(PG8_SB(0, 0), b2, vB_); PG8_STAGE(PG8_SB(0, 1), b2 + hstep, vB_); PG8_STAGE(PG8_SA(0, 0), a2, vA_);
;             PG8_WAIT_V(8); PG8_WAIT_L(0); PG8_BAR; PG8_MMA(1, 0, At, B0); PG8_MMA(1, 1, At, B1); PG8_BAR; PG8_SCHED;
;             PG8_LDB(B0, 1, 0); PG8_LDB(B1, 1, 1); PG8_SCHED; PG8_LDA(At, 1, 0); PG8_STAGE(PG8_SA(0, 1), a2 + hstepA, vA_);
;             PG8_WAIT_V(8); PG8_WAIT_L(0); PG8_BAR; PG8_MMA(0, 0, At, B0); PG8_MMA(0, 1, At, B1); PG8_BAR; PG8_SCHED;
	s_setprio 1
	s_waitcnt lgkmcnt(0)
	v_mfma_f32_16x16x32_bf16 v[104:107], v[142:145], v[188:191], v[104:107]
	v_mfma_f32_16x16x32_bf16 v[100:103], v[150:153], v[188:191], v[100:103]
	v_mfma_f32_16x16x32_bf16 v[96:99], v[142:145], v[196:199], v[96:99]
	v_mfma_f32_16x16x32_bf16 v[92:95], v[150:153], v[196:199], v[92:95]
	v_mfma_f32_16x16x32_bf16 v[88:91], v[142:145], v[204:207], v[88:91]
	v_mfma_f32_16x16x32_bf16 v[84:87], v[150:153], v[204:207], v[84:87]
	v_mfma_f32_16x16x32_bf16 v[80:83], v[142:145], v[212:215], v[80:83]
	v_mfma_f32_16x16x32_bf16 v[76:79], v[150:153], v[212:215], v[76:79]
	v_mfma_f32_16x16x32_bf16 v[104:107], v[146:149], v[192:195], v[104:107]
	v_mfma_f32_16x16x32_bf16 v[100:103], v[168:171], v[192:195], v[100:103]
	v_mfma_f32_16x16x32_bf16 v[96:99], v[146:149], v[200:203], v[96:99]
	v_mfma_f32_16x16x32_bf16 v[92:95], v[168:171], v[200:203], v[92:95]
	v_mfma_f32_16x16x32_bf16 v[88:91], v[146:149], v[208:211], v[88:91]
	v_mfma_f32_16x16x32_bf16 v[84:87], v[168:171], v[208:211], v[84:87]
	v_mfma_f32_16x16x32_bf16 v[80:83], v[146:149], v[216:219], v[80:83]
	v_mfma_f32_16x16x32_bf16 v[76:79], v[168:171], v[216:219], v[76:79]
	s_setprio 0
	s_setprio 1
	v_mfma_f32_16x16x32_bf16 v[40:43], v[172:175], v[188:191], v[40:43]
	v_mfma_f32_16x16x32_bf16 v[36:39], v[180:183], v[188:191], v[36:39]
	v_mfma_f32_16x16x32_bf16 v[32:35], v[172:175], v[196:199], v[32:35]
	v_mfma_f32_16x16x32_bf16 v[28:31], v[180:183], v[196:199], v[28:31]
	v_mfma_f32_16x16x32_bf16 v[24:27], v[172:175], v[204:207], v[24:27]
	v_mfma_f32_16x16x32_bf16 v[20:23], v[180:183], v[204:207], v[20:23]
	v_mfma_f32_16x16x32_bf16 v[16:19], v[172:175], v[212:215], v[16:19]
	v_mfma_f32_16x16x32_bf16 v[10:13], v[180:183], v[212:215], v[12:15]
	v_mfma_f32_16x16x32_bf16 v[40:43], v[176:179], v[192:195], v[40:43]
	v_mfma_f32_16x16x32_bf16 v[36:39], v[184:187], v[192:195], v[36:39]
	v_mfma_f32_16x16x32_bf16 v[32:35], v[176:179], v[200:203], v[32:35]
	v_mfma_f32_16x16x32_bf16 v[28:31], v[184:187], v[200:203], v[28:31]
	s_setprio 2
	s_barrier
	v_mfma_f32_16x16x32_bf16 v[24:27], v[176:179], v[208:211], v[24:27]
	v_mfma_f32_16x16x32_bf16 v[20:23], v[184:187], v[208:211], v[20:23]
	v_mfma_f32_16x16x32_bf16 v[16:19], v[176:179], v[216:219], v[16:19]
	v_mfma_f32_16x16x32_bf16 v[10:13], v[184:187], v[216:219], v[10:13]
	s_setprio 0
	s_add_i32 s71, 0, 0x18000
	v_add_u32_e32 v14, s71, v157
	s_add_i32 s72, 0, 0x1c000
	ds_read_b128 v[142:145], v14
	ds_read_b128 v[146:149], v14 offset:1024
	ds_read_b128 v[150:153], v14 offset:2048
	ds_read_b128 v[168:171], v14 offset:3072
	v_add_u32_e32 v14, s72, v157
	ds_read_b128 v[172:175], v14
	ds_read_b128 v[176:179], v14 offset:1024
	ds_read_b128 v[180:183], v14 offset:2048
	ds_read_b128 v[184:187], v14 offset:3072
	s_add_u32 s42, s50, 0x80000
	s_addc_u32 s43, s51, 0
	s_mov_b32 m0, s54
	ds_read_b128 v[188:191], v167 offset:32768
	ds_read_b128 v[192:195], v167 offset:33792
	ds_read_b128 v[196:199], v167 offset:34816
	ds_read_b128 v[200:203], v167 offset:35840
	ds_read_b128 v[204:207], v167 offset:36864
	ds_read_b128 v[208:211], v167 offset:37888
	ds_read_b128 v[212:215], v167 offset:38912
	ds_read_b128 v[216:219], v167 offset:39936
	s_nop 0
	global_load_lds_dwordx4 v155, s[42:43]
	s_mov_b32 m0, s55
	s_nop 0
	global_load_lds_dwordx4 v9, s[42:43]
	s_waitcnt vmcnt(8)
	s_waitcnt lgkmcnt(0)
	s_barrier
	s_setprio 1
	s_waitcnt lgkmcnt(0)
	v_mfma_f32_16x16x32_bf16 v[136:139], v[142:145], v[188:191], v[136:139]
	v_mfma_f32_16x16x32_bf16 v[132:135], v[150:153], v[188:191], v[132:135]
	v_mfma_f32_16x16x32_bf16 v[128:131], v[142:145], v[196:199], v[128:131]
	v_mfma_f32_16x16x32_bf16 v[124:127], v[150:153], v[196:199], v[124:127]
	v_mfma_f32_16x16x32_bf16 v[120:123], v[142:145], v[204:207], v[120:123]
	v_mfma_f32_16x16x32_bf16 v[116:119], v[150:153], v[204:207], v[116:119]
	v_mfma_f32_16x16x32_bf16 v[112:115], v[142:145], v[212:215], v[112:115]
	v_mfma_f32_16x16x32_bf16 v[108:111], v[150:153], v[212:215], v[108:111]
	v_mfma_f32_16x16x32_bf16 v[136:139], v[146:149], v[192:195], v[136:139]
	v_mfma_f32_16x16x32_bf16 v[132:135], v[168:171], v[192:195], v[132:135]
	v_mfma_f32_16x16x32_bf16 v[128:131], v[146:149], v[200:203], v[128:131]
	v_mfma_f32_16x16x32_bf16 v[124:127], v[168:171], v[200:203], v[124:127]
	v_mfma_f32_16x16x32_bf16 v[120:123], v[146:149], v[208:211], v[120:123]
	v_mfma_f32_16x16x32_bf16 v[116:119], v[168:171], v[208:211], v[116:119]
	v_mfma_f32_16x16x32_bf16 v[112:115], v[146:149], v[216:219], v[112:115]
	v_mfma_f32_16x16x32_bf16 v[108:111], v[168:171], v[216:219], v[108:111]
	s_setprio 0
	s_setprio 1
	v_mfma_f32_16x16x32_bf16 v[72:75], v[172:175], v[188:191], v[72:75]
	v_mfma_f32_16x16x32_bf16 v[68:71], v[180:183], v[188:191], v[68:71]
	v_mfma_f32_16x16x32_bf16 v[64:67], v[172:175], v[196:199], v[64:67]
	v_mfma_f32_16x16x32_bf16 v[60:63], v[180:183], v[196:199], v[60:63]
	v_mfma_f32_16x16x32_bf16 v[56:59], v[172:175], v[204:207], v[56:59]
	v_mfma_f32_16x16x32_bf16 v[52:55], v[180:183], v[204:207], v[52:55]
	v_mfma_f32_16x16x32_bf16 v[48:51], v[172:175], v[212:215], v[48:51]
	v_mfma_f32_16x16x32_bf16 v[44:47], v[180:183], v[212:215], v[44:47]
	v_mfma_f32_16x16x32_bf16 v[72:75], v[176:179], v[192:195], v[72:75]
	v_mfma_f32_16x16x32_bf16 v[68:71], v[184:187], v[192:195], v[68:71]
	v_mfma_f32_16x16x32_bf16 v[64:67], v[176:179], v[200:203], v[64:67]
	v_mfma_f32_16x16x32_bf16 v[60:63], v[184:187], v[200:203], v[60:63]
	s_setprio 2
	s_barrier
;     __device__ float mid(int row) const { return rg(row) / ra(row); }
; #define PG8_STAGE(bufoff, gbase, voff) do { const char* gb_ = (const char*)(gbase); asm volatile("" : "+s"(gb_));     \
;         _Pragma("unroll") for (int _i = 0; _i < 2; ++_i) \
;         __builtin_amdgcn_global_load_lds((const unsigned*)(gb_ + (voff)[_i]), (PG8_LAS unsigned*)(lds + (bufoff) + ldsw + _i * 8192), 16, 0, 0); } while (0)
; #define PG8_LDA(dst, b, h) do { _Pragma("unroll") for (int m = 0; m < 4; ++m) _Pragma("unroll") for (int k = 0; k < 2; ++k) dst[m][k] = *(const PG8_LAS bf16x8*)(lds + PG8_SA(b, h) + aoff + m * 2048 + k * 1024); } while (0)
; #define PG8_MMA(ai, bj, At, Bt) do { __builtin_amdgcn_s_setprio(1); _Pragma("unroll") for (int m = 0; m < 4; ++m) _Pragma("unroll") for (int n = 0; n < 2; ++n) _Pragma("unroll") for (int k = 0; k < 2; ++k) \
;         acc[ai][bj][m][n] = __builtin_amdgcn_mfma_f32_16x16x32_bf16(Bt[n][k], At[m][k], acc[ai][bj][m][n], 0, 0, 0); __builtin_amdgcn_s_setprio(0); } while (0)
; #define PG8_WAIT_V(n) asm volatile("s_waitcnt vmcnt(" #n ")" ::: "memory")
; #define PG8_WAIT_L(n) asm volatile("s_waitcnt lgkmcnt(" #n ")" ::: "memory")
; #define PG8_BAR __builtin_amdgcn_s_barrier()
; #define PG8_SCHED __builtin_amdgcn_sched_barrier(0)
; template <class Epi, class Sched, bool ALIGN_EPI = false, bool SP2 = false>
; __device__ __forceinline__ void gemm_phase(PG8_LAS unsigned char* lds, const Gemm g, const Sched& S, const Epi& E, int wid0) {
;     ...
;             if constexpr (Epi::HAS_MID) { if (t == Epi::MID_T) E.mid(acc, cur, wr, fr); }
;     ...
;             PG8_WAIT_V(8); PG8_WAIT_L(0); PG8_BAR; PG8_MMA(0, 0, At, B0); PG8_MMA(0, 1, At, B1); PG8_BAR; PG8_SCHED;
;             PG8_LDA(At, 1, 1); PG8_STAGE(PG8_SB(1, 0), b3, vB_); PG8_STAGE(PG8_SB(1, 1), b3 + hstep, vB_); PG8_STAGE(PG8_SA(1, 0), a3, vA_);
;             PG8_WAIT_V(8); PG8_WAIT_L(0); PG8_BAR; PG8_MMA(1, 0, At, B0); PG8_MMA(1, 1, At, B1); PG8_BAR; PG8_SCHED;
	v_mfma_f32_16x16x32_bf16 v[56:59], v[176:179], v[208:211], v[56:59]
	v_mfma_f32_16x16x32_bf16 v[52:55], v[184:187], v[208:211], v[52:55]
	v_mfma_f32_16x16x32_bf16 v[48:51], v[176:179], v[216:219], v[48:51]
	v_mfma_f32_16x16x32_bf16 v[44:47], v[184:187], v[216:219], v[44:47]
	s_setprio 0
	s_add_i32 s42, s71, s27
	s_mov_b32 m0, s42
	ds_read_b128 v[188:191], v167 offset:49152
	ds_read_b128 v[192:195], v167 offset:50176
	ds_read_b128 v[196:199], v167 offset:51200
	ds_read_b128 v[200:203], v167 offset:52224
	ds_read_b128 v[204:207], v167 offset:53248
	ds_read_b128 v[208:211], v167 offset:54272
	ds_read_b128 v[212:215], v167 offset:55296
	ds_read_b128 v[216:219], v167 offset:56320
	s_nop 0
	global_load_lds_dwordx4 v166, s[48:49]
	s_add_i32 m0, s42, 0x2000
	s_add_u32 s42, s44, 0x40080
	s_addc_u32 s43, s45, 0
	s_add_i32 s44, s72, s27
	global_load_lds_dwordx4 v154, s[48:49]
	s_mov_b32 m0, s44
	s_nop 0
	global_load_lds_dwordx4 v166, s[42:43]
	s_add_i32 m0, s44, 0x2000
	s_nop 0
	global_load_lds_dwordx4 v154, s[42:43]
	s_mov_b32 m0, s59
	s_nop 0
	global_load_lds_dwordx4 v155, s[46:47]
	s_mov_b32 m0, s60
	s_nop 0
	global_load_lds_dwordx4 v9, s[46:47]
	s_waitcnt vmcnt(8)
	s_waitcnt lgkmcnt(0)
	s_barrier
	s_setprio 1
	s_waitcnt lgkmcnt(0)
	v_mfma_f32_16x16x32_bf16 v[104:107], v[142:145], v[188:191], v[104:107]
	v_mfma_f32_16x16x32_bf16 v[100:103], v[150:153], v[188:191], v[100:103]
	v_mfma_f32_16x16x32_bf16 v[96:99], v[142:145], v[196:199], v[96:99]
	v_mfma_f32_16x16x32_bf16 v[92:95], v[150:153], v[196:199], v[92:95]
	v_mfma_f32_16x16x32_bf16 v[88:91], v[142:145], v[204:207], v[88:91]
	v_mfma_f32_16x16x32_bf16 v[84:87], v[150:153], v[204:207], v[84:87]
	v_mfma_f32_16x16x32_bf16 v[80:83], v[142:145], v[212:215], v[80:83]
	v_mfma_f32_16x16x32_bf16 v[76:79], v[150:153], v[212:215], v[76:79]
	v_mfma_f32_16x16x32_bf16 v[104:107], v[146:149], v[192:195], v[104:107]
	v_mfma_f32_16x16x32_bf16 v[100:103], v[168:171], v[192:195], v[100:103]
	v_mfma_f32_16x16x32_bf16 v[96:99], v[146:149], v[200:203], v[96:99]
	v_mfma_f32_16x16x32_bf16 v[92:95], v[168:171], v[200:203], v[92:95]
	v_mfma_f32_16x16x32_bf16 v[88:91], v[146:149], v[208:211], v[88:91]
	v_mfma_f32_16x16x32_bf16 v[84:87], v[168:171], v[208:211], v[84:87]
	v_mfma_f32_16x16x32_bf16 v[80:83], v[146:149], v[216:219], v[80:83]
	v_mfma_f32_16x16x32_bf16 v[76:79], v[168:171], v[216:219], v[76:79]
	s_setprio 0
	s_setprio 1
	v_mfma_f32_16x16x32_bf16 v[40:43], v[172:175], v[188:191], v[40:43]
	v_mfma_f32_16x16x32_bf16 v[36:39], v[180:183], v[188:191], v[36:39]
	v_mfma_f32_16x16x32_bf16 v[32:35], v[172:175], v[196:199], v[32:35]
	v_mfma_f32_16x16x32_bf16 v[28:31], v[180:183], v[196:199], v[28:31]
	v_mfma_f32_16x16x32_bf16 v[24:27], v[172:175], v[204:207], v[24:27]
	v_mfma_f32_16x16x32_bf16 v[20:23], v[180:183], v[204:207], v[20:23]
	v_mfma_f32_16x16x32_bf16 v[14:17], v[172:175], v[212:215], v[16:19]
	v_mfma_f32_16x16x32_bf16 v[10:13], v[180:183], v[212:215], v[10:13]
	v_mfma_f32_16x16x32_bf16 v[40:43], v[176:179], v[192:195], v[40:43]
	v_mfma_f32_16x16x32_bf16 v[36:39], v[184:187], v[192:195], v[36:39]
	v_mfma_f32_16x16x32_bf16 v[32:35], v[176:179], v[200:203], v[32:35]
	v_mfma_f32_16x16x32_bf16 v[28:31], v[184:187], v[200:203], v[28:31]
	s_setprio 2
	s_barrier
	v_mfma_f32_16x16x32_bf16 v[24:27], v[176:179], v[208:211], v[24:27]
	v_mfma_f32_16x16x32_bf16 v[20:23], v[184:187], v[208:211], v[20:23]
	v_mfma_f32_16x16x32_bf16 v[16:19], v[176:179], v[216:219], v[14:17]
	v_mfma_f32_16x16x32_bf16 v[12:15], v[184:187], v[216:219], v[10:13]
	s_setprio 0
	s_add_i32 s70, s70, 2
	s_add_u32 s68, s68, 0x100
	s_addc_u32 s69, s69, 0
	s_cmp_gt_u32 s70, 13
	s_cbranch_scc1 .LBB13_944
	s_mov_b64 s[42:43], s[6:7]
	s_cmp_lg_u32 s70, 6
	s_cbranch_scc0 .LBB13_941
	s_branch .LBB13_942

;     __device__ float mid(int row) const { return rg(row) / ra(row); }
;     __device__ __forceinline__ bool next(int i, Unit& u) const { return map(rank + i * nloc, u); }
; #define PG8_LDA(dst, b, h) do { _Pragma("unroll") for (int m = 0; m < 4; ++m) _Pragma("unroll") for (int k = 0; k < 2; ++k) dst[m][k] = *(const PG8_LAS bf16x8*)(lds + PG8_SA(b, h) + aoff + m * 2048 + k * 1024); } while (0)
; template <class Epi, class Sched, bool ALIGN_EPI = false, bool SP2 = false>
; __device__ __forceinline__ void gemm_phase(PG8_LAS unsigned char* lds, const Gemm g, const Sched& S, const Epi& E, int wid0) {
;     ...
;         const bool has_next = S.next(ui + 1, nxt); nxt.ui = ui + 1;
;         if constexpr (Epi::HAS_PRE) E.pre_finish(lds, cur, tid, pq0, pq1, pq2);
;         const char* nA = has_next ? (const char*)g.A + (size_t)nxt.pm * tstepA : cA; const char* nB = has_next ? (const char*)g.Bt + (size_t)nxt.pn * tstep : cB;
; #pragma nounroll
;         for (int t = 0; t < nt; t += 2) {
;             const bool last = (t == nt - 2);
;             const char* a1 = cA + (size_t)(t + 1) * kstep;
;             const char* a2 = last ? nA : cA + (size_t)(t + 2) * kstep; const char* b2 = last ? nB : cB + (size_t)(t + 2) * kstep;
;             const char* a3 = a2 + kstep; const char* b3 = b2 + kstep;
;             if (last && has_next) S.a_ready(nxt);
;             if constexpr (Epi::HAS_MID) { if (t == Epi::MID_T) E.mid(acc, cur, wr, fr); }
;             unsigned vA_[2] = {voffA[0], voffA[1]}, vB_[2] = {voffB[0], voffB[1]};
;             asm volatile("" : "+v"(vA_[0]), "+v"(vA_[1]), "+v"(vB_[0]), "+v"(vB_[1]));
;             if constexpr (SP2) {
;             PG8_LDB(B0, 0, 0); PG8_LDB(B1, 0, 1); PG8_SCHED; PG8_LDA(At, 0, 0); PG8_STAGE(PG8_SA(1, 1), a1 + hstepA, vA_);
;             PG8_WAIT_V(8); PG8_WAIT_L(0); PG8_BAR; PG8_MMA(0, 0, At, B0); PG8_MMA(0, 1, At, B1); PG8_BAR; PG8_SCHED;
;             PG8_LDA(At, 0, 1); PG8_STAGE(PG8_SB(0, 0), b2, vB_); PG8_STAGE(PG8_SB(0, 1), b2 + hstep, vB_); PG8_STAGE(PG8_SA(0, 0), a2, vA_);
;             PG8_WAIT_V(8); PG8_WAIT_L(0); PG8_BAR; PG8_MMA(1, 0, At, B0); PG8_MMA(1, 1, At, B1); PG8_BAR; PG8_SCHED;
;             PG8_LDB(B0, 1, 0); PG8_LDB(B1, 1, 1); PG8_SCHED; PG8_LDA(At, 1, 0); PG8_STAGE(PG8_SA(0, 1), a2 + hstepA, vA_);
;             PG8_WAIT_V(8); PG8_WAIT_L(0); PG8_BAR; PG8_MMA(0, 0, At, B0); PG8_MMA(0, 1, At, B1); PG8_BAR; PG8_SCHED;
.LBB13_1074:
	v_mov_b32_e32 v218, v158
	v_mov_b32_e32 v219, v8
	v_mov_b32_e32 v220, v160
	v_mov_b32_e32 v221, v162
	ds_read_b128 v[142:145], v171
	ds_read_b128 v[146:149], v171 offset:1024
	ds_read_b128 v[150:153], v171 offset:2048
	ds_read_b128 v[154:157], v171 offset:3072
	ds_read_b128 v[164:167], v172
	ds_read_b128 v[174:177], v172 offset:1024
	ds_read_b128 v[178:181], v172 offset:2048
	ds_read_b128 v[182:185], v172 offset:3072
	s_add_u32 s34, s8, 0x100
	s_addc_u32 s35, s9, 0
	s_cmp_eq_u32 s61, 12
	s_cselect_b32 s40, s57, s34
	s_cselect_b32 s41, s19, s35
	s_cselect_b32 s38, s58, s59
	s_cselect_b32 s39, s21, s60
	s_add_u32 s36, s40, 0x80
	s_addc_u32 s37, s41, 0
	s_add_u32 s8, s8, 0x40080
	s_addc_u32 s9, s9, 0
	s_add_i32 m0, s29, 0xc000
	ds_read_b128 v[186:189], v173
	ds_read_b128 v[190:193], v173 offset:1024
	ds_read_b128 v[194:197], v173 offset:2048
	ds_read_b128 v[198:201], v173 offset:3072
	ds_read_b128 v[202:205], v173 offset:4096
	ds_read_b128 v[206:209], v173 offset:5120
	ds_read_b128 v[210:213], v173 offset:6144
	ds_read_b128 v[214:217], v173 offset:7168
	s_nop 0
	global_load_lds_dwordx4 v218, s[8:9]
	s_add_i32 m0, s29, 0xe000
	s_nop 0
	global_load_lds_dwordx4 v220, s[8:9]
	s_waitcnt vmcnt(8)
	s_waitcnt lgkmcnt(0)
	s_barrier
	s_setprio 1
	s_waitcnt lgkmcnt(0)
	v_mfma_f32_16x16x32_bf16 v[138:141], v[142:145], v[186:189], v[138:141]
	v_mfma_f32_16x16x32_bf16 v[134:137], v[150:153], v[186:189], v[134:137]
	v_mfma_f32_16x16x32_bf16 v[122:125], v[142:145], v[194:197], v[122:125]
	v_mfma_f32_16x16x32_bf16 v[118:121], v[150:153], v[194:197], v[118:121]
	v_mfma_f32_16x16x32_bf16 v[106:109], v[142:145], v[202:205], v[106:109]
	v_mfma_f32_16x16x32_bf16 v[102:105], v[150:153], v[202:205], v[102:105]
	v_mfma_f32_16x16x32_bf16 v[90:93], v[142:145], v[210:213], v[90:93]
	v_mfma_f32_16x16x32_bf16 v[86:89], v[150:153], v[210:213], v[86:89]
	v_mfma_f32_16x16x32_bf16 v[138:141], v[146:149], v[190:193], v[138:141]
	v_mfma_f32_16x16x32_bf16 v[134:137], v[154:157], v[190:193], v[134:137]
	v_mfma_f32_16x16x32_bf16 v[122:125], v[146:149], v[198:201], v[122:125]
	v_mfma_f32_16x16x32_bf16 v[118:121], v[154:157], v[198:201], v[118:121]
	v_mfma_f32_16x16x32_bf16 v[106:109], v[146:149], v[206:209], v[106:109]
	v_mfma_f32_16x16x32_bf16 v[102:105], v[154:157], v[206:209], v[102:105]
	v_mfma_f32_16x16x32_bf16 v[90:93], v[146:149], v[214:217], v[90:93]
	v_mfma_f32_16x16x32_bf16 v[86:89], v[154:157], v[214:217], v[86:89]
	s_setprio 0
	s_setprio 1
	v_mfma_f32_16x16x32_bf16 v[130:133], v[164:167], v[186:189], v[130:133]
	v_mfma_f32_16x16x32_bf16 v[126:129], v[178:181], v[186:189], v[126:129]
	v_mfma_f32_16x16x32_bf16 v[114:117], v[164:167], v[194:197], v[114:117]
	v_mfma_f32_16x16x32_bf16 v[110:113], v[178:181], v[194:197], v[110:113]
	v_mfma_f32_16x16x32_bf16 v[98:101], v[164:167], v[202:205], v[98:101]
	v_mfma_f32_16x16x32_bf16 v[94:97], v[178:181], v[202:205], v[94:97]
	v_mfma_f32_16x16x32_bf16 v[82:85], v[164:167], v[210:213], v[82:85]
	v_mfma_f32_16x16x32_bf16 v[78:81], v[178:181], v[210:213], v[78:81]
	v_mfma_f32_16x16x32_bf16 v[130:133], v[174:177], v[190:193], v[130:133]
	v_mfma_f32_16x16x32_bf16 v[126:129], v[182:185], v[190:193], v[126:129]
	v_mfma_f32_16x16x32_bf16 v[114:117], v[174:177], v[198:201], v[114:117]
	v_mfma_f32_16x16x32_bf16 v[110:113], v[182:185], v[198:201], v[110:113]
	s_setprio 2
	s_barrier
	v_mfma_f32_16x16x32_bf16 v[98:101], v[174:177], v[206:209], v[98:101]
	v_mfma_f32_16x16x32_bf16 v[94:97], v[182:185], v[206:209], v[94:97]
	v_mfma_f32_16x16x32_bf16 v[82:85], v[174:177], v[214:217], v[82:85]
	v_mfma_f32_16x16x32_bf16 v[78:81], v[182:185], v[214:217], v[78:81]
	s_setprio 0
	s_add_i32 s62, s53, s27
	s_mov_b64 s[8:9], s[38:39]
	s_mov_b32 m0, s62
	ds_read_b128 v[186:189], v173 offset:16384
	ds_read_b128 v[190:193], v173 offset:17408
	ds_read_b128 v[194:197], v173 offset:18432
	ds_read_b128 v[198:201], v173 offset:19456
	ds_read_b128 v[202:205], v173 offset:20480
	ds_read_b128 v[206:209], v173 offset:21504
	ds_read_b128 v[210:213], v173 offset:22528
	ds_read_b128 v[214:217], v173 offset:23552
	s_nop 0
	global_load_lds_dwordx4 v219, s[8:9]
	s_add_i32 m0, s62, 0x2000
	s_nop 0
	global_load_lds_dwordx4 v221, s[8:9]
	s_add_u32 s8, s38, 0x40000
	s_addc_u32 s9, s39, 0
	s_add_i32 s62, s54, s27
	s_mov_b32 m0, s62
	s_nop 0
	global_load_lds_dwordx4 v219, s[8:9]
	s_add_i32 m0, s62, 0x2000
	s_nop 0
	global_load_lds_dwordx4 v221, s[8:9]
	s_mov_b64 s[8:9], s[40:41]
	s_mov_b32 m0, s29
	s_nop 0
	global_load_lds_dwordx4 v218, s[8:9]
	s_mov_b32 m0, s45
	s_nop 0
	global_load_lds_dwordx4 v220, s[8:9]
	s_waitcnt vmcnt(8)
	s_waitcnt lgkmcnt(0)
	s_barrier
	s_setprio 1
	s_waitcnt lgkmcnt(0)
	v_mfma_f32_16x16x32_bf16 v[74:77], v[142:145], v[186:189], v[74:77]
	v_mfma_f32_16x16x32_bf16 v[70:73], v[150:153], v[186:189], v[70:73]
	v_mfma_f32_16x16x32_bf16 v[58:61], v[142:145], v[194:197], v[58:61]
	v_mfma_f32_16x16x32_bf16 v[54:57], v[150:153], v[194:197], v[54:57]
	v_mfma_f32_16x16x32_bf16 v[42:45], v[142:145], v[202:205], v[42:45]
	v_mfma_f32_16x16x32_bf16 v[38:41], v[150:153], v[202:205], v[38:41]
	v_mfma_f32_16x16x32_bf16 v[26:29], v[142:145], v[210:213], v[26:29]
	v_mfma_f32_16x16x32_bf16 v[22:25], v[150:153], v[210:213], v[22:25]
	v_mfma_f32_16x16x32_bf16 v[74:77], v[146:149], v[190:193], v[74:77]
	v_mfma_f32_16x16x32_bf16 v[70:73], v[154:157], v[190:193], v[70:73]
	v_mfma_f32_16x16x32_bf16 v[58:61], v[146:149], v[198:201], v[58:61]
	v_mfma_f32_16x16x32_bf16 v[54:57], v[154:157], v[198:201], v[54:57]
	v_mfma_f32_16x16x32_bf16 v[42:45], v[146:149], v[206:209], v[42:45]
	v_mfma_f32_16x16x32_bf16 v[38:41], v[154:157], v[206:209], v[38:41]
	v_mfma_f32_16x16x32_bf16 v[26:29], v[146:149], v[214:217], v[26:29]
	v_mfma_f32_16x16x32_bf16 v[22:25], v[154:157], v[214:217], v[22:25]
	s_setprio 0
	s_setprio 1
	v_mfma_f32_16x16x32_bf16 v[66:69], v[164:167], v[186:189], v[66:69]
	v_mfma_f32_16x16x32_bf16 v[62:65], v[178:181], v[186:189], v[62:65]
	v_mfma_f32_16x16x32_bf16 v[50:53], v[164:167], v[194:197], v[50:53]
	v_mfma_f32_16x16x32_bf16 v[46:49], v[178:181], v[194:197], v[46:49]
	v_mfma_f32_16x16x32_bf16 v[34:37], v[164:167], v[202:205], v[34:37]
	v_mfma_f32_16x16x32_bf16 v[30:33], v[178:181], v[202:205], v[30:33]
	v_mfma_f32_16x16x32_bf16 v[18:21], v[164:167], v[210:213], v[18:21]
	v_mfma_f32_16x16x32_bf16 v[14:17], v[178:181], v[210:213], v[14:17]
	v_mfma_f32_16x16x32_bf16 v[66:69], v[174:177], v[190:193], v[66:69]
	v_mfma_f32_16x16x32_bf16 v[62:65], v[182:185], v[190:193], v[62:65]
	v_mfma_f32_16x16x32_bf16 v[50:53], v[174:177], v[198:201], v[50:53]
	v_mfma_f32_16x16x32_bf16 v[46:49], v[182:185], v[198:201], v[46:49]
	s_setprio 2
	s_barrier
; #define PG8_STAGE(bufoff, gbase, voff) do { const char* gb_ = (const char*)(gbase); asm volatile("" : "+s"(gb_));     \
;         _Pragma("unroll") for (int _i = 0; _i < 2; ++_i) \
;         __builtin_amdgcn_global_load_lds((const unsigned*)(gb_ + (voff)[_i]), (PG8_LAS unsigned*)(lds + (bufoff) + ldsw + _i * 8192), 16, 0, 0); } while (0)
; #define PG8_LDA(dst, b, h) do { _Pragma("unroll") for (int m = 0; m < 4; ++m) _Pragma("unroll") for (int k = 0; k < 2; ++k) dst[m][k] = *(const PG8_LAS bf16x8*)(lds + PG8_SA(b, h) + aoff + m * 2048 + k * 1024); } while (0)
; #define PG8_LDB(dst, b, h) do { _Pragma("unroll") for (int n = 0; n < 2; ++n) _Pragma("unroll") for (int k = 0; k < 2; ++k) dst[n][k] = *(const PG8_LAS bf16x8*)(lds + PG8_SB(b, h) + boff + n * 2048 + k * 1024); } while (0)
; #define PG8_MMA(ai, bj, At, Bt) do { __builtin_amdgcn_s_setprio(1); _Pragma("unroll") for (int m = 0; m < 4; ++m) _Pragma("unroll") for (int n = 0; n < 2; ++n) _Pragma("unroll") for (int k = 0; k < 2; ++k) \
;         acc[ai][bj][m][n] = __builtin_amdgcn_mfma_f32_16x16x32_bf16(Bt[n][k], At[m][k], acc[ai][bj][m][n], 0, 0, 0); __builtin_amdgcn_s_setprio(0); } while (0)
; #define PG8_WAIT_V(n) asm volatile("s_waitcnt vmcnt(" #n ")" ::: "memory")
; #define PG8_WAIT_L(n) asm volatile("s_waitcnt lgkmcnt(" #n ")" ::: "memory")
; #define PG8_BAR __builtin_amdgcn_s_barrier()
; #define PG8_SCHED __builtin_amdgcn_sched_barrier(0)
; template <class Epi, class Sched, bool ALIGN_EPI = false, bool SP2 = false>
; __device__ __forceinline__ void gemm_phase(PG8_LAS unsigned char* lds, const Gemm g, const Sched& S, const Epi& E, int wid0) {
;     ...
;             PG8_WAIT_V(8); PG8_WAIT_L(0); PG8_BAR; PG8_MMA(0, 0, At, B0); PG8_MMA(0, 1, At, B1); PG8_BAR; PG8_SCHED;
;             PG8_LDA(At, 0, 1); PG8_STAGE(PG8_SB(0, 0), b2, vB_); PG8_STAGE(PG8_SB(0, 1), b2 + hstep, vB_); PG8_STAGE(PG8_SA(0, 0), a2, vA_);
;             PG8_WAIT_V(8); PG8_WAIT_L(0); PG8_BAR; PG8_MMA(1, 0, At, B0); PG8_MMA(1, 1, At, B1); PG8_BAR; PG8_SCHED;
;             PG8_LDB(B0, 1, 0); PG8_LDB(B1, 1, 1); PG8_SCHED; PG8_LDA(At, 1, 0); PG8_STAGE(PG8_SA(0, 1), a2 + hstepA, vA_);
;             PG8_WAIT_V(8); PG8_WAIT_L(0); PG8_BAR; PG8_MMA(0, 0, At, B0); PG8_MMA(0, 1, At, B1); PG8_BAR; PG8_SCHED;
	v_mfma_f32_16x16x32_bf16 v[34:37], v[174:177], v[206:209], v[34:37]
	v_mfma_f32_16x16x32_bf16 v[30:33], v[182:185], v[206:209], v[30:33]
	v_mfma_f32_16x16x32_bf16 v[18:21], v[174:177], v[214:217], v[18:21]
	v_mfma_f32_16x16x32_bf16 v[14:17], v[182:185], v[214:217], v[14:17]
	s_setprio 0
	s_add_i32 s62, 0, 0x18000
	s_add_i32 s63, 0, 0x1c000
	v_add_u32_e32 v154, s62, v9
	v_add_u32_e32 v182, s63, v9
	ds_read_b128 v[142:145], v154
	ds_read_b128 v[146:149], v154 offset:1024
	ds_read_b128 v[150:153], v154 offset:2048
	ds_read_b128 v[154:157], v154 offset:3072
	ds_read_b128 v[164:167], v182
	ds_read_b128 v[174:177], v182 offset:1024
	ds_read_b128 v[178:181], v182 offset:2048
	ds_read_b128 v[182:185], v182 offset:3072
	s_add_u32 s8, s40, 0x40000
	s_addc_u32 s9, s41, 0
	s_mov_b32 m0, s46
	ds_read_b128 v[186:189], v173 offset:32768
	ds_read_b128 v[190:193], v173 offset:33792
	ds_read_b128 v[194:197], v173 offset:34816
	ds_read_b128 v[198:201], v173 offset:35840
	ds_read_b128 v[202:205], v173 offset:36864
	ds_read_b128 v[206:209], v173 offset:37888
	ds_read_b128 v[210:213], v173 offset:38912
	ds_read_b128 v[214:217], v173 offset:39936
	s_nop 0
	global_load_lds_dwordx4 v218, s[8:9]
	s_mov_b32 m0, s47
	s_nop 0
	global_load_lds_dwordx4 v220, s[8:9]
	s_waitcnt vmcnt(8)
	s_waitcnt lgkmcnt(0)
	s_barrier
	s_setprio 1
	s_waitcnt lgkmcnt(0)
	v_mfma_f32_16x16x32_bf16 v[138:141], v[142:145], v[186:189], v[138:141]
	v_mfma_f32_16x16x32_bf16 v[134:137], v[150:153], v[186:189], v[134:137]
	v_mfma_f32_16x16x32_bf16 v[122:125], v[142:145], v[194:197], v[122:125]
	v_mfma_f32_16x16x32_bf16 v[118:121], v[150:153], v[194:197], v[118:121]
	v_mfma_f32_16x16x32_bf16 v[106:109], v[142:145], v[202:205], v[106:109]
	v_mfma_f32_16x16x32_bf16 v[102:105], v[150:153], v[202:205], v[102:105]
	v_mfma_f32_16x16x32_bf16 v[90:93], v[142:145], v[210:213], v[90:93]
	v_mfma_f32_16x16x32_bf16 v[86:89], v[150:153], v[210:213], v[86:89]
	v_mfma_f32_16x16x32_bf16 v[138:141], v[146:149], v[190:193], v[138:141]
	v_mfma_f32_16x16x32_bf16 v[134:137], v[154:157], v[190:193], v[134:137]
	v_mfma_f32_16x16x32_bf16 v[122:125], v[146:149], v[198:201], v[122:125]
	v_mfma_f32_16x16x32_bf16 v[118:121], v[154:157], v[198:201], v[118:121]
	v_mfma_f32_16x16x32_bf16 v[106:109], v[146:149], v[206:209], v[106:109]
	v_mfma_f32_16x16x32_bf16 v[102:105], v[154:157], v[206:209], v[102:105]
	v_mfma_f32_16x16x32_bf16 v[90:93], v[146:149], v[214:217], v[90:93]
	v_mfma_f32_16x16x32_bf16 v[86:89], v[154:157], v[214:217], v[86:89]
	s_setprio 0
	s_setprio 1
	v_mfma_f32_16x16x32_bf16 v[130:133], v[164:167], v[186:189], v[130:133]
	v_mfma_f32_16x16x32_bf16 v[126:129], v[178:181], v[186:189], v[126:129]
	v_mfma_f32_16x16x32_bf16 v[114:117], v[164:167], v[194:197], v[114:117]
	v_mfma_f32_16x16x32_bf16 v[110:113], v[178:181], v[194:197], v[110:113]
	v_mfma_f32_16x16x32_bf16 v[98:101], v[164:167], v[202:205], v[98:101]
	v_mfma_f32_16x16x32_bf16 v[94:97], v[178:181], v[202:205], v[94:97]
	v_mfma_f32_16x16x32_bf16 v[82:85], v[164:167], v[210:213], v[82:85]
	v_mfma_f32_16x16x32_bf16 v[78:81], v[178:181], v[210:213], v[78:81]
	v_mfma_f32_16x16x32_bf16 v[130:133], v[174:177], v[190:193], v[130:133]
	v_mfma_f32_16x16x32_bf16 v[126:129], v[182:185], v[190:193], v[126:129]
	v_mfma_f32_16x16x32_bf16 v[114:117], v[174:177], v[198:201], v[114:117]
	v_mfma_f32_16x16x32_bf16 v[110:113], v[182:185], v[198:201], v[110:113]
	s_setprio 2
	s_barrier
; #define PG8_STAGE(bufoff, gbase, voff) do { const char* gb_ = (const char*)(gbase); asm volatile("" : "+s"(gb_));     \
;         _Pragma("unroll") for (int _i = 0; _i < 2; ++_i) \
;         __builtin_amdgcn_global_load_lds((const unsigned*)(gb_ + (voff)[_i]), (PG8_LAS unsigned*)(lds + (bufoff) + ldsw + _i * 8192), 16, 0, 0); } while (0)
; #define PG8_LDA(dst, b, h) do { _Pragma("unroll") for (int m = 0; m < 4; ++m) _Pragma("unroll") for (int k = 0; k < 2; ++k) dst[m][k] = *(const PG8_LAS bf16x8*)(lds + PG8_SA(b, h) + aoff + m * 2048 + k * 1024); } while (0)
; #define PG8_MMA(ai, bj, At, Bt) do { __builtin_amdgcn_s_setprio(1); _Pragma("unroll") for (int m = 0; m < 4; ++m) _Pragma("unroll") for (int n = 0; n < 2; ++n) _Pragma("unroll") for (int k = 0; k < 2; ++k) \
;         acc[ai][bj][m][n] = __builtin_amdgcn_mfma_f32_16x16x32_bf16(Bt[n][k], At[m][k], acc[ai][bj][m][n], 0, 0, 0); __builtin_amdgcn_s_setprio(0); } while (0)
; #define PG8_WAIT_V(n) asm volatile("s_waitcnt vmcnt(" #n ")" ::: "memory")
; #define PG8_WAIT_L(n) asm volatile("s_waitcnt lgkmcnt(" #n ")" ::: "memory")
; #define PG8_BAR __builtin_amdgcn_s_barrier()
; #define PG8_SCHED __builtin_amdgcn_sched_barrier(0)
; template <class Epi, class Sched, bool ALIGN_EPI = false, bool SP2 = false>
; __device__ __forceinline__ void gemm_phase(PG8_LAS unsigned char* lds, const Gemm g, const Sched& S, const Epi& E, int wid0) {
;     ...
;             PG8_WAIT_V(8); PG8_WAIT_L(0); PG8_BAR; PG8_MMA(0, 0, At, B0); PG8_MMA(0, 1, At, B1); PG8_BAR; PG8_SCHED;
;             PG8_LDA(At, 1, 1); PG8_STAGE(PG8_SB(1, 0), b3, vB_); PG8_STAGE(PG8_SB(1, 1), b3 + hstep, vB_); PG8_STAGE(PG8_SA(1, 0), a3, vA_);
;             PG8_WAIT_V(8); PG8_WAIT_L(0); PG8_BAR; PG8_MMA(1, 0, At, B0); PG8_MMA(1, 1, At, B1); PG8_BAR; PG8_SCHED;
;     ...
;         if constexpr (ALIGN_EPI) { if (wr == 0) PG8_BAR; }
	v_mfma_f32_16x16x32_bf16 v[98:101], v[174:177], v[206:209], v[98:101]
	v_mfma_f32_16x16x32_bf16 v[94:97], v[182:185], v[206:209], v[94:97]
	v_mfma_f32_16x16x32_bf16 v[82:85], v[174:177], v[214:217], v[82:85]
	v_mfma_f32_16x16x32_bf16 v[78:81], v[182:185], v[214:217], v[78:81]
	s_setprio 0
	s_add_u32 s8, s38, 0x80
	s_addc_u32 s9, s39, 0
	s_add_i32 s40, s62, s27
	s_mov_b32 m0, s40
	ds_read_b128 v[186:189], v173 offset:49152
	ds_read_b128 v[190:193], v173 offset:50176
	ds_read_b128 v[194:197], v173 offset:51200
	ds_read_b128 v[198:201], v173 offset:52224
	ds_read_b128 v[202:205], v173 offset:53248
	ds_read_b128 v[206:209], v173 offset:54272
	ds_read_b128 v[210:213], v173 offset:55296
	ds_read_b128 v[214:217], v173 offset:56320
	s_nop 0
	global_load_lds_dwordx4 v219, s[8:9]
	s_add_i32 m0, s40, 0x2000
	s_nop 0
	global_load_lds_dwordx4 v221, s[8:9]
	s_add_u32 s8, s38, 0x40080
	s_addc_u32 s9, s39, 0
	s_add_i32 s38, s63, s27
	s_mov_b32 m0, s38
	s_nop 0
	global_load_lds_dwordx4 v219, s[8:9]
	s_add_i32 m0, s38, 0x2000
	s_nop 0
	global_load_lds_dwordx4 v221, s[8:9]
	s_mov_b32 m0, s50
	s_nop 0
	global_load_lds_dwordx4 v218, s[36:37]
	s_mov_b32 m0, s51
	s_nop 0
	global_load_lds_dwordx4 v220, s[36:37]
	s_waitcnt vmcnt(8)
	s_waitcnt lgkmcnt(0)
	s_barrier
	s_setprio 1
	s_waitcnt lgkmcnt(0)
	v_mfma_f32_16x16x32_bf16 v[74:77], v[142:145], v[186:189], v[74:77]
	v_mfma_f32_16x16x32_bf16 v[70:73], v[150:153], v[186:189], v[70:73]
	v_mfma_f32_16x16x32_bf16 v[58:61], v[142:145], v[194:197], v[58:61]
	v_mfma_f32_16x16x32_bf16 v[54:57], v[150:153], v[194:197], v[54:57]
	v_mfma_f32_16x16x32_bf16 v[42:45], v[142:145], v[202:205], v[42:45]
	v_mfma_f32_16x16x32_bf16 v[38:41], v[150:153], v[202:205], v[38:41]
	v_mfma_f32_16x16x32_bf16 v[26:29], v[142:145], v[210:213], v[26:29]
	v_mfma_f32_16x16x32_bf16 v[22:25], v[150:153], v[210:213], v[22:25]
	v_mfma_f32_16x16x32_bf16 v[74:77], v[146:149], v[190:193], v[74:77]
	v_mfma_f32_16x16x32_bf16 v[70:73], v[154:157], v[190:193], v[70:73]
	v_mfma_f32_16x16x32_bf16 v[58:61], v[146:149], v[198:201], v[58:61]
	v_mfma_f32_16x16x32_bf16 v[54:57], v[154:157], v[198:201], v[54:57]
	v_mfma_f32_16x16x32_bf16 v[42:45], v[146:149], v[206:209], v[42:45]
	v_mfma_f32_16x16x32_bf16 v[38:41], v[154:157], v[206:209], v[38:41]
	v_mfma_f32_16x16x32_bf16 v[26:29], v[146:149], v[214:217], v[26:29]
	v_mfma_f32_16x16x32_bf16 v[22:25], v[154:157], v[214:217], v[22:25]
	s_setprio 0
	s_setprio 1
	v_mfma_f32_16x16x32_bf16 v[66:69], v[164:167], v[186:189], v[66:69]
	v_mfma_f32_16x16x32_bf16 v[62:65], v[178:181], v[186:189], v[62:65]
	v_mfma_f32_16x16x32_bf16 v[50:53], v[164:167], v[194:197], v[50:53]
	v_mfma_f32_16x16x32_bf16 v[46:49], v[178:181], v[194:197], v[46:49]
	v_mfma_f32_16x16x32_bf16 v[34:37], v[164:167], v[202:205], v[34:37]
	v_mfma_f32_16x16x32_bf16 v[30:33], v[178:181], v[202:205], v[30:33]
	v_mfma_f32_16x16x32_bf16 v[18:21], v[164:167], v[210:213], v[18:21]
	v_mfma_f32_16x16x32_bf16 v[14:17], v[178:181], v[210:213], v[14:17]
	v_mfma_f32_16x16x32_bf16 v[66:69], v[174:177], v[190:193], v[66:69]
	v_mfma_f32_16x16x32_bf16 v[62:65], v[182:185], v[190:193], v[62:65]
	v_mfma_f32_16x16x32_bf16 v[50:53], v[174:177], v[198:201], v[50:53]
	v_mfma_f32_16x16x32_bf16 v[46:49], v[182:185], v[198:201], v[46:49]
	s_setprio 2
	s_barrier
	v_mfma_f32_16x16x32_bf16 v[34:37], v[174:177], v[206:209], v[34:37]
	v_mfma_f32_16x16x32_bf16 v[30:33], v[182:185], v[206:209], v[30:33]
	v_mfma_f32_16x16x32_bf16 v[18:21], v[174:177], v[214:217], v[18:21]
	v_mfma_f32_16x16x32_bf16 v[14:17], v[182:185], v[214:217], v[14:17]
	s_setprio 0
	s_add_i32 s61, s61, 2
	s_add_u32 s59, s59, 0x100
	s_addc_u32 s60, s60, 0
	s_cmp_gt_u32 s61, 13
	s_mov_b64 s[8:9], s[34:35]
	s_cbranch_scc0 .LBB13_1074
	s_and_b64 vcc, exec, s[16:17]
	s_cbranch_vccz .LBB13_1077
	s_barrier

;     __device__ float mid(int row) const { return rg(row) / ra(row); }
;     __device__ __forceinline__ bool next(int i, Unit& u) const { return map(rank + i * nloc, u); }
; #define PG8_LDA(dst, b, h) do { _Pragma("unroll") for (int m = 0; m < 4; ++m) _Pragma("unroll") for (int k = 0; k < 2; ++k) dst[m][k] = *(const PG8_LAS bf16x8*)(lds + PG8_SA(b, h) + aoff + m * 2048 + k * 1024); } while (0)
; template <class Epi, class Sched, bool ALIGN_EPI = false, bool SP2 = false>
; __device__ __forceinline__ void gemm_phase(PG8_LAS unsigned char* lds, const Gemm g, const Sched& S, const Epi& E, int wid0) {
;     ...
;         const bool has_next = S.next(ui + 1, nxt); nxt.ui = ui + 1;
;         if constexpr (Epi::HAS_PRE) E.pre_finish(lds, cur, tid, pq0, pq1, pq2);
;         const char* nA = has_next ? (const char*)g.A + (size_t)nxt.pm * tstepA : cA; const char* nB = has_next ? (const char*)g.Bt + (size_t)nxt.pn * tstep : cB;
; #pragma nounroll
;         for (int t = 0; t < nt; t += 2) {
;             const bool last = (t == nt - 2);
;             const char* a1 = cA + (size_t)(t + 1) * kstep;
;             const char* a2 = last ? nA : cA + (size_t)(t + 2) * kstep; const char* b2 = last ? nB : cB + (size_t)(t + 2) * kstep;
;             const char* a3 = a2 + kstep; const char* b3 = b2 + kstep;
;             if (last && has_next) S.a_ready(nxt);
;             if constexpr (Epi::HAS_MID) { if (t == Epi::MID_T) E.mid(acc, cur, wr, fr); }
;             unsigned vA_[2] = {voffA[0], voffA[1]}, vB_[2] = {voffB[0], voffB[1]};
;             asm volatile("" : "+v"(vA_[0]), "+v"(vA_[1]), "+v"(vB_[0]), "+v"(vB_[1]));
;             if constexpr (SP2) {
;             PG8_LDB(B0, 0, 0); PG8_LDB(B1, 0, 1); PG8_SCHED; PG8_LDA(At, 0, 0); PG8_STAGE(PG8_SA(1, 1), a1 + hstepA, vA_);
;             PG8_WAIT_V(8); PG8_WAIT_L(0); PG8_BAR; PG8_MMA(0, 0, At, B0); PG8_MMA(0, 1, At, B1); PG8_BAR; PG8_SCHED;
;             PG8_LDA(At, 0, 1); PG8_STAGE(PG8_SB(0, 0), b2, vB_); PG8_STAGE(PG8_SB(0, 1), b2 + hstep, vB_); PG8_STAGE(PG8_SA(0, 0), a2, vA_);
;             PG8_WAIT_V(8); PG8_WAIT_L(0); PG8_BAR; PG8_MMA(1, 0, At, B0); PG8_MMA(1, 1, At, B1); PG8_BAR; PG8_SCHED;
;             PG8_LDB(B0, 1, 0); PG8_LDB(B1, 1, 1); PG8_SCHED; PG8_LDA(At, 1, 0); PG8_STAGE(PG8_SA(0, 1), a2 + hstepA, vA_);
;             PG8_WAIT_V(8); PG8_WAIT_L(0); PG8_BAR; PG8_MMA(0, 0, At, B0); PG8_MMA(0, 1, At, B1); PG8_BAR; PG8_SCHED;
.LBB13_1187:
	v_mov_b32_e32 v181, v162
	v_mov_b32_e32 v202, v156
	v_mov_b32_e32 v203, v158
	v_mov_b32_e32 v204, v160
	ds_read_b128 v[128:131], v161
	ds_read_b128 v[132:135], v161 offset:1024
	ds_read_b128 v[136:139], v161 offset:2048
	ds_read_b128 v[140:143], v161 offset:3072
	ds_read_b128 v[144:147], v163
	ds_read_b128 v[148:151], v163 offset:1024
	ds_read_b128 v[152:155], v163 offset:2048
	ds_read_b128 v[164:167], v163 offset:3072
	s_add_u32 s34, s30, 0x100
	s_addc_u32 s35, s31, 0
	s_cmp_eq_u32 s60, 60
	s_cselect_b32 s40, s27, s34
	s_cselect_b32 s41, s17, s35
	s_cselect_b32 s38, s57, s58
	s_cselect_b32 s39, s19, s59
	s_add_u32 s36, s40, 0x80
	s_addc_u32 s37, s41, 0
	s_add_u32 s30, s30, 0x100080
	s_addc_u32 s31, s31, 0
	s_add_i32 m0, s29, 0xc000
	ds_read_b128 v[168:171], v180
	ds_read_b128 v[172:175], v180 offset:1024
	ds_read_b128 v[176:179], v180 offset:2048
	ds_read_b128 v[182:185], v180 offset:3072
	ds_read_b128 v[186:189], v180 offset:4096
	ds_read_b128 v[190:193], v180 offset:5120
	ds_read_b128 v[194:197], v180 offset:6144
	ds_read_b128 v[198:201], v180 offset:7168
	s_nop 0
	global_load_lds_dwordx4 v202, s[30:31]
	s_add_i32 m0, s29, 0xe000
	s_nop 0
	global_load_lds_dwordx4 v204, s[30:31]
	s_waitcnt vmcnt(8)
	s_waitcnt lgkmcnt(0)
	s_barrier
	s_setprio 1
	s_waitcnt lgkmcnt(0)
	v_mfma_f32_16x16x32_bf16 v[124:127], v[128:131], v[168:171], v[124:127]
	v_mfma_f32_16x16x32_bf16 v[120:123], v[136:139], v[168:171], v[120:123]
	v_mfma_f32_16x16x32_bf16 v[116:119], v[128:131], v[176:179], v[116:119]
	v_mfma_f32_16x16x32_bf16 v[112:115], v[136:139], v[176:179], v[112:115]
	v_mfma_f32_16x16x32_bf16 v[108:111], v[128:131], v[186:189], v[108:111]
	v_mfma_f32_16x16x32_bf16 v[104:107], v[136:139], v[186:189], v[104:107]
	v_mfma_f32_16x16x32_bf16 v[100:103], v[128:131], v[194:197], v[100:103]
	v_mfma_f32_16x16x32_bf16 v[96:99], v[136:139], v[194:197], v[96:99]
	v_mfma_f32_16x16x32_bf16 v[124:127], v[132:135], v[172:175], v[124:127]
	v_mfma_f32_16x16x32_bf16 v[120:123], v[140:143], v[172:175], v[120:123]
	v_mfma_f32_16x16x32_bf16 v[116:119], v[132:135], v[182:185], v[116:119]
	v_mfma_f32_16x16x32_bf16 v[112:115], v[140:143], v[182:185], v[112:115]
	v_mfma_f32_16x16x32_bf16 v[108:111], v[132:135], v[190:193], v[108:111]
	v_mfma_f32_16x16x32_bf16 v[104:107], v[140:143], v[190:193], v[104:107]
	v_mfma_f32_16x16x32_bf16 v[100:103], v[132:135], v[198:201], v[100:103]
	v_mfma_f32_16x16x32_bf16 v[96:99], v[140:143], v[198:201], v[96:99]
	s_setprio 0
	s_setprio 1
	v_mfma_f32_16x16x32_bf16 v[60:63], v[144:147], v[168:171], v[60:63]
	v_mfma_f32_16x16x32_bf16 v[56:59], v[152:155], v[168:171], v[56:59]
	v_mfma_f32_16x16x32_bf16 v[52:55], v[144:147], v[176:179], v[52:55]
	v_mfma_f32_16x16x32_bf16 v[48:51], v[152:155], v[176:179], v[48:51]
	v_mfma_f32_16x16x32_bf16 v[44:47], v[144:147], v[186:189], v[44:47]
	v_mfma_f32_16x16x32_bf16 v[40:43], v[152:155], v[186:189], v[40:43]
	v_mfma_f32_16x16x32_bf16 v[36:39], v[144:147], v[194:197], v[36:39]
	v_mfma_f32_16x16x32_bf16 v[32:35], v[152:155], v[194:197], v[32:35]
	v_mfma_f32_16x16x32_bf16 v[60:63], v[148:151], v[172:175], v[60:63]
	v_mfma_f32_16x16x32_bf16 v[56:59], v[164:167], v[172:175], v[56:59]
	v_mfma_f32_16x16x32_bf16 v[52:55], v[148:151], v[182:185], v[52:55]
	v_mfma_f32_16x16x32_bf16 v[48:51], v[164:167], v[182:185], v[48:51]
	s_setprio 2
	s_barrier
	v_mfma_f32_16x16x32_bf16 v[44:47], v[148:151], v[190:193], v[44:47]
	v_mfma_f32_16x16x32_bf16 v[40:43], v[164:167], v[190:193], v[40:43]
	v_mfma_f32_16x16x32_bf16 v[36:39], v[148:151], v[198:201], v[36:39]
	v_mfma_f32_16x16x32_bf16 v[32:35], v[164:167], v[198:201], v[32:35]
	s_setprio 0
	s_add_i32 s61, s55, s33
	s_mov_b64 s[30:31], s[38:39]
	s_mov_b32 m0, s61
	ds_read_b128 v[168:171], v180 offset:16384
	ds_read_b128 v[172:175], v180 offset:17408
	ds_read_b128 v[176:179], v180 offset:18432
	ds_read_b128 v[182:185], v180 offset:19456
	ds_read_b128 v[186:189], v180 offset:20480
	ds_read_b128 v[190:193], v180 offset:21504
	ds_read_b128 v[194:197], v180 offset:22528
	ds_read_b128 v[198:201], v180 offset:23552
	s_nop 0
	global_load_lds_dwordx4 v203, s[30:31]
	s_add_i32 m0, s61, 0x2000
	s_nop 0
	global_load_lds_dwordx4 v181, s[30:31]
	s_add_u32 s30, s38, 0x100000
	s_addc_u32 s31, s39, 0
	s_add_i32 s61, s56, s33
	s_mov_b32 m0, s61
	s_nop 0
	global_load_lds_dwordx4 v203, s[30:31]
	s_add_i32 m0, s61, 0x2000
	s_nop 0
	global_load_lds_dwordx4 v181, s[30:31]
	s_mov_b64 s[30:31], s[40:41]
	s_mov_b32 m0, s29
	s_nop 0
	global_load_lds_dwordx4 v202, s[30:31]
	s_mov_b32 m0, s46
	s_nop 0
	global_load_lds_dwordx4 v204, s[30:31]
	s_waitcnt vmcnt(8)
	s_waitcnt lgkmcnt(0)
	s_barrier
	s_setprio 1
	s_waitcnt lgkmcnt(0)
	v_mfma_f32_16x16x32_bf16 v[92:95], v[128:131], v[168:171], v[92:95]
	v_mfma_f32_16x16x32_bf16 v[88:91], v[136:139], v[168:171], v[88:91]
	v_mfma_f32_16x16x32_bf16 v[84:87], v[128:131], v[176:179], v[84:87]
	v_mfma_f32_16x16x32_bf16 v[80:83], v[136:139], v[176:179], v[80:83]
	v_mfma_f32_16x16x32_bf16 v[76:79], v[128:131], v[186:189], v[76:79]
	v_mfma_f32_16x16x32_bf16 v[72:75], v[136:139], v[186:189], v[72:75]
	v_mfma_f32_16x16x32_bf16 v[68:71], v[128:131], v[194:197], v[68:71]
	v_mfma_f32_16x16x32_bf16 v[64:67], v[136:139], v[194:197], v[64:67]
	v_mfma_f32_16x16x32_bf16 v[92:95], v[132:135], v[172:175], v[92:95]
	v_mfma_f32_16x16x32_bf16 v[88:91], v[140:143], v[172:175], v[88:91]
	v_mfma_f32_16x16x32_bf16 v[84:87], v[132:135], v[182:185], v[84:87]
	v_mfma_f32_16x16x32_bf16 v[80:83], v[140:143], v[182:185], v[80:83]
	v_mfma_f32_16x16x32_bf16 v[76:79], v[132:135], v[190:193], v[76:79]
	v_mfma_f32_16x16x32_bf16 v[72:75], v[140:143], v[190:193], v[72:75]
	v_mfma_f32_16x16x32_bf16 v[68:71], v[132:135], v[198:201], v[68:71]
	v_mfma_f32_16x16x32_bf16 v[64:67], v[140:143], v[198:201], v[64:67]
	s_setprio 0
	s_setprio 1
	v_mfma_f32_16x16x32_bf16 v[28:31], v[144:147], v[168:171], v[28:31]
	v_mfma_f32_16x16x32_bf16 v[24:27], v[152:155], v[168:171], v[24:27]
	v_mfma_f32_16x16x32_bf16 v[20:23], v[144:147], v[176:179], v[20:23]
	v_mfma_f32_16x16x32_bf16 v[16:19], v[152:155], v[176:179], v[16:19]
	v_mfma_f32_16x16x32_bf16 v[12:15], v[144:147], v[186:189], v[12:15]
	v_mfma_f32_16x16x32_bf16 v[8:11], v[152:155], v[186:189], v[8:11]
	v_mfma_f32_16x16x32_bf16 v[4:7], v[144:147], v[194:197], v[4:7]
	v_mfma_f32_16x16x32_bf16 v[0:3], v[152:155], v[194:197], v[0:3]
	v_mfma_f32_16x16x32_bf16 v[28:31], v[148:151], v[172:175], v[28:31]
	v_mfma_f32_16x16x32_bf16 v[24:27], v[164:167], v[172:175], v[24:27]
	v_mfma_f32_16x16x32_bf16 v[20:23], v[148:151], v[182:185], v[20:23]
	v_mfma_f32_16x16x32_bf16 v[16:19], v[164:167], v[182:185], v[16:19]
	s_setprio 2
	s_barrier
; #define PG8_STAGE(bufoff, gbase, voff) do { const char* gb_ = (const char*)(gbase); asm volatile("" : "+s"(gb_));     \
;         _Pragma("unroll") for (int _i = 0; _i < 2; ++_i) \
;         __builtin_amdgcn_global_load_lds((const unsigned*)(gb_ + (voff)[_i]), (PG8_LAS unsigned*)(lds + (bufoff) + ldsw + _i * 8192), 16, 0, 0); } while (0)
; #define PG8_LDA(dst, b, h) do { _Pragma("unroll") for (int m = 0; m < 4; ++m) _Pragma("unroll") for (int k = 0; k < 2; ++k) dst[m][k] = *(const PG8_LAS bf16x8*)(lds + PG8_SA(b, h) + aoff + m * 2048 + k * 1024); } while (0)
; #define PG8_LDB(dst, b, h) do { _Pragma("unroll") for (int n = 0; n < 2; ++n) _Pragma("unroll") for (int k = 0; k < 2; ++k) dst[n][k] = *(const PG8_LAS bf16x8*)(lds + PG8_SB(b, h) + boff + n * 2048 + k * 1024); } while (0)
; #define PG8_MMA(ai, bj, At, Bt) do { __builtin_amdgcn_s_setprio(1); _Pragma("unroll") for (int m = 0; m < 4; ++m) _Pragma("unroll") for (int n = 0; n < 2; ++n) _Pragma("unroll") for (int k = 0; k < 2; ++k) \
;         acc[ai][bj][m][n] = __builtin_amdgcn_mfma_f32_16x16x32_bf16(Bt[n][k], At[m][k], acc[ai][bj][m][n], 0, 0, 0); __builtin_amdgcn_s_setprio(0); } while (0)
; #define PG8_WAIT_V(n) asm volatile("s_waitcnt vmcnt(" #n ")" ::: "memory")
; #define PG8_WAIT_L(n) asm volatile("s_waitcnt lgkmcnt(" #n ")" ::: "memory")
; #define PG8_BAR __builtin_amdgcn_s_barrier()
; #define PG8_SCHED __builtin_amdgcn_sched_barrier(0)
; template <class Epi, class Sched, bool ALIGN_EPI = false, bool SP2 = false>
; __device__ __forceinline__ void gemm_phase(PG8_LAS unsigned char* lds, const Gemm g, const Sched& S, const Epi& E, int wid0) {
;     ...
;             PG8_WAIT_V(8); PG8_WAIT_L(0); PG8_BAR; PG8_MMA(0, 0, At, B0); PG8_MMA(0, 1, At, B1); PG8_BAR; PG8_SCHED;
;             PG8_LDA(At, 0, 1); PG8_STAGE(PG8_SB(0, 0), b2, vB_); PG8_STAGE(PG8_SB(0, 1), b2 + hstep, vB_); PG8_STAGE(PG8_SA(0, 0), a2, vA_);
;             PG8_WAIT_V(8); PG8_WAIT_L(0); PG8_BAR; PG8_MMA(1, 0, At, B0); PG8_MMA(1, 1, At, B1); PG8_BAR; PG8_SCHED;
;             PG8_LDB(B0, 1, 0); PG8_LDB(B1, 1, 1); PG8_SCHED; PG8_LDA(At, 1, 0); PG8_STAGE(PG8_SA(0, 1), a2 + hstepA, vA_);
;             PG8_WAIT_V(8); PG8_WAIT_L(0); PG8_BAR; PG8_MMA(0, 0, At, B0); PG8_MMA(0, 1, At, B1); PG8_BAR; PG8_SCHED;
	v_mfma_f32_16x16x32_bf16 v[12:15], v[148:151], v[190:193], v[12:15]
	v_mfma_f32_16x16x32_bf16 v[8:11], v[164:167], v[190:193], v[8:11]
	v_mfma_f32_16x16x32_bf16 v[4:7], v[148:151], v[198:201], v[4:7]
	v_mfma_f32_16x16x32_bf16 v[0:3], v[164:167], v[198:201], v[0:3]
	s_setprio 0
	s_add_i32 s61, 0, 0x18000
	s_add_i32 s62, 0, 0x1c000
	v_add_u32_e32 v140, s61, v157
	v_add_u32_e32 v164, s62, v157
	ds_read_b128 v[128:131], v140
	ds_read_b128 v[132:135], v140 offset:1024
	ds_read_b128 v[136:139], v140 offset:2048
	ds_read_b128 v[140:143], v140 offset:3072
	ds_read_b128 v[144:147], v164
	ds_read_b128 v[148:151], v164 offset:1024
	ds_read_b128 v[152:155], v164 offset:2048
	ds_read_b128 v[164:167], v164 offset:3072
	s_add_u32 s30, s40, 0x100000
	s_addc_u32 s31, s41, 0
	s_mov_b32 m0, s47
	ds_read_b128 v[168:171], v180 offset:32768
	ds_read_b128 v[172:175], v180 offset:33792
	ds_read_b128 v[176:179], v180 offset:34816
	ds_read_b128 v[182:185], v180 offset:35840
	ds_read_b128 v[186:189], v180 offset:36864
	ds_read_b128 v[190:193], v180 offset:37888
	ds_read_b128 v[194:197], v180 offset:38912
	ds_read_b128 v[198:201], v180 offset:39936
	s_nop 0
	global_load_lds_dwordx4 v202, s[30:31]
	s_mov_b32 m0, s48
	s_nop 0
	global_load_lds_dwordx4 v204, s[30:31]
	s_waitcnt vmcnt(8)
	s_waitcnt lgkmcnt(0)
	s_barrier
	s_setprio 1
	s_waitcnt lgkmcnt(0)
	v_mfma_f32_16x16x32_bf16 v[124:127], v[128:131], v[168:171], v[124:127]
	v_mfma_f32_16x16x32_bf16 v[120:123], v[136:139], v[168:171], v[120:123]
	v_mfma_f32_16x16x32_bf16 v[116:119], v[128:131], v[176:179], v[116:119]
	v_mfma_f32_16x16x32_bf16 v[112:115], v[136:139], v[176:179], v[112:115]
	v_mfma_f32_16x16x32_bf16 v[108:111], v[128:131], v[186:189], v[108:111]
	v_mfma_f32_16x16x32_bf16 v[104:107], v[136:139], v[186:189], v[104:107]
	v_mfma_f32_16x16x32_bf16 v[100:103], v[128:131], v[194:197], v[100:103]
	v_mfma_f32_16x16x32_bf16 v[96:99], v[136:139], v[194:197], v[96:99]
	v_mfma_f32_16x16x32_bf16 v[124:127], v[132:135], v[172:175], v[124:127]
	v_mfma_f32_16x16x32_bf16 v[120:123], v[140:143], v[172:175], v[120:123]
	v_mfma_f32_16x16x32_bf16 v[116:119], v[132:135], v[182:185], v[116:119]
	v_mfma_f32_16x16x32_bf16 v[112:115], v[140:143], v[182:185], v[112:115]
	v_mfma_f32_16x16x32_bf16 v[108:111], v[132:135], v[190:193], v[108:111]
	v_mfma_f32_16x16x32_bf16 v[104:107], v[140:143], v[190:193], v[104:107]
	v_mfma_f32_16x16x32_bf16 v[100:103], v[132:135], v[198:201], v[100:103]
	v_mfma_f32_16x16x32_bf16 v[96:99], v[140:143], v[198:201], v[96:99]
	s_setprio 0
	s_setprio 1
	v_mfma_f32_16x16x32_bf16 v[60:63], v[144:147], v[168:171], v[60:63]
	v_mfma_f32_16x16x32_bf16 v[56:59], v[152:155], v[168:171], v[56:59]
	v_mfma_f32_16x16x32_bf16 v[52:55], v[144:147], v[176:179], v[52:55]
	v_mfma_f32_16x16x32_bf16 v[48:51], v[152:155], v[176:179], v[48:51]
	v_mfma_f32_16x16x32_bf16 v[44:47], v[144:147], v[186:189], v[44:47]
	v_mfma_f32_16x16x32_bf16 v[40:43], v[152:155], v[186:189], v[40:43]
	v_mfma_f32_16x16x32_bf16 v[36:39], v[144:147], v[194:197], v[36:39]
	v_mfma_f32_16x16x32_bf16 v[32:35], v[152:155], v[194:197], v[32:35]
	v_mfma_f32_16x16x32_bf16 v[60:63], v[148:151], v[172:175], v[60:63]
	v_mfma_f32_16x16x32_bf16 v[56:59], v[164:167], v[172:175], v[56:59]
	v_mfma_f32_16x16x32_bf16 v[52:55], v[148:151], v[182:185], v[52:55]
	v_mfma_f32_16x16x32_bf16 v[48:51], v[164:167], v[182:185], v[48:51]
	s_setprio 2
	s_barrier
; #define PG8_STAGE(bufoff, gbase, voff) do { const char* gb_ = (const char*)(gbase); asm volatile("" : "+s"(gb_));     \
;         _Pragma("unroll") for (int _i = 0; _i < 2; ++_i) \
;         __builtin_amdgcn_global_load_lds((const unsigned*)(gb_ + (voff)[_i]), (PG8_LAS unsigned*)(lds + (bufoff) + ldsw + _i * 8192), 16, 0, 0); } while (0)
; #define PG8_LDA(dst, b, h) do { _Pragma("unroll") for (int m = 0; m < 4; ++m) _Pragma("unroll") for (int k = 0; k < 2; ++k) dst[m][k] = *(const PG8_LAS bf16x8*)(lds + PG8_SA(b, h) + aoff + m * 2048 + k * 1024); } while (0)
; #define PG8_MMA(ai, bj, At, Bt) do { __builtin_amdgcn_s_setprio(1); _Pragma("unroll") for (int m = 0; m < 4; ++m) _Pragma("unroll") for (int n = 0; n < 2; ++n) _Pragma("unroll") for (int k = 0; k < 2; ++k) \
;         acc[ai][bj][m][n] = __builtin_amdgcn_mfma_f32_16x16x32_bf16(Bt[n][k], At[m][k], acc[ai][bj][m][n], 0, 0, 0); __builtin_amdgcn_s_setprio(0); } while (0)
; #define PG8_WAIT_V(n) asm volatile("s_waitcnt vmcnt(" #n ")" ::: "memory")
; #define PG8_WAIT_L(n) asm volatile("s_waitcnt lgkmcnt(" #n ")" ::: "memory")
; #define PG8_BAR __builtin_amdgcn_s_barrier()
; #define PG8_SCHED __builtin_amdgcn_sched_barrier(0)
; template <class Epi, class Sched, bool ALIGN_EPI = false, bool SP2 = false>
; __device__ __forceinline__ void gemm_phase(PG8_LAS unsigned char* lds, const Gemm g, const Sched& S, const Epi& E, int wid0) {
;     ...
;             PG8_WAIT_V(8); PG8_WAIT_L(0); PG8_BAR; PG8_MMA(0, 0, At, B0); PG8_MMA(0, 1, At, B1); PG8_BAR; PG8_SCHED;
;             PG8_LDA(At, 1, 1); PG8_STAGE(PG8_SB(1, 0), b3, vB_); PG8_STAGE(PG8_SB(1, 1), b3 + hstep, vB_); PG8_STAGE(PG8_SA(1, 0), a3, vA_);
;             PG8_WAIT_V(8); PG8_WAIT_L(0); PG8_BAR; PG8_MMA(1, 0, At, B0); PG8_MMA(1, 1, At, B1); PG8_BAR; PG8_SCHED;
;     ...
;         if constexpr (ALIGN_EPI) { if (wr == 0) PG8_BAR; }
	v_mfma_f32_16x16x32_bf16 v[44:47], v[148:151], v[190:193], v[44:47]
	v_mfma_f32_16x16x32_bf16 v[40:43], v[164:167], v[190:193], v[40:43]
	v_mfma_f32_16x16x32_bf16 v[36:39], v[148:151], v[198:201], v[36:39]
	v_mfma_f32_16x16x32_bf16 v[32:35], v[164:167], v[198:201], v[32:35]
	s_setprio 0
	s_add_u32 s30, s38, 0x80
	s_addc_u32 s31, s39, 0
	s_add_i32 s40, s61, s33
	s_mov_b32 m0, s40
	ds_read_b128 v[168:171], v180 offset:49152
	ds_read_b128 v[172:175], v180 offset:50176
	ds_read_b128 v[176:179], v180 offset:51200
	ds_read_b128 v[182:185], v180 offset:52224
	ds_read_b128 v[186:189], v180 offset:53248
	ds_read_b128 v[190:193], v180 offset:54272
	ds_read_b128 v[194:197], v180 offset:55296
	ds_read_b128 v[198:201], v180 offset:56320
	s_nop 0
	global_load_lds_dwordx4 v203, s[30:31]
	s_add_i32 m0, s40, 0x2000
	s_nop 0
	global_load_lds_dwordx4 v181, s[30:31]
	s_add_u32 s30, s38, 0x100080
	s_addc_u32 s31, s39, 0
	s_add_i32 s38, s62, s33
	s_mov_b32 m0, s38
	s_nop 0
	global_load_lds_dwordx4 v203, s[30:31]
	s_add_i32 m0, s38, 0x2000
	s_nop 0
	global_load_lds_dwordx4 v181, s[30:31]
	s_mov_b32 m0, s53
	s_nop 0
	global_load_lds_dwordx4 v202, s[36:37]
	s_mov_b32 m0, s54
	s_nop 0
	global_load_lds_dwordx4 v204, s[36:37]
	s_waitcnt vmcnt(8)
	s_waitcnt lgkmcnt(0)
	s_barrier
	s_setprio 1
	s_waitcnt lgkmcnt(0)
	v_mfma_f32_16x16x32_bf16 v[92:95], v[128:131], v[168:171], v[92:95]
	v_mfma_f32_16x16x32_bf16 v[88:91], v[136:139], v[168:171], v[88:91]
	v_mfma_f32_16x16x32_bf16 v[84:87], v[128:131], v[176:179], v[84:87]
	v_mfma_f32_16x16x32_bf16 v[80:83], v[136:139], v[176:179], v[80:83]
	v_mfma_f32_16x16x32_bf16 v[76:79], v[128:131], v[186:189], v[76:79]
	v_mfma_f32_16x16x32_bf16 v[72:75], v[136:139], v[186:189], v[72:75]
	v_mfma_f32_16x16x32_bf16 v[68:71], v[128:131], v[194:197], v[68:71]
	v_mfma_f32_16x16x32_bf16 v[64:67], v[136:139], v[194:197], v[64:67]
	v_mfma_f32_16x16x32_bf16 v[92:95], v[132:135], v[172:175], v[92:95]
	v_mfma_f32_16x16x32_bf16 v[88:91], v[140:143], v[172:175], v[88:91]
	v_mfma_f32_16x16x32_bf16 v[84:87], v[132:135], v[182:185], v[84:87]
	v_mfma_f32_16x16x32_bf16 v[80:83], v[140:143], v[182:185], v[80:83]
	v_mfma_f32_16x16x32_bf16 v[76:79], v[132:135], v[190:193], v[76:79]
	v_mfma_f32_16x16x32_bf16 v[72:75], v[140:143], v[190:193], v[72:75]
	v_mfma_f32_16x16x32_bf16 v[68:71], v[132:135], v[198:201], v[68:71]
	v_mfma_f32_16x16x32_bf16 v[64:67], v[140:143], v[198:201], v[64:67]
	s_setprio 0
	s_setprio 1
	v_mfma_f32_16x16x32_bf16 v[28:31], v[144:147], v[168:171], v[28:31]
	v_mfma_f32_16x16x32_bf16 v[24:27], v[152:155], v[168:171], v[24:27]
	v_mfma_f32_16x16x32_bf16 v[20:23], v[144:147], v[176:179], v[20:23]
	v_mfma_f32_16x16x32_bf16 v[16:19], v[152:155], v[176:179], v[16:19]
	v_mfma_f32_16x16x32_bf16 v[12:15], v[144:147], v[186:189], v[12:15]
	v_mfma_f32_16x16x32_bf16 v[8:11], v[152:155], v[186:189], v[8:11]
	v_mfma_f32_16x16x32_bf16 v[4:7], v[144:147], v[194:197], v[4:7]
	v_mfma_f32_16x16x32_bf16 v[0:3], v[152:155], v[194:197], v[0:3]
	v_mfma_f32_16x16x32_bf16 v[28:31], v[148:151], v[172:175], v[28:31]
	v_mfma_f32_16x16x32_bf16 v[24:27], v[164:167], v[172:175], v[24:27]
	v_mfma_f32_16x16x32_bf16 v[20:23], v[148:151], v[182:185], v[20:23]
	v_mfma_f32_16x16x32_bf16 v[16:19], v[164:167], v[182:185], v[16:19]
	s_setprio 2
	s_barrier
	v_mfma_f32_16x16x32_bf16 v[12:15], v[148:151], v[190:193], v[12:15]
	v_mfma_f32_16x16x32_bf16 v[8:11], v[164:167], v[190:193], v[8:11]
	v_mfma_f32_16x16x32_bf16 v[4:7], v[148:151], v[198:201], v[4:7]
	v_mfma_f32_16x16x32_bf16 v[0:3], v[164:167], v[198:201], v[0:3]
	s_setprio 0
	s_add_i32 s60, s60, 2
	s_add_u32 s58, s58, 0x100
	s_addc_u32 s59, s59, 0
	s_cmp_gt_u32 s60, 61
	s_mov_b64 s[30:31], s[34:35]
	s_cbranch_scc0 .LBB13_1187
	s_and_b64 vcc, exec, s[14:15]
	s_cbranch_vccz .LBB13_1190
	s_barrier

;     __device__ float mid(int row) const { return rg(row) / ra(row); }
;     __device__ __forceinline__ bool next(int i, Unit& u) const { return map(rank + i * nloc, u); }
; #define PG8_LDA(dst, b, h) do { _Pragma("unroll") for (int m = 0; m < 4; ++m) _Pragma("unroll") for (int k = 0; k < 2; ++k) dst[m][k] = *(const PG8_LAS bf16x8*)(lds + PG8_SA(b, h) + aoff + m * 2048 + k * 1024); } while (0)
; template <class Epi, class Sched, bool ALIGN_EPI = false, bool SP2 = false>
; __device__ __forceinline__ void gemm_phase(PG8_LAS unsigned char* lds, const Gemm g, const Sched& S, const Epi& E, int wid0) {
;     ...
;         const bool has_next = S.next(ui + 1, nxt); nxt.ui = ui + 1;
;         if constexpr (Epi::HAS_PRE) E.pre_finish(lds, cur, tid, pq0, pq1, pq2);
;         const char* nA = has_next ? (const char*)g.A + (size_t)nxt.pm * tstepA : cA; const char* nB = has_next ? (const char*)g.Bt + (size_t)nxt.pn * tstep : cB;
; #pragma nounroll
;         for (int t = 0; t < nt; t += 2) {
;             const bool last = (t == nt - 2);
;             const char* a1 = cA + (size_t)(t + 1) * kstep;
;             const char* a2 = last ? nA : cA + (size_t)(t + 2) * kstep; const char* b2 = last ? nB : cB + (size_t)(t + 2) * kstep;
;             const char* a3 = a2 + kstep; const char* b3 = b2 + kstep;
;             if (last && has_next) S.a_ready(nxt);
;             if constexpr (Epi::HAS_MID) { if (t == Epi::MID_T) E.mid(acc, cur, wr, fr); }
;             unsigned vA_[2] = {voffA[0], voffA[1]}, vB_[2] = {voffB[0], voffB[1]};
;             asm volatile("" : "+v"(vA_[0]), "+v"(vA_[1]), "+v"(vB_[0]), "+v"(vB_[1]));
;             if constexpr (SP2) {
;             PG8_LDB(B0, 0, 0); PG8_LDB(B1, 0, 1); PG8_SCHED; PG8_LDA(At, 0, 0); PG8_STAGE(PG8_SA(1, 1), a1 + hstepA, vA_);
;             PG8_WAIT_V(8); PG8_WAIT_L(0); PG8_BAR; PG8_MMA(0, 0, At, B0); PG8_MMA(0, 1, At, B1); PG8_BAR; PG8_SCHED;
;             PG8_LDA(At, 0, 1); PG8_STAGE(PG8_SB(0, 0), b2, vB_); PG8_STAGE(PG8_SB(0, 1), b2 + hstep, vB_); PG8_STAGE(PG8_SA(0, 0), a2, vA_);
;             PG8_WAIT_V(8); PG8_WAIT_L(0); PG8_BAR; PG8_MMA(1, 0, At, B0); PG8_MMA(1, 1, At, B1); PG8_BAR; PG8_SCHED;
;             PG8_LDB(B0, 1, 0); PG8_LDB(B1, 1, 1); PG8_SCHED; PG8_LDA(At, 1, 0); PG8_STAGE(PG8_SA(0, 1), a2 + hstepA, vA_);
;             PG8_WAIT_V(8); PG8_WAIT_L(0); PG8_BAR; PG8_MMA(0, 0, At, B0); PG8_MMA(0, 1, At, B1); PG8_BAR; PG8_SCHED;
.LBB13_1336:
	v_mov_b32_e32 v8, v178
	v_mov_b32_e32 v220, v174
	v_mov_b32_e32 v221, v200
	v_mov_b32_e32 v222, v176
	ds_read_b128 v[82:85], v201
	ds_read_b128 v[90:93], v201 offset:1024
	ds_read_b128 v[94:97], v201 offset:2048
	ds_read_b128 v[102:105], v201 offset:3072
	ds_read_b128 v[158:161], v202
	ds_read_b128 v[162:165], v202 offset:1024
	ds_read_b128 v[166:169], v202 offset:2048
	ds_read_b128 v[170:173], v202 offset:3072
	s_add_u32 s8, s2, 0x100
	s_addc_u32 s9, s3, 0
	s_cmp_eq_u32 s82, 12
	s_cselect_b32 s58, s78, s8
	s_cselect_b32 s59, s47, s9
	s_cselect_b32 s12, s79, s80
	s_cselect_b32 s13, s49, s81
	s_add_u32 s10, s58, 0x80
	s_addc_u32 s11, s59, 0
	s_add_u32 s2, s2, 0x40080
	s_addc_u32 s3, s3, 0
	s_add_i32 m0, s57, 0xc000
	ds_read_b128 v[180:183], v203
	ds_read_b128 v[184:187], v203 offset:1024
	ds_read_b128 v[188:191], v203 offset:2048
	ds_read_b128 v[192:195], v203 offset:3072
	ds_read_b128 v[204:207], v203 offset:4096
	ds_read_b128 v[208:211], v203 offset:5120
	ds_read_b128 v[212:215], v203 offset:6144
	ds_read_b128 v[216:219], v203 offset:7168
	s_nop 0
	global_load_lds_dwordx4 v220, s[2:3]
	s_add_i32 m0, s57, 0xe000
	s_nop 0
	global_load_lds_dwordx4 v222, s[2:3]
	s_waitcnt vmcnt(8)
	s_waitcnt lgkmcnt(0)
	s_barrier
	s_setprio 1
	s_waitcnt lgkmcnt(0)
	v_mfma_f32_16x16x32_bf16 v[154:157], v[82:85], v[180:183], v[154:157]
	v_mfma_f32_16x16x32_bf16 v[150:153], v[94:97], v[180:183], v[150:153]
	v_mfma_f32_16x16x32_bf16 v[138:141], v[82:85], v[188:191], v[138:141]
	v_mfma_f32_16x16x32_bf16 v[134:137], v[94:97], v[188:191], v[134:137]
	v_mfma_f32_16x16x32_bf16 v[122:125], v[82:85], v[204:207], v[122:125]
	v_mfma_f32_16x16x32_bf16 v[118:121], v[94:97], v[204:207], v[118:121]
	v_mfma_f32_16x16x32_bf16 v[106:109], v[82:85], v[212:215], v[106:109]
	v_mfma_f32_16x16x32_bf16 v[98:101], v[94:97], v[212:215], v[98:101]
	v_mfma_f32_16x16x32_bf16 v[154:157], v[90:93], v[184:187], v[154:157]
	v_mfma_f32_16x16x32_bf16 v[150:153], v[102:105], v[184:187], v[150:153]
	v_mfma_f32_16x16x32_bf16 v[138:141], v[90:93], v[192:195], v[138:141]
	v_mfma_f32_16x16x32_bf16 v[134:137], v[102:105], v[192:195], v[134:137]
	v_mfma_f32_16x16x32_bf16 v[122:125], v[90:93], v[208:211], v[122:125]
	v_mfma_f32_16x16x32_bf16 v[118:121], v[102:105], v[208:211], v[118:121]
	v_mfma_f32_16x16x32_bf16 v[106:109], v[90:93], v[216:219], v[106:109]
	v_mfma_f32_16x16x32_bf16 v[98:101], v[102:105], v[216:219], v[98:101]
	s_setprio 0
	s_setprio 1
	v_mfma_f32_16x16x32_bf16 v[146:149], v[158:161], v[180:183], v[146:149]
	v_mfma_f32_16x16x32_bf16 v[142:145], v[166:169], v[180:183], v[142:145]
	v_mfma_f32_16x16x32_bf16 v[130:133], v[158:161], v[188:191], v[130:133]
	v_mfma_f32_16x16x32_bf16 v[126:129], v[166:169], v[188:191], v[126:129]
	v_mfma_f32_16x16x32_bf16 v[114:117], v[158:161], v[204:207], v[114:117]
	v_mfma_f32_16x16x32_bf16 v[110:113], v[166:169], v[204:207], v[110:113]
	v_mfma_f32_16x16x32_bf16 v[86:89], v[158:161], v[212:215], v[86:89]
	v_mfma_f32_16x16x32_bf16 v[78:81], v[166:169], v[212:215], v[78:81]
	v_mfma_f32_16x16x32_bf16 v[146:149], v[162:165], v[184:187], v[146:149]
	v_mfma_f32_16x16x32_bf16 v[142:145], v[170:173], v[184:187], v[142:145]
	v_mfma_f32_16x16x32_bf16 v[130:133], v[162:165], v[192:195], v[130:133]
	v_mfma_f32_16x16x32_bf16 v[126:129], v[170:173], v[192:195], v[126:129]
	s_setprio 2
	s_barrier
	v_mfma_f32_16x16x32_bf16 v[114:117], v[162:165], v[208:211], v[114:117]
	v_mfma_f32_16x16x32_bf16 v[110:113], v[170:173], v[208:211], v[110:113]
	v_mfma_f32_16x16x32_bf16 v[86:89], v[162:165], v[216:219], v[86:89]
	v_mfma_f32_16x16x32_bf16 v[78:81], v[170:173], v[216:219], v[78:81]
	s_setprio 0
	s_add_i32 s83, s75, s55
	s_mov_b64 s[2:3], s[12:13]
	s_mov_b32 m0, s83
	ds_read_b128 v[180:183], v203 offset:16384
	ds_read_b128 v[184:187], v203 offset:17408
	ds_read_b128 v[188:191], v203 offset:18432
	ds_read_b128 v[192:195], v203 offset:19456
	ds_read_b128 v[204:207], v203 offset:20480
	ds_read_b128 v[208:211], v203 offset:21504
	ds_read_b128 v[212:215], v203 offset:22528
	ds_read_b128 v[216:219], v203 offset:23552
	s_nop 0
	global_load_lds_dwordx4 v221, s[2:3]
	s_add_i32 m0, s83, 0x2000
	s_nop 0
	global_load_lds_dwordx4 v8, s[2:3]
	s_add_u32 s2, s12, 0x40000
	s_addc_u32 s3, s13, 0
	s_add_i32 s83, s76, s55
	s_mov_b32 m0, s83
	s_nop 0
	global_load_lds_dwordx4 v221, s[2:3]
	s_add_i32 m0, s83, 0x2000
	s_nop 0
	global_load_lds_dwordx4 v8, s[2:3]
	s_mov_b64 s[2:3], s[58:59]
	s_mov_b32 m0, s57
	s_nop 0
	global_load_lds_dwordx4 v220, s[2:3]
	s_mov_b32 m0, s64
	s_nop 0
	global_load_lds_dwordx4 v222, s[2:3]
	s_waitcnt vmcnt(8)
	s_waitcnt lgkmcnt(0)
	s_barrier
	s_setprio 1
	s_waitcnt lgkmcnt(0)
	v_mfma_f32_16x16x32_bf16 v[74:77], v[82:85], v[180:183], v[74:77]
	v_mfma_f32_16x16x32_bf16 v[70:73], v[94:97], v[180:183], v[70:73]
	v_mfma_f32_16x16x32_bf16 v[58:61], v[82:85], v[188:191], v[58:61]
	v_mfma_f32_16x16x32_bf16 v[54:57], v[94:97], v[188:191], v[54:57]
	v_mfma_f32_16x16x32_bf16 v[42:45], v[82:85], v[204:207], v[42:45]
	v_mfma_f32_16x16x32_bf16 v[38:41], v[94:97], v[204:207], v[38:41]
	v_mfma_f32_16x16x32_bf16 v[26:29], v[82:85], v[212:215], v[26:29]
	v_mfma_f32_16x16x32_bf16 v[22:25], v[94:97], v[212:215], v[22:25]
	v_mfma_f32_16x16x32_bf16 v[74:77], v[90:93], v[184:187], v[74:77]
	v_mfma_f32_16x16x32_bf16 v[70:73], v[102:105], v[184:187], v[70:73]
	v_mfma_f32_16x16x32_bf16 v[58:61], v[90:93], v[192:195], v[58:61]
	v_mfma_f32_16x16x32_bf16 v[54:57], v[102:105], v[192:195], v[54:57]
	v_mfma_f32_16x16x32_bf16 v[42:45], v[90:93], v[208:211], v[42:45]
	v_mfma_f32_16x16x32_bf16 v[38:41], v[102:105], v[208:211], v[38:41]
	v_mfma_f32_16x16x32_bf16 v[26:29], v[90:93], v[216:219], v[26:29]
	v_mfma_f32_16x16x32_bf16 v[22:25], v[102:105], v[216:219], v[22:25]
	s_setprio 0
	s_setprio 1
	v_mfma_f32_16x16x32_bf16 v[66:69], v[158:161], v[180:183], v[66:69]
	v_mfma_f32_16x16x32_bf16 v[62:65], v[166:169], v[180:183], v[62:65]
	v_mfma_f32_16x16x32_bf16 v[50:53], v[158:161], v[188:191], v[50:53]
	v_mfma_f32_16x16x32_bf16 v[46:49], v[166:169], v[188:191], v[46:49]
	v_mfma_f32_16x16x32_bf16 v[34:37], v[158:161], v[204:207], v[34:37]
	v_mfma_f32_16x16x32_bf16 v[30:33], v[166:169], v[204:207], v[30:33]
	v_mfma_f32_16x16x32_bf16 v[18:21], v[158:161], v[212:215], v[18:21]
	v_mfma_f32_16x16x32_bf16 v[14:17], v[166:169], v[212:215], v[14:17]
	v_mfma_f32_16x16x32_bf16 v[66:69], v[162:165], v[184:187], v[66:69]
	v_mfma_f32_16x16x32_bf16 v[62:65], v[170:173], v[184:187], v[62:65]
	v_mfma_f32_16x16x32_bf16 v[50:53], v[162:165], v[192:195], v[50:53]
	v_mfma_f32_16x16x32_bf16 v[46:49], v[170:173], v[192:195], v[46:49]
	s_setprio 2
	s_barrier
; #define PG8_STAGE(bufoff, gbase, voff) do { const char* gb_ = (const char*)(gbase); asm volatile("" : "+s"(gb_));     \
;         _Pragma("unroll") for (int _i = 0; _i < 2; ++_i) \
;         __builtin_amdgcn_global_load_lds((const unsigned*)(gb_ + (voff)[_i]), (PG8_LAS unsigned*)(lds + (bufoff) + ldsw + _i * 8192), 16, 0, 0); } while (0)
; #define PG8_LDA(dst, b, h) do { _Pragma("unroll") for (int m = 0; m < 4; ++m) _Pragma("unroll") for (int k = 0; k < 2; ++k) dst[m][k] = *(const PG8_LAS bf16x8*)(lds + PG8_SA(b, h) + aoff + m * 2048 + k * 1024); } while (0)
; #define PG8_LDB(dst, b, h) do { _Pragma("unroll") for (int n = 0; n < 2; ++n) _Pragma("unroll") for (int k = 0; k < 2; ++k) dst[n][k] = *(const PG8_LAS bf16x8*)(lds + PG8_SB(b, h) + boff + n * 2048 + k * 1024); } while (0)
; #define PG8_MMA(ai, bj, At, Bt) do { __builtin_amdgcn_s_setprio(1); _Pragma("unroll") for (int m = 0; m < 4; ++m) _Pragma("unroll") for (int n = 0; n < 2; ++n) _Pragma("unroll") for (int k = 0; k < 2; ++k) \
;         acc[ai][bj][m][n] = __builtin_amdgcn_mfma_f32_16x16x32_bf16(Bt[n][k], At[m][k], acc[ai][bj][m][n], 0, 0, 0); __builtin_amdgcn_s_setprio(0); } while (0)
; #define PG8_WAIT_V(n) asm volatile("s_waitcnt vmcnt(" #n ")" ::: "memory")
; #define PG8_WAIT_L(n) asm volatile("s_waitcnt lgkmcnt(" #n ")" ::: "memory")
; #define PG8_BAR __builtin_amdgcn_s_barrier()
; #define PG8_SCHED __builtin_amdgcn_sched_barrier(0)
; template <class Epi, class Sched, bool ALIGN_EPI = false, bool SP2 = false>
; __device__ __forceinline__ void gemm_phase(PG8_LAS unsigned char* lds, const Gemm g, const Sched& S, const Epi& E, int wid0) {
;     ...
;             PG8_WAIT_V(8); PG8_WAIT_L(0); PG8_BAR; PG8_MMA(0, 0, At, B0); PG8_MMA(0, 1, At, B1); PG8_BAR; PG8_SCHED;
;             PG8_LDA(At, 0, 1); PG8_STAGE(PG8_SB(0, 0), b2, vB_); PG8_STAGE(PG8_SB(0, 1), b2 + hstep, vB_); PG8_STAGE(PG8_SA(0, 0), a2, vA_);
;             PG8_WAIT_V(8); PG8_WAIT_L(0); PG8_BAR; PG8_MMA(1, 0, At, B0); PG8_MMA(1, 1, At, B1); PG8_BAR; PG8_SCHED;
;             PG8_LDB(B0, 1, 0); PG8_LDB(B1, 1, 1); PG8_SCHED; PG8_LDA(At, 1, 0); PG8_STAGE(PG8_SA(0, 1), a2 + hstepA, vA_);
;             PG8_WAIT_V(8); PG8_WAIT_L(0); PG8_BAR; PG8_MMA(0, 0, At, B0); PG8_MMA(0, 1, At, B1); PG8_BAR; PG8_SCHED;
	v_mfma_f32_16x16x32_bf16 v[34:37], v[162:165], v[208:211], v[34:37]
	v_mfma_f32_16x16x32_bf16 v[30:33], v[170:173], v[208:211], v[30:33]
	v_mfma_f32_16x16x32_bf16 v[18:21], v[162:165], v[216:219], v[18:21]
	v_mfma_f32_16x16x32_bf16 v[14:17], v[170:173], v[216:219], v[14:17]
	s_setprio 0
	s_add_i32 s83, 0, 0x18000
	s_add_i32 s84, 0, 0x1c000
	v_add_u32_e32 v102, s83, v175
	v_add_u32_e32 v170, s84, v175
	ds_read_b128 v[82:85], v102
	ds_read_b128 v[90:93], v102 offset:1024
	ds_read_b128 v[94:97], v102 offset:2048
	ds_read_b128 v[102:105], v102 offset:3072
	ds_read_b128 v[158:161], v170
	ds_read_b128 v[162:165], v170 offset:1024
	ds_read_b128 v[166:169], v170 offset:2048
	ds_read_b128 v[170:173], v170 offset:3072
	s_add_u32 s2, s58, 0x40000
	s_addc_u32 s3, s59, 0
	s_mov_b32 m0, s65
	ds_read_b128 v[180:183], v203 offset:32768
	ds_read_b128 v[184:187], v203 offset:33792
	ds_read_b128 v[188:191], v203 offset:34816
	ds_read_b128 v[192:195], v203 offset:35840
	ds_read_b128 v[204:207], v203 offset:36864
	ds_read_b128 v[208:211], v203 offset:37888
	ds_read_b128 v[212:215], v203 offset:38912
	ds_read_b128 v[216:219], v203 offset:39936
	s_nop 0
	global_load_lds_dwordx4 v220, s[2:3]
	s_mov_b32 m0, s66
	s_nop 0
	global_load_lds_dwordx4 v222, s[2:3]
	s_waitcnt vmcnt(8)
	s_waitcnt lgkmcnt(0)
	s_barrier
	s_setprio 1
	s_waitcnt lgkmcnt(0)
	v_mfma_f32_16x16x32_bf16 v[154:157], v[82:85], v[180:183], v[154:157]
	v_mfma_f32_16x16x32_bf16 v[150:153], v[94:97], v[180:183], v[150:153]
	v_mfma_f32_16x16x32_bf16 v[138:141], v[82:85], v[188:191], v[138:141]
	v_mfma_f32_16x16x32_bf16 v[134:137], v[94:97], v[188:191], v[134:137]
	v_mfma_f32_16x16x32_bf16 v[122:125], v[82:85], v[204:207], v[122:125]
	v_mfma_f32_16x16x32_bf16 v[118:121], v[94:97], v[204:207], v[118:121]
	v_mfma_f32_16x16x32_bf16 v[106:109], v[82:85], v[212:215], v[106:109]
	v_mfma_f32_16x16x32_bf16 v[98:101], v[94:97], v[212:215], v[98:101]
	v_mfma_f32_16x16x32_bf16 v[154:157], v[90:93], v[184:187], v[154:157]
	v_mfma_f32_16x16x32_bf16 v[150:153], v[102:105], v[184:187], v[150:153]
	v_mfma_f32_16x16x32_bf16 v[138:141], v[90:93], v[192:195], v[138:141]
	v_mfma_f32_16x16x32_bf16 v[134:137], v[102:105], v[192:195], v[134:137]
	v_mfma_f32_16x16x32_bf16 v[122:125], v[90:93], v[208:211], v[122:125]
	v_mfma_f32_16x16x32_bf16 v[118:121], v[102:105], v[208:211], v[118:121]
	v_mfma_f32_16x16x32_bf16 v[106:109], v[90:93], v[216:219], v[106:109]
	v_mfma_f32_16x16x32_bf16 v[98:101], v[102:105], v[216:219], v[98:101]
	s_setprio 0
	s_setprio 1
	v_mfma_f32_16x16x32_bf16 v[146:149], v[158:161], v[180:183], v[146:149]
	v_mfma_f32_16x16x32_bf16 v[142:145], v[166:169], v[180:183], v[142:145]
	v_mfma_f32_16x16x32_bf16 v[130:133], v[158:161], v[188:191], v[130:133]
	v_mfma_f32_16x16x32_bf16 v[126:129], v[166:169], v[188:191], v[126:129]
	v_mfma_f32_16x16x32_bf16 v[114:117], v[158:161], v[204:207], v[114:117]
	v_mfma_f32_16x16x32_bf16 v[110:113], v[166:169], v[204:207], v[110:113]
	v_mfma_f32_16x16x32_bf16 v[86:89], v[158:161], v[212:215], v[86:89]
	v_mfma_f32_16x16x32_bf16 v[78:81], v[166:169], v[212:215], v[78:81]
	v_mfma_f32_16x16x32_bf16 v[146:149], v[162:165], v[184:187], v[146:149]
	v_mfma_f32_16x16x32_bf16 v[142:145], v[170:173], v[184:187], v[142:145]
	v_mfma_f32_16x16x32_bf16 v[130:133], v[162:165], v[192:195], v[130:133]
	v_mfma_f32_16x16x32_bf16 v[126:129], v[170:173], v[192:195], v[126:129]
	s_setprio 2
	s_barrier
; #define PG8_STAGE(bufoff, gbase, voff) do { const char* gb_ = (const char*)(gbase); asm volatile("" : "+s"(gb_));     \
;         _Pragma("unroll") for (int _i = 0; _i < 2; ++_i) \
;         __builtin_amdgcn_global_load_lds((const unsigned*)(gb_ + (voff)[_i]), (PG8_LAS unsigned*)(lds + (bufoff) + ldsw + _i * 8192), 16, 0, 0); } while (0)
; #define PG8_LDA(dst, b, h) do { _Pragma("unroll") for (int m = 0; m < 4; ++m) _Pragma("unroll") for (int k = 0; k < 2; ++k) dst[m][k] = *(const PG8_LAS bf16x8*)(lds + PG8_SA(b, h) + aoff + m * 2048 + k * 1024); } while (0)
; #define PG8_MMA(ai, bj, At, Bt) do { __builtin_amdgcn_s_setprio(1); _Pragma("unroll") for (int m = 0; m < 4; ++m) _Pragma("unroll") for (int n = 0; n < 2; ++n) _Pragma("unroll") for (int k = 0; k < 2; ++k) \
;         acc[ai][bj][m][n] = __builtin_amdgcn_mfma_f32_16x16x32_bf16(Bt[n][k], At[m][k], acc[ai][bj][m][n], 0, 0, 0); __builtin_amdgcn_s_setprio(0); } while (0)
; #define PG8_WAIT_V(n) asm volatile("s_waitcnt vmcnt(" #n ")" ::: "memory")
; #define PG8_WAIT_L(n) asm volatile("s_waitcnt lgkmcnt(" #n ")" ::: "memory")
; #define PG8_BAR __builtin_amdgcn_s_barrier()
; #define PG8_SCHED __builtin_amdgcn_sched_barrier(0)
; template <class Epi, class Sched, bool ALIGN_EPI = false, bool SP2 = false>
; __device__ __forceinline__ void gemm_phase(PG8_LAS unsigned char* lds, const Gemm g, const Sched& S, const Epi& E, int wid0) {
;     ...
;             PG8_WAIT_V(8); PG8_WAIT_L(0); PG8_BAR; PG8_MMA(0, 0, At, B0); PG8_MMA(0, 1, At, B1); PG8_BAR; PG8_SCHED;
;             PG8_LDA(At, 1, 1); PG8_STAGE(PG8_SB(1, 0), b3, vB_); PG8_STAGE(PG8_SB(1, 1), b3 + hstep, vB_); PG8_STAGE(PG8_SA(1, 0), a3, vA_);
;             PG8_WAIT_V(8); PG8_WAIT_L(0); PG8_BAR; PG8_MMA(1, 0, At, B0); PG8_MMA(1, 1, At, B1); PG8_BAR; PG8_SCHED;
;     ...
;         if constexpr (ALIGN_EPI) { if (wr == 0) PG8_BAR; }
	v_mfma_f32_16x16x32_bf16 v[114:117], v[162:165], v[208:211], v[114:117]
	v_mfma_f32_16x16x32_bf16 v[110:113], v[170:173], v[208:211], v[110:113]
	v_mfma_f32_16x16x32_bf16 v[86:89], v[162:165], v[216:219], v[86:89]
	v_mfma_f32_16x16x32_bf16 v[78:81], v[170:173], v[216:219], v[78:81]
	s_setprio 0
	s_add_u32 s2, s12, 0x80
	s_addc_u32 s3, s13, 0
	s_add_i32 s58, s83, s55
	s_mov_b32 m0, s58
	ds_read_b128 v[180:183], v203 offset:49152
	ds_read_b128 v[184:187], v203 offset:50176
	ds_read_b128 v[188:191], v203 offset:51200
	ds_read_b128 v[192:195], v203 offset:52224
	ds_read_b128 v[204:207], v203 offset:53248
	ds_read_b128 v[208:211], v203 offset:54272
	ds_read_b128 v[212:215], v203 offset:55296
	ds_read_b128 v[216:219], v203 offset:56320
	s_nop 0
	global_load_lds_dwordx4 v221, s[2:3]
	s_add_i32 m0, s58, 0x2000
	s_nop 0
	global_load_lds_dwordx4 v8, s[2:3]
	s_add_u32 s2, s12, 0x40080
	s_addc_u32 s3, s13, 0
	s_add_i32 s12, s84, s55
	s_mov_b32 m0, s12
	s_nop 0
	global_load_lds_dwordx4 v221, s[2:3]
	s_add_i32 m0, s12, 0x2000
	s_nop 0
	global_load_lds_dwordx4 v8, s[2:3]
	s_mov_b32 m0, s69
	s_nop 0
	global_load_lds_dwordx4 v220, s[10:11]
	s_mov_b32 m0, s70
	s_nop 0
	global_load_lds_dwordx4 v222, s[10:11]
	s_waitcnt vmcnt(8)
	s_waitcnt lgkmcnt(0)
	s_barrier
	s_setprio 1
	s_waitcnt lgkmcnt(0)
	v_mfma_f32_16x16x32_bf16 v[74:77], v[82:85], v[180:183], v[74:77]
	v_mfma_f32_16x16x32_bf16 v[70:73], v[94:97], v[180:183], v[70:73]
	v_mfma_f32_16x16x32_bf16 v[58:61], v[82:85], v[188:191], v[58:61]
	v_mfma_f32_16x16x32_bf16 v[54:57], v[94:97], v[188:191], v[54:57]
	v_mfma_f32_16x16x32_bf16 v[42:45], v[82:85], v[204:207], v[42:45]
	v_mfma_f32_16x16x32_bf16 v[38:41], v[94:97], v[204:207], v[38:41]
	v_mfma_f32_16x16x32_bf16 v[26:29], v[82:85], v[212:215], v[26:29]
	v_mfma_f32_16x16x32_bf16 v[22:25], v[94:97], v[212:215], v[22:25]
	v_mfma_f32_16x16x32_bf16 v[74:77], v[90:93], v[184:187], v[74:77]
	v_mfma_f32_16x16x32_bf16 v[70:73], v[102:105], v[184:187], v[70:73]
	v_mfma_f32_16x16x32_bf16 v[58:61], v[90:93], v[192:195], v[58:61]
	v_mfma_f32_16x16x32_bf16 v[54:57], v[102:105], v[192:195], v[54:57]
	v_mfma_f32_16x16x32_bf16 v[42:45], v[90:93], v[208:211], v[42:45]
	v_mfma_f32_16x16x32_bf16 v[38:41], v[102:105], v[208:211], v[38:41]
	v_mfma_f32_16x16x32_bf16 v[26:29], v[90:93], v[216:219], v[26:29]
	v_mfma_f32_16x16x32_bf16 v[22:25], v[102:105], v[216:219], v[22:25]
	s_setprio 0
	s_setprio 1
	v_mfma_f32_16x16x32_bf16 v[66:69], v[158:161], v[180:183], v[66:69]
	v_mfma_f32_16x16x32_bf16 v[62:65], v[166:169], v[180:183], v[62:65]
	v_mfma_f32_16x16x32_bf16 v[50:53], v[158:161], v[188:191], v[50:53]
	v_mfma_f32_16x16x32_bf16 v[46:49], v[166:169], v[188:191], v[46:49]
	v_mfma_f32_16x16x32_bf16 v[34:37], v[158:161], v[204:207], v[34:37]
	v_mfma_f32_16x16x32_bf16 v[30:33], v[166:169], v[204:207], v[30:33]
	v_mfma_f32_16x16x32_bf16 v[18:21], v[158:161], v[212:215], v[18:21]
	v_mfma_f32_16x16x32_bf16 v[14:17], v[166:169], v[212:215], v[14:17]
	v_mfma_f32_16x16x32_bf16 v[66:69], v[162:165], v[184:187], v[66:69]
	v_mfma_f32_16x16x32_bf16 v[62:65], v[170:173], v[184:187], v[62:65]
	v_mfma_f32_16x16x32_bf16 v[50:53], v[162:165], v[192:195], v[50:53]
	v_mfma_f32_16x16x32_bf16 v[46:49], v[170:173], v[192:195], v[46:49]
	s_setprio 2
	s_barrier
	v_mfma_f32_16x16x32_bf16 v[34:37], v[162:165], v[208:211], v[34:37]
	v_mfma_f32_16x16x32_bf16 v[30:33], v[170:173], v[208:211], v[30:33]
	v_mfma_f32_16x16x32_bf16 v[18:21], v[162:165], v[216:219], v[18:21]
	v_mfma_f32_16x16x32_bf16 v[14:17], v[170:173], v[216:219], v[14:17]
	s_setprio 0
	s_add_i32 s82, s82, 2
	s_add_u32 s80, s80, 0x100
	s_addc_u32 s81, s81, 0
	s_cmp_gt_u32 s82, 13
	s_mov_b64 s[2:3], s[8:9]
	s_cbranch_scc0 .LBB13_1336
	s_and_b64 vcc, exec, s[42:43]
	s_cbranch_vccz .LBB13_1339
	s_barrier

;     __device__ float mid(int row) const { return rg(row) / ra(row); }
;     __device__ __forceinline__ bool next(int i, Unit& u) const { return map(rank + i * nloc, u); }
; #define PG8_LDA(dst, b, h) do { _Pragma("unroll") for (int m = 0; m < 4; ++m) _Pragma("unroll") for (int k = 0; k < 2; ++k) dst[m][k] = *(const PG8_LAS bf16x8*)(lds + PG8_SA(b, h) + aoff + m * 2048 + k * 1024); } while (0)
; template <class Epi, class Sched, bool ALIGN_EPI = false, bool SP2 = false>
; __device__ __forceinline__ void gemm_phase(PG8_LAS unsigned char* lds, const Gemm g, const Sched& S, const Epi& E, int wid0) {
;     ...
;         const bool has_next = S.next(ui + 1, nxt); nxt.ui = ui + 1;
;         if constexpr (Epi::HAS_PRE) E.pre_finish(lds, cur, tid, pq0, pq1, pq2);
;         const char* nA = has_next ? (const char*)g.A + (size_t)nxt.pm * tstepA : cA; const char* nB = has_next ? (const char*)g.Bt + (size_t)nxt.pn * tstep : cB;
; #pragma nounroll
;         for (int t = 0; t < nt; t += 2) {
;             const bool last = (t == nt - 2);
;             const char* a1 = cA + (size_t)(t + 1) * kstep;
;             const char* a2 = last ? nA : cA + (size_t)(t + 2) * kstep; const char* b2 = last ? nB : cB + (size_t)(t + 2) * kstep;
;             const char* a3 = a2 + kstep; const char* b3 = b2 + kstep;
;             if (last && has_next) S.a_ready(nxt);
;             if constexpr (Epi::HAS_MID) { if (t == Epi::MID_T) E.mid(acc, cur, wr, fr); }
;             unsigned vA_[2] = {voffA[0], voffA[1]}, vB_[2] = {voffB[0], voffB[1]};
;             asm volatile("" : "+v"(vA_[0]), "+v"(vA_[1]), "+v"(vB_[0]), "+v"(vB_[1]));
;             if constexpr (SP2) {
;             PG8_LDB(B0, 0, 0); PG8_LDB(B1, 0, 1); PG8_SCHED; PG8_LDA(At, 0, 0); PG8_STAGE(PG8_SA(1, 1), a1 + hstepA, vA_);
;             PG8_WAIT_V(8); PG8_WAIT_L(0); PG8_BAR; PG8_MMA(0, 0, At, B0); PG8_MMA(0, 1, At, B1); PG8_BAR; PG8_SCHED;
;             PG8_LDA(At, 0, 1); PG8_STAGE(PG8_SB(0, 0), b2, vB_); PG8_STAGE(PG8_SB(0, 1), b2 + hstep, vB_); PG8_STAGE(PG8_SA(0, 0), a2, vA_);
;             PG8_WAIT_V(8); PG8_WAIT_L(0); PG8_BAR; PG8_MMA(1, 0, At, B0); PG8_MMA(1, 1, At, B1); PG8_BAR; PG8_SCHED;
;             PG8_LDB(B0, 1, 0); PG8_LDB(B1, 1, 1); PG8_SCHED; PG8_LDA(At, 1, 0); PG8_STAGE(PG8_SA(0, 1), a2 + hstepA, vA_);
;             PG8_WAIT_V(8); PG8_WAIT_L(0); PG8_BAR; PG8_MMA(0, 0, At, B0); PG8_MMA(0, 1, At, B1); PG8_BAR; PG8_SCHED;
.LBB13_1520:
	s_add_u32 s40, s28, s36
	s_addc_u32 s41, s29, s37
	s_add_u32 s42, s40, 0x100
	s_addc_u32 s43, s41, 0
	s_and_b64 s[38:39], s[34:35], exec
	s_cselect_b32 s43, s5, s43
	s_cselect_b32 s42, s7, s42
	s_add_u32 s36, s26, s36
	s_addc_u32 s37, s27, s37
	s_add_u32 s38, s36, 0x100
	s_addc_u32 s39, s37, 0
	s_add_u32 s36, s42, 0x80
	s_addc_u32 s37, s43, 0
	s_and_b64 s[34:35], s[34:35], exec
	s_cselect_b32 s45, s17, s39
	s_cselect_b32 s44, s19, s38
	s_add_u32 s48, s40, 0x10080
	s_addc_u32 s49, s41, 0
	s_add_i32 s76, s64, s50
	v_mov_b32_e32 v158, v160
	v_mov_b32_e32 v183, v162
	v_mov_b32_e32 v212, v156
	v_mov_b32_e32 v213, v163
	s_add_i32 m0, s55, 0xc000
	s_add_i32 s79, s55, 0xe000
	s_add_i32 s74, s76, 0x2000
	ds_read_b128 v[72:75], v172
	ds_read_b128 v[92:95], v172 offset:1024
	ds_read_b128 v[112:115], v172 offset:2048
	ds_read_b128 v[132:135], v172 offset:3072
	ds_read_b128 v[144:147], v173
	ds_read_b128 v[148:151], v173 offset:1024
	ds_read_b128 v[152:155], v173 offset:2048
	ds_read_b128 v[164:167], v173 offset:3072
	s_add_u32 s46, s44, 0x10000
	s_addc_u32 s47, s45, 0
	s_add_i32 s75, s65, s50
	s_add_i32 s73, s75, 0x2000
	s_add_i32 s72, 0, 0x18000
	s_add_i32 s71, 0, 0x1c000
	s_add_u32 s40, s42, 0x10000
	s_addc_u32 s41, s43, 0
	s_add_u32 s38, s44, 0x80
	s_addc_u32 s39, s45, 0
	s_add_i32 s70, s72, s50
	s_add_i32 s69, s70, 0x2000
	s_add_u32 s34, s44, 0x10080
	s_addc_u32 s35, s45, 0
	s_add_i32 s78, s71, s50
	s_add_i32 s77, s78, 0x2000
	ds_read_b128 v[168:171], v174
	ds_read_b128 v[184:187], v174 offset:1024
	ds_read_b128 v[188:191], v174 offset:2048
	ds_read_b128 v[192:195], v174 offset:3072
	ds_read_b128 v[196:199], v174 offset:4096
	ds_read_b128 v[200:203], v174 offset:5120
	ds_read_b128 v[204:207], v174 offset:6144
	ds_read_b128 v[208:211], v174 offset:7168
	s_nop 0
	global_load_lds_dwordx4 v212, s[48:49]
	s_mov_b32 m0, s79
	s_nop 0
	global_load_lds_dwordx4 v158, s[48:49]
	s_waitcnt vmcnt(8)
	s_waitcnt lgkmcnt(0)
	s_barrier
	s_setprio 1
	s_waitcnt lgkmcnt(0)
	v_mfma_f32_16x16x32_bf16 v[140:143], v[72:75], v[168:171], v[140:143]
	v_mfma_f32_16x16x32_bf16 v[136:139], v[112:115], v[168:171], v[136:139]
	v_mfma_f32_16x16x32_bf16 v[120:123], v[72:75], v[188:191], v[120:123]
	v_mfma_f32_16x16x32_bf16 v[116:119], v[112:115], v[188:191], v[116:119]
	v_mfma_f32_16x16x32_bf16 v[100:103], v[72:75], v[196:199], v[100:103]
	v_mfma_f32_16x16x32_bf16 v[96:99], v[112:115], v[196:199], v[96:99]
	v_mfma_f32_16x16x32_bf16 v[80:83], v[72:75], v[204:207], v[80:83]
	v_mfma_f32_16x16x32_bf16 v[76:79], v[112:115], v[204:207], v[76:79]
	v_mfma_f32_16x16x32_bf16 v[140:143], v[92:95], v[184:187], v[140:143]
	v_mfma_f32_16x16x32_bf16 v[136:139], v[132:135], v[184:187], v[136:139]
	v_mfma_f32_16x16x32_bf16 v[120:123], v[92:95], v[192:195], v[120:123]
	v_mfma_f32_16x16x32_bf16 v[116:119], v[132:135], v[192:195], v[116:119]
	v_mfma_f32_16x16x32_bf16 v[100:103], v[92:95], v[200:203], v[100:103]
	v_mfma_f32_16x16x32_bf16 v[96:99], v[132:135], v[200:203], v[96:99]
	v_mfma_f32_16x16x32_bf16 v[80:83], v[92:95], v[208:211], v[80:83]
	v_mfma_f32_16x16x32_bf16 v[76:79], v[132:135], v[208:211], v[76:79]
	s_setprio 0
	s_setprio 1
	v_mfma_f32_16x16x32_bf16 v[128:131], v[144:147], v[168:171], v[128:131]
	v_mfma_f32_16x16x32_bf16 v[124:127], v[152:155], v[168:171], v[124:127]
	v_mfma_f32_16x16x32_bf16 v[108:111], v[144:147], v[188:191], v[108:111]
	v_mfma_f32_16x16x32_bf16 v[104:107], v[152:155], v[188:191], v[104:107]
	v_mfma_f32_16x16x32_bf16 v[88:91], v[144:147], v[196:199], v[88:91]
	v_mfma_f32_16x16x32_bf16 v[84:87], v[152:155], v[196:199], v[84:87]
	v_mfma_f32_16x16x32_bf16 v[68:71], v[144:147], v[204:207], v[68:71]
	v_mfma_f32_16x16x32_bf16 v[64:67], v[152:155], v[204:207], v[64:67]
	v_mfma_f32_16x16x32_bf16 v[128:131], v[148:151], v[184:187], v[128:131]
	v_mfma_f32_16x16x32_bf16 v[124:127], v[164:167], v[184:187], v[124:127]
	v_mfma_f32_16x16x32_bf16 v[108:111], v[148:151], v[192:195], v[108:111]
	v_mfma_f32_16x16x32_bf16 v[104:107], v[164:167], v[192:195], v[104:107]
	s_setprio 2
	s_barrier
	v_mfma_f32_16x16x32_bf16 v[88:91], v[148:151], v[200:203], v[88:91]
	v_mfma_f32_16x16x32_bf16 v[84:87], v[164:167], v[200:203], v[84:87]
	v_mfma_f32_16x16x32_bf16 v[68:71], v[148:151], v[208:211], v[68:71]
	v_mfma_f32_16x16x32_bf16 v[64:67], v[164:167], v[208:211], v[64:67]
	s_setprio 0
	s_mov_b32 m0, s76
	ds_read_b128 v[168:171], v174 offset:16384
	ds_read_b128 v[184:187], v174 offset:17408
	ds_read_b128 v[188:191], v174 offset:18432
	ds_read_b128 v[192:195], v174 offset:19456
	ds_read_b128 v[196:199], v174 offset:20480
	ds_read_b128 v[200:203], v174 offset:21504
	ds_read_b128 v[204:207], v174 offset:22528
	ds_read_b128 v[208:211], v174 offset:23552
	s_nop 0
	global_load_lds_dwordx4 v213, s[44:45]
	s_mov_b32 m0, s74
	s_nop 0
	global_load_lds_dwordx4 v183, s[44:45]
	s_mov_b32 m0, s75
	s_nop 0
	global_load_lds_dwordx4 v213, s[46:47]
	s_mov_b32 m0, s73
	s_nop 0
	global_load_lds_dwordx4 v183, s[46:47]
	s_mov_b32 m0, s55
	s_nop 0
	global_load_lds_dwordx4 v212, s[42:43]
	s_mov_b32 m0, s56
	s_nop 0
	global_load_lds_dwordx4 v158, s[42:43]
	s_waitcnt vmcnt(8)
	s_waitcnt lgkmcnt(0)
	s_barrier
; #define PG8_STAGE(bufoff, gbase, voff) do { const char* gb_ = (const char*)(gbase); asm volatile("" : "+s"(gb_));     \
;         _Pragma("unroll") for (int _i = 0; _i < 2; ++_i) \
;         __builtin_amdgcn_global_load_lds((const unsigned*)(gb_ + (voff)[_i]), (PG8_LAS unsigned*)(lds + (bufoff) + ldsw + _i * 8192), 16, 0, 0); } while (0)
; #define PG8_LDA(dst, b, h) do { _Pragma("unroll") for (int m = 0; m < 4; ++m) _Pragma("unroll") for (int k = 0; k < 2; ++k) dst[m][k] = *(const PG8_LAS bf16x8*)(lds + PG8_SA(b, h) + aoff + m * 2048 + k * 1024); } while (0)
; #define PG8_LDB(dst, b, h) do { _Pragma("unroll") for (int n = 0; n < 2; ++n) _Pragma("unroll") for (int k = 0; k < 2; ++k) dst[n][k] = *(const PG8_LAS bf16x8*)(lds + PG8_SB(b, h) + boff + n * 2048 + k * 1024); } while (0)
; #define PG8_MMA(ai, bj, At, Bt) do { __builtin_amdgcn_s_setprio(1); _Pragma("unroll") for (int m = 0; m < 4; ++m) _Pragma("unroll") for (int n = 0; n < 2; ++n) _Pragma("unroll") for (int k = 0; k < 2; ++k) \
;         acc[ai][bj][m][n] = __builtin_amdgcn_mfma_f32_16x16x32_bf16(Bt[n][k], At[m][k], acc[ai][bj][m][n], 0, 0, 0); __builtin_amdgcn_s_setprio(0); } while (0)
; #define PG8_WAIT_V(n) asm volatile("s_waitcnt vmcnt(" #n ")" ::: "memory")
; #define PG8_WAIT_L(n) asm volatile("s_waitcnt lgkmcnt(" #n ")" ::: "memory")
; #define PG8_BAR __builtin_amdgcn_s_barrier()
; #define PG8_SCHED __builtin_amdgcn_sched_barrier(0)
; template <class Epi, class Sched, bool ALIGN_EPI = false, bool SP2 = false>
; __device__ __forceinline__ void gemm_phase(PG8_LAS unsigned char* lds, const Gemm g, const Sched& S, const Epi& E, int wid0) {
;     ...
;             PG8_WAIT_V(8); PG8_WAIT_L(0); PG8_BAR; PG8_MMA(0, 0, At, B0); PG8_MMA(0, 1, At, B1); PG8_BAR; PG8_SCHED;
;             PG8_LDA(At, 0, 1); PG8_STAGE(PG8_SB(0, 0), b2, vB_); PG8_STAGE(PG8_SB(0, 1), b2 + hstep, vB_); PG8_STAGE(PG8_SA(0, 0), a2, vA_);
;             PG8_WAIT_V(8); PG8_WAIT_L(0); PG8_BAR; PG8_MMA(1, 0, At, B0); PG8_MMA(1, 1, At, B1); PG8_BAR; PG8_SCHED;
;             PG8_LDB(B0, 1, 0); PG8_LDB(B1, 1, 1); PG8_SCHED; PG8_LDA(At, 1, 0); PG8_STAGE(PG8_SA(0, 1), a2 + hstepA, vA_);
;             PG8_WAIT_V(8); PG8_WAIT_L(0); PG8_BAR; PG8_MMA(0, 0, At, B0); PG8_MMA(0, 1, At, B1); PG8_BAR; PG8_SCHED;
	s_setprio 1
	s_waitcnt lgkmcnt(0)
	v_mfma_f32_16x16x32_bf16 v[60:63], v[72:75], v[168:171], v[60:63]
	v_mfma_f32_16x16x32_bf16 v[56:59], v[112:115], v[168:171], v[56:59]
	v_mfma_f32_16x16x32_bf16 v[44:47], v[72:75], v[188:191], v[44:47]
	v_mfma_f32_16x16x32_bf16 v[40:43], v[112:115], v[188:191], v[40:43]
	v_mfma_f32_16x16x32_bf16 v[28:31], v[72:75], v[196:199], v[28:31]
	v_mfma_f32_16x16x32_bf16 v[24:27], v[112:115], v[196:199], v[24:27]
	v_mfma_f32_16x16x32_bf16 v[12:15], v[72:75], v[204:207], v[12:15]
	v_mfma_f32_16x16x32_bf16 v[8:11], v[112:115], v[204:207], v[8:11]
	v_mfma_f32_16x16x32_bf16 v[60:63], v[92:95], v[184:187], v[60:63]
	v_mfma_f32_16x16x32_bf16 v[56:59], v[132:135], v[184:187], v[56:59]
	v_mfma_f32_16x16x32_bf16 v[44:47], v[92:95], v[192:195], v[44:47]
	v_mfma_f32_16x16x32_bf16 v[40:43], v[132:135], v[192:195], v[40:43]
	v_mfma_f32_16x16x32_bf16 v[28:31], v[92:95], v[200:203], v[28:31]
	v_mfma_f32_16x16x32_bf16 v[24:27], v[132:135], v[200:203], v[24:27]
	v_mfma_f32_16x16x32_bf16 v[12:15], v[92:95], v[208:211], v[12:15]
	v_mfma_f32_16x16x32_bf16 v[8:11], v[132:135], v[208:211], v[8:11]
	s_setprio 0
	s_setprio 1
	v_mfma_f32_16x16x32_bf16 v[52:55], v[144:147], v[168:171], v[52:55]
	v_mfma_f32_16x16x32_bf16 v[48:51], v[152:155], v[168:171], v[48:51]
	v_mfma_f32_16x16x32_bf16 v[36:39], v[144:147], v[188:191], v[36:39]
	v_mfma_f32_16x16x32_bf16 v[32:35], v[152:155], v[188:191], v[32:35]
	v_mfma_f32_16x16x32_bf16 v[20:23], v[144:147], v[196:199], v[20:23]
	v_mfma_f32_16x16x32_bf16 v[16:19], v[152:155], v[196:199], v[16:19]
	v_mfma_f32_16x16x32_bf16 v[4:7], v[144:147], v[204:207], v[4:7]
	v_mfma_f32_16x16x32_bf16 v[0:3], v[152:155], v[204:207], v[0:3]
	v_mfma_f32_16x16x32_bf16 v[52:55], v[148:151], v[184:187], v[52:55]
	v_mfma_f32_16x16x32_bf16 v[48:51], v[164:167], v[184:187], v[48:51]
	v_mfma_f32_16x16x32_bf16 v[36:39], v[148:151], v[192:195], v[36:39]
	v_mfma_f32_16x16x32_bf16 v[32:35], v[164:167], v[192:195], v[32:35]
	s_setprio 2
	s_barrier
	v_mfma_f32_16x16x32_bf16 v[20:23], v[148:151], v[200:203], v[20:23]
	v_mfma_f32_16x16x32_bf16 v[16:19], v[164:167], v[200:203], v[16:19]
	v_mfma_f32_16x16x32_bf16 v[4:7], v[148:151], v[208:211], v[4:7]
	v_mfma_f32_16x16x32_bf16 v[0:3], v[164:167], v[208:211], v[0:3]
	s_setprio 0
	v_add_u32_e32 v132, s72, v157
	v_add_u32_e32 v164, s71, v157
	ds_read_b128 v[72:75], v132
	ds_read_b128 v[92:95], v132 offset:1024
	ds_read_b128 v[112:115], v132 offset:2048
	ds_read_b128 v[132:135], v132 offset:3072
	ds_read_b128 v[144:147], v164
	ds_read_b128 v[148:151], v164 offset:1024
	ds_read_b128 v[152:155], v164 offset:2048
	ds_read_b128 v[164:167], v164 offset:3072
	s_mov_b32 m0, s57
	ds_read_b128 v[168:171], v174 offset:32768
	ds_read_b128 v[184:187], v174 offset:33792
	ds_read_b128 v[188:191], v174 offset:34816
	ds_read_b128 v[192:195], v174 offset:35840
	ds_read_b128 v[196:199], v174 offset:36864
	ds_read_b128 v[200:203], v174 offset:37888
	ds_read_b128 v[204:207], v174 offset:38912
	ds_read_b128 v[208:211], v174 offset:39936
	s_nop 0
	global_load_lds_dwordx4 v212, s[40:41]
	s_mov_b32 m0, s58
	s_nop 0
	global_load_lds_dwordx4 v158, s[40:41]
	s_waitcnt vmcnt(8)
	s_waitcnt lgkmcnt(0)
	s_barrier
	s_setprio 1
	s_waitcnt lgkmcnt(0)
	v_mfma_f32_16x16x32_bf16 v[140:143], v[72:75], v[168:171], v[140:143]
	v_mfma_f32_16x16x32_bf16 v[136:139], v[112:115], v[168:171], v[136:139]
	v_mfma_f32_16x16x32_bf16 v[120:123], v[72:75], v[188:191], v[120:123]
	v_mfma_f32_16x16x32_bf16 v[116:119], v[112:115], v[188:191], v[116:119]
	v_mfma_f32_16x16x32_bf16 v[100:103], v[72:75], v[196:199], v[100:103]
	v_mfma_f32_16x16x32_bf16 v[96:99], v[112:115], v[196:199], v[96:99]
	v_mfma_f32_16x16x32_bf16 v[80:83], v[72:75], v[204:207], v[80:83]
	v_mfma_f32_16x16x32_bf16 v[76:79], v[112:115], v[204:207], v[76:79]
	v_mfma_f32_16x16x32_bf16 v[140:143], v[92:95], v[184:187], v[140:143]
	v_mfma_f32_16x16x32_bf16 v[136:139], v[132:135], v[184:187], v[136:139]
	v_mfma_f32_16x16x32_bf16 v[120:123], v[92:95], v[192:195], v[120:123]
	v_mfma_f32_16x16x32_bf16 v[116:119], v[132:135], v[192:195], v[116:119]
	v_mfma_f32_16x16x32_bf16 v[100:103], v[92:95], v[200:203], v[100:103]
	v_mfma_f32_16x16x32_bf16 v[96:99], v[132:135], v[200:203], v[96:99]
	v_mfma_f32_16x16x32_bf16 v[80:83], v[92:95], v[208:211], v[80:83]
	v_mfma_f32_16x16x32_bf16 v[76:79], v[132:135], v[208:211], v[76:79]
	s_setprio 0
	s_setprio 1
	v_mfma_f32_16x16x32_bf16 v[128:131], v[144:147], v[168:171], v[128:131]
	v_mfma_f32_16x16x32_bf16 v[124:127], v[152:155], v[168:171], v[124:127]
	v_mfma_f32_16x16x32_bf16 v[108:111], v[144:147], v[188:191], v[108:111]
	v_mfma_f32_16x16x32_bf16 v[104:107], v[152:155], v[188:191], v[104:107]
	v_mfma_f32_16x16x32_bf16 v[88:91], v[144:147], v[196:199], v[88:91]
	v_mfma_f32_16x16x32_bf16 v[84:87], v[152:155], v[196:199], v[84:87]
	v_mfma_f32_16x16x32_bf16 v[68:71], v[144:147], v[204:207], v[68:71]
	v_mfma_f32_16x16x32_bf16 v[64:67], v[152:155], v[204:207], v[64:67]
	v_mfma_f32_16x16x32_bf16 v[128:131], v[148:151], v[184:187], v[128:131]
	v_mfma_f32_16x16x32_bf16 v[124:127], v[164:167], v[184:187], v[124:127]
	v_mfma_f32_16x16x32_bf16 v[108:111], v[148:151], v[192:195], v[108:111]
	v_mfma_f32_16x16x32_bf16 v[104:107], v[164:167], v[192:195], v[104:107]
	s_setprio 2
	s_barrier
; #define PG8_STAGE(bufoff, gbase, voff) do { const char* gb_ = (const char*)(gbase); asm volatile("" : "+s"(gb_));     \
;         _Pragma("unroll") for (int _i = 0; _i < 2; ++_i) \
;         __builtin_amdgcn_global_load_lds((const unsigned*)(gb_ + (voff)[_i]), (PG8_LAS unsigned*)(lds + (bufoff) + ldsw + _i * 8192), 16, 0, 0); } while (0)
; #define PG8_LDA(dst, b, h) do { _Pragma("unroll") for (int m = 0; m < 4; ++m) _Pragma("unroll") for (int k = 0; k < 2; ++k) dst[m][k] = *(const PG8_LAS bf16x8*)(lds + PG8_SA(b, h) + aoff + m * 2048 + k * 1024); } while (0)
; #define PG8_MMA(ai, bj, At, Bt) do { __builtin_amdgcn_s_setprio(1); _Pragma("unroll") for (int m = 0; m < 4; ++m) _Pragma("unroll") for (int n = 0; n < 2; ++n) _Pragma("unroll") for (int k = 0; k < 2; ++k) \
;         acc[ai][bj][m][n] = __builtin_amdgcn_mfma_f32_16x16x32_bf16(Bt[n][k], At[m][k], acc[ai][bj][m][n], 0, 0, 0); __builtin_amdgcn_s_setprio(0); } while (0)
; #define PG8_WAIT_V(n) asm volatile("s_waitcnt vmcnt(" #n ")" ::: "memory")
; #define PG8_WAIT_L(n) asm volatile("s_waitcnt lgkmcnt(" #n ")" ::: "memory")
; #define PG8_BAR __builtin_amdgcn_s_barrier()
; #define PG8_SCHED __builtin_amdgcn_sched_barrier(0)
; template <class Epi, class Sched, bool ALIGN_EPI = false, bool SP2 = false>
; __device__ __forceinline__ void gemm_phase(PG8_LAS unsigned char* lds, const Gemm g, const Sched& S, const Epi& E, int wid0) {
;     ...
;             PG8_WAIT_V(8); PG8_WAIT_L(0); PG8_BAR; PG8_MMA(0, 0, At, B0); PG8_MMA(0, 1, At, B1); PG8_BAR; PG8_SCHED;
;             PG8_LDA(At, 1, 1); PG8_STAGE(PG8_SB(1, 0), b3, vB_); PG8_STAGE(PG8_SB(1, 1), b3 + hstep, vB_); PG8_STAGE(PG8_SA(1, 0), a3, vA_);
;             PG8_WAIT_V(8); PG8_WAIT_L(0); PG8_BAR; PG8_MMA(1, 0, At, B0); PG8_MMA(1, 1, At, B1); PG8_BAR; PG8_SCHED;
;     ...
;         if constexpr (ALIGN_EPI) { if (wr == 0) PG8_BAR; }
	v_mfma_f32_16x16x32_bf16 v[88:91], v[148:151], v[200:203], v[88:91]
	v_mfma_f32_16x16x32_bf16 v[84:87], v[164:167], v[200:203], v[84:87]
	v_mfma_f32_16x16x32_bf16 v[68:71], v[148:151], v[208:211], v[68:71]
	v_mfma_f32_16x16x32_bf16 v[64:67], v[164:167], v[208:211], v[64:67]
	s_setprio 0
	s_mov_b32 m0, s70
	ds_read_b128 v[168:171], v174 offset:49152
	ds_read_b128 v[184:187], v174 offset:50176
	ds_read_b128 v[188:191], v174 offset:51200
	ds_read_b128 v[192:195], v174 offset:52224
	ds_read_b128 v[196:199], v174 offset:53248
	ds_read_b128 v[200:203], v174 offset:54272
	ds_read_b128 v[204:207], v174 offset:55296
	ds_read_b128 v[208:211], v174 offset:56320
	s_nop 0
	global_load_lds_dwordx4 v213, s[38:39]
	s_mov_b32 m0, s69
	s_nop 0
	global_load_lds_dwordx4 v183, s[38:39]
	s_mov_b32 m0, s78
	s_nop 0
	global_load_lds_dwordx4 v213, s[34:35]
	s_mov_b32 m0, s77
	s_nop 0
	global_load_lds_dwordx4 v183, s[34:35]
	s_mov_b32 m0, s62
	s_nop 0
	global_load_lds_dwordx4 v212, s[36:37]
	s_mov_b32 m0, s63
	s_nop 0
	global_load_lds_dwordx4 v158, s[36:37]
	s_waitcnt vmcnt(8)
	s_waitcnt lgkmcnt(0)
	s_barrier
	s_setprio 1
	s_waitcnt lgkmcnt(0)
	v_mfma_f32_16x16x32_bf16 v[60:63], v[72:75], v[168:171], v[60:63]
	v_mfma_f32_16x16x32_bf16 v[56:59], v[112:115], v[168:171], v[56:59]
	v_mfma_f32_16x16x32_bf16 v[44:47], v[72:75], v[188:191], v[44:47]
	v_mfma_f32_16x16x32_bf16 v[40:43], v[112:115], v[188:191], v[40:43]
	v_mfma_f32_16x16x32_bf16 v[28:31], v[72:75], v[196:199], v[28:31]
	v_mfma_f32_16x16x32_bf16 v[24:27], v[112:115], v[196:199], v[24:27]
	v_mfma_f32_16x16x32_bf16 v[12:15], v[72:75], v[204:207], v[12:15]
	v_mfma_f32_16x16x32_bf16 v[8:11], v[112:115], v[204:207], v[8:11]
	v_mfma_f32_16x16x32_bf16 v[60:63], v[92:95], v[184:187], v[60:63]
	v_mfma_f32_16x16x32_bf16 v[56:59], v[132:135], v[184:187], v[56:59]
	v_mfma_f32_16x16x32_bf16 v[44:47], v[92:95], v[192:195], v[44:47]
	v_mfma_f32_16x16x32_bf16 v[40:43], v[132:135], v[192:195], v[40:43]
	v_mfma_f32_16x16x32_bf16 v[28:31], v[92:95], v[200:203], v[28:31]
	v_mfma_f32_16x16x32_bf16 v[24:27], v[132:135], v[200:203], v[24:27]
	v_mfma_f32_16x16x32_bf16 v[12:15], v[92:95], v[208:211], v[12:15]
	v_mfma_f32_16x16x32_bf16 v[8:11], v[132:135], v[208:211], v[8:11]
	s_setprio 0
	s_setprio 1
	v_mfma_f32_16x16x32_bf16 v[52:55], v[144:147], v[168:171], v[52:55]
	v_mfma_f32_16x16x32_bf16 v[48:51], v[152:155], v[168:171], v[48:51]
	v_mfma_f32_16x16x32_bf16 v[36:39], v[144:147], v[188:191], v[36:39]
	v_mfma_f32_16x16x32_bf16 v[32:35], v[152:155], v[188:191], v[32:35]
	v_mfma_f32_16x16x32_bf16 v[20:23], v[144:147], v[196:199], v[20:23]
	v_mfma_f32_16x16x32_bf16 v[16:19], v[152:155], v[196:199], v[16:19]
	v_mfma_f32_16x16x32_bf16 v[4:7], v[144:147], v[204:207], v[4:7]
	v_mfma_f32_16x16x32_bf16 v[0:3], v[152:155], v[204:207], v[0:3]
	v_mfma_f32_16x16x32_bf16 v[52:55], v[148:151], v[184:187], v[52:55]
	v_mfma_f32_16x16x32_bf16 v[48:51], v[164:167], v[184:187], v[48:51]
	v_mfma_f32_16x16x32_bf16 v[36:39], v[148:151], v[192:195], v[36:39]
	v_mfma_f32_16x16x32_bf16 v[32:35], v[164:167], v[192:195], v[32:35]
	s_setprio 2
	s_barrier
	v_mfma_f32_16x16x32_bf16 v[20:23], v[148:151], v[200:203], v[20:23]
	v_mfma_f32_16x16x32_bf16 v[16:19], v[164:167], v[200:203], v[16:19]
	v_mfma_f32_16x16x32_bf16 v[4:7], v[148:151], v[208:211], v[4:7]
	v_mfma_f32_16x16x32_bf16 v[0:3], v[164:167], v[208:211], v[0:3]
	s_setprio 0
	s_andn2_b64 vcc, exec, s[30:31]
	s_mov_b64 s[34:35], -1
	s_mov_b64 s[30:31], 0
	s_mov_b64 s[36:37], 0x100
	s_cbranch_vccz .LBB13_1520
	s_and_b64 vcc, exec, s[14:15]
	s_cbranch_vccz .LBB13_1523
	s_barrier

;     __device__ float mid(int row) const { return rg(row) / ra(row); }
;     __device__ __forceinline__ bool next(int i, Unit& u) const { return map(rank + i * nloc, u); }
; #define PG8_LDA(dst, b, h) do { _Pragma("unroll") for (int m = 0; m < 4; ++m) _Pragma("unroll") for (int k = 0; k < 2; ++k) dst[m][k] = *(const PG8_LAS bf16x8*)(lds + PG8_SA(b, h) + aoff + m * 2048 + k * 1024); } while (0)
; template <class Epi, class Sched, bool ALIGN_EPI = false, bool SP2 = false>
; __device__ __forceinline__ void gemm_phase(PG8_LAS unsigned char* lds, const Gemm g, const Sched& S, const Epi& E, int wid0) {
;     ...
;         const bool has_next = S.next(ui + 1, nxt); nxt.ui = ui + 1;
;         if constexpr (Epi::HAS_PRE) E.pre_finish(lds, cur, tid, pq0, pq1, pq2);
;         const char* nA = has_next ? (const char*)g.A + (size_t)nxt.pm * tstepA : cA; const char* nB = has_next ? (const char*)g.Bt + (size_t)nxt.pn * tstep : cB;
; #pragma nounroll
;         for (int t = 0; t < nt; t += 2) {
;             const bool last = (t == nt - 2);
;             const char* a1 = cA + (size_t)(t + 1) * kstep;
;             const char* a2 = last ? nA : cA + (size_t)(t + 2) * kstep; const char* b2 = last ? nB : cB + (size_t)(t + 2) * kstep;
;             const char* a3 = a2 + kstep; const char* b3 = b2 + kstep;
;             if (last && has_next) S.a_ready(nxt);
;             if constexpr (Epi::HAS_MID) { if (t == Epi::MID_T) E.mid(acc, cur, wr, fr); }
;             unsigned vA_[2] = {voffA[0], voffA[1]}, vB_[2] = {voffB[0], voffB[1]};
;             asm volatile("" : "+v"(vA_[0]), "+v"(vA_[1]), "+v"(vB_[0]), "+v"(vB_[1]));
;             if constexpr (SP2) {
;             PG8_LDB(B0, 0, 0); PG8_LDB(B1, 0, 1); PG8_SCHED; PG8_LDA(At, 0, 0); PG8_STAGE(PG8_SA(1, 1), a1 + hstepA, vA_);
;             PG8_WAIT_V(8); PG8_WAIT_L(0); PG8_BAR; PG8_MMA(0, 0, At, B0); PG8_MMA(0, 1, At, B1); PG8_BAR; PG8_SCHED;
;             PG8_LDA(At, 0, 1); PG8_STAGE(PG8_SB(0, 0), b2, vB_); PG8_STAGE(PG8_SB(0, 1), b2 + hstep, vB_); PG8_STAGE(PG8_SA(0, 0), a2, vA_);
;             PG8_WAIT_V(8); PG8_WAIT_L(0); PG8_BAR; PG8_MMA(1, 0, At, B0); PG8_MMA(1, 1, At, B1); PG8_BAR; PG8_SCHED;
;             PG8_LDB(B0, 1, 0); PG8_LDB(B1, 1, 1); PG8_SCHED; PG8_LDA(At, 1, 0); PG8_STAGE(PG8_SA(0, 1), a2 + hstepA, vA_);
;             PG8_WAIT_V(8); PG8_WAIT_L(0); PG8_BAR; PG8_MMA(0, 0, At, B0); PG8_MMA(0, 1, At, B1); PG8_BAR; PG8_SCHED;
.LBB13_1920:
	v_mov_b32_e32 v9, v172
	v_mov_b32_e32 v170, v174
	v_mov_b32_e32 v171, v176
	v_mov_b32_e32 v182, v178
	v_add_u32_e32 v10, s62, v173
	ds_read_b128 v[142:145], v10
	ds_read_b128 v[146:149], v10 offset:1024
	ds_read_b128 v[150:153], v10 offset:2048
	ds_read_b128 v[154:157], v10 offset:3072
	v_add_u32_e32 v10, s63, v173
	s_add_u32 s6, s40, 0x100
	ds_read_b128 v[158:161], v10
	ds_read_b128 v[162:165], v10 offset:1024
	ds_read_b128 v[166:169], v10 offset:2048
	ds_read_b128 v[184:187], v10 offset:3072
	s_addc_u32 s7, s41, 0
	s_cmp_eq_u32 s68, 12
	s_cselect_b32 s48, s31, s6
	s_cselect_b32 s49, s27, s7
	s_cselect_b32 s43, s29, s67
	s_cselect_b32 s42, s65, s66
	s_add_u32 s44, s48, 0x80
	s_addc_u32 s45, s49, 0
	s_add_u32 s46, s42, 0x80
	s_addc_u32 s47, s43, 0
	s_add_u32 s40, s40, 0x80080
	s_addc_u32 s41, s41, 0
	s_add_i32 m0, s13, 0xc000
	ds_read_b128 v[188:191], v183
	ds_read_b128 v[192:195], v183 offset:1024
	ds_read_b128 v[196:199], v183 offset:2048
	ds_read_b128 v[200:203], v183 offset:3072
	ds_read_b128 v[204:207], v183 offset:4096
	ds_read_b128 v[208:211], v183 offset:5120
	ds_read_b128 v[212:215], v183 offset:6144
	ds_read_b128 v[216:219], v183 offset:7168
	s_nop 0
	global_load_lds_dwordx4 v9, s[40:41]
	s_add_i32 m0, s13, 0xe000
	s_nop 0
	global_load_lds_dwordx4 v171, s[40:41]
	s_waitcnt vmcnt(8)
	s_waitcnt lgkmcnt(0)
	s_barrier
	s_setprio 1
	s_waitcnt lgkmcnt(0)
	v_mfma_f32_16x16x32_bf16 v[136:139], v[142:145], v[188:191], v[136:139]
	v_mfma_f32_16x16x32_bf16 v[132:135], v[150:153], v[188:191], v[132:135]
	v_mfma_f32_16x16x32_bf16 v[128:131], v[142:145], v[196:199], v[128:131]
	v_mfma_f32_16x16x32_bf16 v[124:127], v[150:153], v[196:199], v[124:127]
	v_mfma_f32_16x16x32_bf16 v[120:123], v[142:145], v[204:207], v[120:123]
	v_mfma_f32_16x16x32_bf16 v[116:119], v[150:153], v[204:207], v[116:119]
	v_mfma_f32_16x16x32_bf16 v[112:115], v[142:145], v[212:215], v[112:115]
	v_mfma_f32_16x16x32_bf16 v[108:111], v[150:153], v[212:215], v[108:111]
	v_mfma_f32_16x16x32_bf16 v[136:139], v[146:149], v[192:195], v[136:139]
	v_mfma_f32_16x16x32_bf16 v[132:135], v[154:157], v[192:195], v[132:135]
	v_mfma_f32_16x16x32_bf16 v[128:131], v[146:149], v[200:203], v[128:131]
	v_mfma_f32_16x16x32_bf16 v[124:127], v[154:157], v[200:203], v[124:127]
	v_mfma_f32_16x16x32_bf16 v[120:123], v[146:149], v[208:211], v[120:123]
	v_mfma_f32_16x16x32_bf16 v[116:119], v[154:157], v[208:211], v[116:119]
	v_mfma_f32_16x16x32_bf16 v[112:115], v[146:149], v[216:219], v[112:115]
	v_mfma_f32_16x16x32_bf16 v[108:111], v[154:157], v[216:219], v[108:111]
	s_setprio 0
	s_setprio 1
	v_mfma_f32_16x16x32_bf16 v[72:75], v[158:161], v[188:191], v[72:75]
	v_mfma_f32_16x16x32_bf16 v[68:71], v[166:169], v[188:191], v[68:71]
	v_mfma_f32_16x16x32_bf16 v[64:67], v[158:161], v[196:199], v[64:67]
	v_mfma_f32_16x16x32_bf16 v[60:63], v[166:169], v[196:199], v[60:63]
	v_mfma_f32_16x16x32_bf16 v[56:59], v[158:161], v[204:207], v[56:59]
	v_mfma_f32_16x16x32_bf16 v[52:55], v[166:169], v[204:207], v[52:55]
	v_mfma_f32_16x16x32_bf16 v[48:51], v[158:161], v[212:215], v[48:51]
	v_mfma_f32_16x16x32_bf16 v[44:47], v[166:169], v[212:215], v[44:47]
	v_mfma_f32_16x16x32_bf16 v[72:75], v[162:165], v[192:195], v[72:75]
	v_mfma_f32_16x16x32_bf16 v[68:71], v[184:187], v[192:195], v[68:71]
	v_mfma_f32_16x16x32_bf16 v[64:67], v[162:165], v[200:203], v[64:67]
	v_mfma_f32_16x16x32_bf16 v[60:63], v[184:187], v[200:203], v[60:63]
	s_setprio 2
	s_barrier
	v_mfma_f32_16x16x32_bf16 v[56:59], v[162:165], v[208:211], v[56:59]
	v_mfma_f32_16x16x32_bf16 v[52:55], v[184:187], v[208:211], v[52:55]
	v_mfma_f32_16x16x32_bf16 v[48:51], v[162:165], v[216:219], v[48:51]
	v_mfma_f32_16x16x32_bf16 v[44:47], v[184:187], v[216:219], v[44:47]
	s_setprio 0
	s_add_i32 s69, s62, s25
	s_mov_b64 s[40:41], s[42:43]
	s_mov_b32 m0, s69
	ds_read_b128 v[188:191], v183 offset:16384
	ds_read_b128 v[192:195], v183 offset:17408
	ds_read_b128 v[196:199], v183 offset:18432
	ds_read_b128 v[200:203], v183 offset:19456
	ds_read_b128 v[204:207], v183 offset:20480
	ds_read_b128 v[208:211], v183 offset:21504
	ds_read_b128 v[212:215], v183 offset:22528
	ds_read_b128 v[216:219], v183 offset:23552
	s_nop 0
	global_load_lds_dwordx4 v170, s[40:41]
	s_add_i32 m0, s69, 0x2000
	s_nop 0
	global_load_lds_dwordx4 v182, s[40:41]
	s_add_u32 s40, s42, 0x40000
	s_addc_u32 s41, s43, 0
	s_add_i32 s69, s63, s25
	s_mov_b32 m0, s69
	s_nop 0
	global_load_lds_dwordx4 v170, s[40:41]
	s_add_i32 m0, s69, 0x2000
	s_nop 0
	global_load_lds_dwordx4 v182, s[40:41]
	s_mov_b64 s[40:41], s[48:49]
	s_mov_b32 m0, s13
	s_nop 0
	global_load_lds_dwordx4 v9, s[40:41]
	s_mov_b32 m0, s51
	s_nop 0
	global_load_lds_dwordx4 v171, s[40:41]
	s_waitcnt vmcnt(8)
	s_waitcnt lgkmcnt(0)
	s_barrier
; #define PG8_STAGE(bufoff, gbase, voff) do { const char* gb_ = (const char*)(gbase); asm volatile("" : "+s"(gb_));     \
;         _Pragma("unroll") for (int _i = 0; _i < 2; ++_i) \
;         __builtin_amdgcn_global_load_lds((const unsigned*)(gb_ + (voff)[_i]), (PG8_LAS unsigned*)(lds + (bufoff) + ldsw + _i * 8192), 16, 0, 0); } while (0)
; #define PG8_LDA(dst, b, h) do { _Pragma("unroll") for (int m = 0; m < 4; ++m) _Pragma("unroll") for (int k = 0; k < 2; ++k) dst[m][k] = *(const PG8_LAS bf16x8*)(lds + PG8_SA(b, h) + aoff + m * 2048 + k * 1024); } while (0)
; #define PG8_LDB(dst, b, h) do { _Pragma("unroll") for (int n = 0; n < 2; ++n) _Pragma("unroll") for (int k = 0; k < 2; ++k) dst[n][k] = *(const PG8_LAS bf16x8*)(lds + PG8_SB(b, h) + boff + n * 2048 + k * 1024); } while (0)
; #define PG8_MMA(ai, bj, At, Bt) do { __builtin_amdgcn_s_setprio(1); _Pragma("unroll") for (int m = 0; m < 4; ++m) _Pragma("unroll") for (int n = 0; n < 2; ++n) _Pragma("unroll") for (int k = 0; k < 2; ++k) \
;         acc[ai][bj][m][n] = __builtin_amdgcn_mfma_f32_16x16x32_bf16(Bt[n][k], At[m][k], acc[ai][bj][m][n], 0, 0, 0); __builtin_amdgcn_s_setprio(0); } while (0)
; #define PG8_WAIT_V(n) asm volatile("s_waitcnt vmcnt(" #n ")" ::: "memory")
; #define PG8_WAIT_L(n) asm volatile("s_waitcnt lgkmcnt(" #n ")" ::: "memory")
; #define PG8_BAR __builtin_amdgcn_s_barrier()
; #define PG8_SCHED __builtin_amdgcn_sched_barrier(0)
; template <class Epi, class Sched, bool ALIGN_EPI = false, bool SP2 = false>
; __device__ __forceinline__ void gemm_phase(PG8_LAS unsigned char* lds, const Gemm g, const Sched& S, const Epi& E, int wid0) {
;     ...
;             PG8_WAIT_V(8); PG8_WAIT_L(0); PG8_BAR; PG8_MMA(0, 0, At, B0); PG8_MMA(0, 1, At, B1); PG8_BAR; PG8_SCHED;
;             PG8_LDA(At, 0, 1); PG8_STAGE(PG8_SB(0, 0), b2, vB_); PG8_STAGE(PG8_SB(0, 1), b2 + hstep, vB_); PG8_STAGE(PG8_SA(0, 0), a2, vA_);
;             PG8_WAIT_V(8); PG8_WAIT_L(0); PG8_BAR; PG8_MMA(1, 0, At, B0); PG8_MMA(1, 1, At, B1); PG8_BAR; PG8_SCHED;
;             PG8_LDB(B0, 1, 0); PG8_LDB(B1, 1, 1); PG8_SCHED; PG8_LDA(At, 1, 0); PG8_STAGE(PG8_SA(0, 1), a2 + hstepA, vA_);
;             PG8_WAIT_V(8); PG8_WAIT_L(0); PG8_BAR; PG8_MMA(0, 0, At, B0); PG8_MMA(0, 1, At, B1); PG8_BAR; PG8_SCHED;
	s_setprio 1
	s_waitcnt lgkmcnt(0)
	v_mfma_f32_16x16x32_bf16 v[104:107], v[142:145], v[188:191], v[104:107]
	v_mfma_f32_16x16x32_bf16 v[100:103], v[150:153], v[188:191], v[100:103]
	v_mfma_f32_16x16x32_bf16 v[96:99], v[142:145], v[196:199], v[96:99]
	v_mfma_f32_16x16x32_bf16 v[92:95], v[150:153], v[196:199], v[92:95]
	v_mfma_f32_16x16x32_bf16 v[88:91], v[142:145], v[204:207], v[88:91]
	v_mfma_f32_16x16x32_bf16 v[84:87], v[150:153], v[204:207], v[84:87]
	v_mfma_f32_16x16x32_bf16 v[80:83], v[142:145], v[212:215], v[80:83]
	v_mfma_f32_16x16x32_bf16 v[76:79], v[150:153], v[212:215], v[76:79]
	v_mfma_f32_16x16x32_bf16 v[104:107], v[146:149], v[192:195], v[104:107]
	v_mfma_f32_16x16x32_bf16 v[100:103], v[154:157], v[192:195], v[100:103]
	v_mfma_f32_16x16x32_bf16 v[96:99], v[146:149], v[200:203], v[96:99]
	v_mfma_f32_16x16x32_bf16 v[92:95], v[154:157], v[200:203], v[92:95]
	v_mfma_f32_16x16x32_bf16 v[88:91], v[146:149], v[208:211], v[88:91]
	v_mfma_f32_16x16x32_bf16 v[84:87], v[154:157], v[208:211], v[84:87]
	v_mfma_f32_16x16x32_bf16 v[80:83], v[146:149], v[216:219], v[80:83]
	v_mfma_f32_16x16x32_bf16 v[76:79], v[154:157], v[216:219], v[76:79]
	s_setprio 0
	s_setprio 1
	v_mfma_f32_16x16x32_bf16 v[40:43], v[158:161], v[188:191], v[40:43]
	v_mfma_f32_16x16x32_bf16 v[36:39], v[166:169], v[188:191], v[36:39]
	v_mfma_f32_16x16x32_bf16 v[32:35], v[158:161], v[196:199], v[32:35]
	v_mfma_f32_16x16x32_bf16 v[28:31], v[166:169], v[196:199], v[28:31]
	v_mfma_f32_16x16x32_bf16 v[24:27], v[158:161], v[204:207], v[24:27]
	v_mfma_f32_16x16x32_bf16 v[20:23], v[166:169], v[204:207], v[20:23]
	v_mfma_f32_16x16x32_bf16 v[16:19], v[158:161], v[212:215], v[16:19]
	v_mfma_f32_16x16x32_bf16 v[10:13], v[166:169], v[212:215], v[12:15]
	v_mfma_f32_16x16x32_bf16 v[40:43], v[162:165], v[192:195], v[40:43]
	v_mfma_f32_16x16x32_bf16 v[36:39], v[184:187], v[192:195], v[36:39]
	v_mfma_f32_16x16x32_bf16 v[32:35], v[162:165], v[200:203], v[32:35]
	v_mfma_f32_16x16x32_bf16 v[28:31], v[184:187], v[200:203], v[28:31]
	s_setprio 2
	s_barrier
	v_mfma_f32_16x16x32_bf16 v[24:27], v[162:165], v[208:211], v[24:27]
	v_mfma_f32_16x16x32_bf16 v[20:23], v[184:187], v[208:211], v[20:23]
	v_mfma_f32_16x16x32_bf16 v[16:19], v[162:165], v[216:219], v[16:19]
	v_mfma_f32_16x16x32_bf16 v[10:13], v[184:187], v[216:219], v[10:13]
	s_setprio 0
	s_add_i32 s69, 0, 0x18000
	v_add_u32_e32 v14, s69, v173
	s_add_i32 s70, 0, 0x1c000
	ds_read_b128 v[142:145], v14
	ds_read_b128 v[146:149], v14 offset:1024
	ds_read_b128 v[150:153], v14 offset:2048
	ds_read_b128 v[154:157], v14 offset:3072
	v_add_u32_e32 v14, s70, v173
	ds_read_b128 v[158:161], v14
	ds_read_b128 v[162:165], v14 offset:1024
	ds_read_b128 v[166:169], v14 offset:2048
	ds_read_b128 v[184:187], v14 offset:3072
	s_add_u32 s40, s48, 0x80000
	s_addc_u32 s41, s49, 0
	s_mov_b32 m0, s52
	ds_read_b128 v[188:191], v183 offset:32768
	ds_read_b128 v[192:195], v183 offset:33792
	ds_read_b128 v[196:199], v183 offset:34816
	ds_read_b128 v[200:203], v183 offset:35840
	ds_read_b128 v[204:207], v183 offset:36864
	ds_read_b128 v[208:211], v183 offset:37888
	ds_read_b128 v[212:215], v183 offset:38912
	ds_read_b128 v[216:219], v183 offset:39936
	s_nop 0
	global_load_lds_dwordx4 v9, s[40:41]
	s_mov_b32 m0, s53
	s_nop 0
	global_load_lds_dwordx4 v171, s[40:41]
	s_waitcnt vmcnt(8)
	s_waitcnt lgkmcnt(0)
	s_barrier
	s_setprio 1
	s_waitcnt lgkmcnt(0)
	v_mfma_f32_16x16x32_bf16 v[136:139], v[142:145], v[188:191], v[136:139]
	v_mfma_f32_16x16x32_bf16 v[132:135], v[150:153], v[188:191], v[132:135]
	v_mfma_f32_16x16x32_bf16 v[128:131], v[142:145], v[196:199], v[128:131]
	v_mfma_f32_16x16x32_bf16 v[124:127], v[150:153], v[196:199], v[124:127]
	v_mfma_f32_16x16x32_bf16 v[120:123], v[142:145], v[204:207], v[120:123]
	v_mfma_f32_16x16x32_bf16 v[116:119], v[150:153], v[204:207], v[116:119]
	v_mfma_f32_16x16x32_bf16 v[112:115], v[142:145], v[212:215], v[112:115]
	v_mfma_f32_16x16x32_bf16 v[108:111], v[150:153], v[212:215], v[108:111]
	v_mfma_f32_16x16x32_bf16 v[136:139], v[146:149], v[192:195], v[136:139]
	v_mfma_f32_16x16x32_bf16 v[132:135], v[154:157], v[192:195], v[132:135]
	v_mfma_f32_16x16x32_bf16 v[128:131], v[146:149], v[200:203], v[128:131]
	v_mfma_f32_16x16x32_bf16 v[124:127], v[154:157], v[200:203], v[124:127]
	v_mfma_f32_16x16x32_bf16 v[120:123], v[146:149], v[208:211], v[120:123]
	v_mfma_f32_16x16x32_bf16 v[116:119], v[154:157], v[208:211], v[116:119]
	v_mfma_f32_16x16x32_bf16 v[112:115], v[146:149], v[216:219], v[112:115]
	v_mfma_f32_16x16x32_bf16 v[108:111], v[154:157], v[216:219], v[108:111]
	s_setprio 0
	s_setprio 1
	v_mfma_f32_16x16x32_bf16 v[72:75], v[158:161], v[188:191], v[72:75]
	v_mfma_f32_16x16x32_bf16 v[68:71], v[166:169], v[188:191], v[68:71]
	v_mfma_f32_16x16x32_bf16 v[64:67], v[158:161], v[196:199], v[64:67]
	v_mfma_f32_16x16x32_bf16 v[60:63], v[166:169], v[196:199], v[60:63]
	v_mfma_f32_16x16x32_bf16 v[56:59], v[158:161], v[204:207], v[56:59]
	v_mfma_f32_16x16x32_bf16 v[52:55], v[166:169], v[204:207], v[52:55]
	v_mfma_f32_16x16x32_bf16 v[48:51], v[158:161], v[212:215], v[48:51]
	v_mfma_f32_16x16x32_bf16 v[44:47], v[166:169], v[212:215], v[44:47]
	v_mfma_f32_16x16x32_bf16 v[72:75], v[162:165], v[192:195], v[72:75]
	v_mfma_f32_16x16x32_bf16 v[68:71], v[184:187], v[192:195], v[68:71]
	v_mfma_f32_16x16x32_bf16 v[64:67], v[162:165], v[200:203], v[64:67]
	v_mfma_f32_16x16x32_bf16 v[60:63], v[184:187], v[200:203], v[60:63]
	s_setprio 2
	s_barrier
; #define PG8_STAGE(bufoff, gbase, voff) do { const char* gb_ = (const char*)(gbase); asm volatile("" : "+s"(gb_));     \
;         _Pragma("unroll") for (int _i = 0; _i < 2; ++_i) \
;         __builtin_amdgcn_global_load_lds((const unsigned*)(gb_ + (voff)[_i]), (PG8_LAS unsigned*)(lds + (bufoff) + ldsw + _i * 8192), 16, 0, 0); } while (0)
; #define PG8_LDA(dst, b, h) do { _Pragma("unroll") for (int m = 0; m < 4; ++m) _Pragma("unroll") for (int k = 0; k < 2; ++k) dst[m][k] = *(const PG8_LAS bf16x8*)(lds + PG8_SA(b, h) + aoff + m * 2048 + k * 1024); } while (0)
; #define PG8_MMA(ai, bj, At, Bt) do { __builtin_amdgcn_s_setprio(1); _Pragma("unroll") for (int m = 0; m < 4; ++m) _Pragma("unroll") for (int n = 0; n < 2; ++n) _Pragma("unroll") for (int k = 0; k < 2; ++k) \
;         acc[ai][bj][m][n] = __builtin_amdgcn_mfma_f32_16x16x32_bf16(Bt[n][k], At[m][k], acc[ai][bj][m][n], 0, 0, 0); __builtin_amdgcn_s_setprio(0); } while (0)
; #define PG8_WAIT_V(n) asm volatile("s_waitcnt vmcnt(" #n ")" ::: "memory")
; #define PG8_WAIT_L(n) asm volatile("s_waitcnt lgkmcnt(" #n ")" ::: "memory")
; #define PG8_BAR __builtin_amdgcn_s_barrier()
; #define PG8_SCHED __builtin_amdgcn_sched_barrier(0)
; template <class Epi, class Sched, bool ALIGN_EPI = false, bool SP2 = false>
; __device__ __forceinline__ void gemm_phase(PG8_LAS unsigned char* lds, const Gemm g, const Sched& S, const Epi& E, int wid0) {
;     ...
;             PG8_WAIT_V(8); PG8_WAIT_L(0); PG8_BAR; PG8_MMA(0, 0, At, B0); PG8_MMA(0, 1, At, B1); PG8_BAR; PG8_SCHED;
;             PG8_LDA(At, 1, 1); PG8_STAGE(PG8_SB(1, 0), b3, vB_); PG8_STAGE(PG8_SB(1, 1), b3 + hstep, vB_); PG8_STAGE(PG8_SA(1, 0), a3, vA_);
;             PG8_WAIT_V(8); PG8_WAIT_L(0); PG8_BAR; PG8_MMA(1, 0, At, B0); PG8_MMA(1, 1, At, B1); PG8_BAR; PG8_SCHED;
	v_mfma_f32_16x16x32_bf16 v[56:59], v[162:165], v[208:211], v[56:59]
	v_mfma_f32_16x16x32_bf16 v[52:55], v[184:187], v[208:211], v[52:55]
	v_mfma_f32_16x16x32_bf16 v[48:51], v[162:165], v[216:219], v[48:51]
	v_mfma_f32_16x16x32_bf16 v[44:47], v[184:187], v[216:219], v[44:47]
	s_setprio 0
	s_add_i32 s40, s69, s25
	s_mov_b32 m0, s40
	ds_read_b128 v[188:191], v183 offset:49152
	ds_read_b128 v[192:195], v183 offset:50176
	ds_read_b128 v[196:199], v183 offset:51200
	ds_read_b128 v[200:203], v183 offset:52224
	ds_read_b128 v[204:207], v183 offset:53248
	ds_read_b128 v[208:211], v183 offset:54272
	ds_read_b128 v[212:215], v183 offset:55296
	ds_read_b128 v[216:219], v183 offset:56320
	s_nop 0
	global_load_lds_dwordx4 v170, s[46:47]
	s_add_i32 m0, s40, 0x2000
	s_add_u32 s40, s42, 0x40080
	s_addc_u32 s41, s43, 0
	s_add_i32 s42, s70, s25
	global_load_lds_dwordx4 v182, s[46:47]
	s_mov_b32 m0, s42
	s_nop 0
	global_load_lds_dwordx4 v170, s[40:41]
	s_add_i32 m0, s42, 0x2000
	s_nop 0
	global_load_lds_dwordx4 v182, s[40:41]
	s_mov_b32 m0, s57
	s_nop 0
	global_load_lds_dwordx4 v9, s[44:45]
	s_mov_b32 m0, s58
	s_nop 0
	global_load_lds_dwordx4 v171, s[44:45]
	s_waitcnt vmcnt(8)
	s_waitcnt lgkmcnt(0)
	s_barrier
	s_setprio 1
	s_waitcnt lgkmcnt(0)
	v_mfma_f32_16x16x32_bf16 v[104:107], v[142:145], v[188:191], v[104:107]
	v_mfma_f32_16x16x32_bf16 v[100:103], v[150:153], v[188:191], v[100:103]
	v_mfma_f32_16x16x32_bf16 v[96:99], v[142:145], v[196:199], v[96:99]
	v_mfma_f32_16x16x32_bf16 v[92:95], v[150:153], v[196:199], v[92:95]
	v_mfma_f32_16x16x32_bf16 v[88:91], v[142:145], v[204:207], v[88:91]
	v_mfma_f32_16x16x32_bf16 v[84:87], v[150:153], v[204:207], v[84:87]
	v_mfma_f32_16x16x32_bf16 v[80:83], v[142:145], v[212:215], v[80:83]
	v_mfma_f32_16x16x32_bf16 v[76:79], v[150:153], v[212:215], v[76:79]
	v_mfma_f32_16x16x32_bf16 v[104:107], v[146:149], v[192:195], v[104:107]
	v_mfma_f32_16x16x32_bf16 v[100:103], v[154:157], v[192:195], v[100:103]
	v_mfma_f32_16x16x32_bf16 v[96:99], v[146:149], v[200:203], v[96:99]
	v_mfma_f32_16x16x32_bf16 v[92:95], v[154:157], v[200:203], v[92:95]
	v_mfma_f32_16x16x32_bf16 v[88:91], v[146:149], v[208:211], v[88:91]
	v_mfma_f32_16x16x32_bf16 v[84:87], v[154:157], v[208:211], v[84:87]
	v_mfma_f32_16x16x32_bf16 v[80:83], v[146:149], v[216:219], v[80:83]
	v_mfma_f32_16x16x32_bf16 v[76:79], v[154:157], v[216:219], v[76:79]
	s_setprio 0
	s_setprio 1
	v_mfma_f32_16x16x32_bf16 v[40:43], v[158:161], v[188:191], v[40:43]
	v_mfma_f32_16x16x32_bf16 v[36:39], v[166:169], v[188:191], v[36:39]
	v_mfma_f32_16x16x32_bf16 v[32:35], v[158:161], v[196:199], v[32:35]
	v_mfma_f32_16x16x32_bf16 v[28:31], v[166:169], v[196:199], v[28:31]
	v_mfma_f32_16x16x32_bf16 v[24:27], v[158:161], v[204:207], v[24:27]
	v_mfma_f32_16x16x32_bf16 v[20:23], v[166:169], v[204:207], v[20:23]
	v_mfma_f32_16x16x32_bf16 v[14:17], v[158:161], v[212:215], v[16:19]
	v_mfma_f32_16x16x32_bf16 v[10:13], v[166:169], v[212:215], v[10:13]
	v_mfma_f32_16x16x32_bf16 v[40:43], v[162:165], v[192:195], v[40:43]
	v_mfma_f32_16x16x32_bf16 v[36:39], v[184:187], v[192:195], v[36:39]
	v_mfma_f32_16x16x32_bf16 v[32:35], v[162:165], v[200:203], v[32:35]
	v_mfma_f32_16x16x32_bf16 v[28:31], v[184:187], v[200:203], v[28:31]
	s_setprio 2
	s_barrier
	v_mfma_f32_16x16x32_bf16 v[24:27], v[162:165], v[208:211], v[24:27]
	v_mfma_f32_16x16x32_bf16 v[20:23], v[184:187], v[208:211], v[20:23]
	v_mfma_f32_16x16x32_bf16 v[16:19], v[162:165], v[216:219], v[14:17]
	v_mfma_f32_16x16x32_bf16 v[12:15], v[184:187], v[216:219], v[10:13]
	s_setprio 0
	s_add_i32 s68, s68, 2
	s_add_u32 s66, s66, 0x100
	s_addc_u32 s67, s67, 0
	s_cmp_gt_u32 s68, 13
	s_cbranch_scc1 .LBB13_1922
	s_mov_b64 s[40:41], s[6:7]
	s_cmp_lg_u32 s68, 6
	s_cbranch_scc0 .LBB13_1919
	s_branch .LBB13_1920

;     __device__ float mid(int row) const { return rg(row) / ra(row); }
; #define PG8_STAGE(bufoff, gbase, voff) do { const char* gb_ = (const char*)(gbase); asm volatile("" : "+s"(gb_));     \
;         _Pragma("unroll") for (int _i = 0; _i < 2; ++_i) \
;         __builtin_amdgcn_global_load_lds((const unsigned*)(gb_ + (voff)[_i]), (PG8_LAS unsigned*)(lds + (bufoff) + ldsw + _i * 8192), 16, 0, 0); } while (0)
; #define PG8_LDA(dst, b, h) do { _Pragma("unroll") for (int m = 0; m < 4; ++m) _Pragma("unroll") for (int k = 0; k < 2; ++k) dst[m][k] = *(const PG8_LAS bf16x8*)(lds + PG8_SA(b, h) + aoff + m * 2048 + k * 1024); } while (0)
; #define PG8_LDB(dst, b, h) do { _Pragma("unroll") for (int n = 0; n < 2; ++n) _Pragma("unroll") for (int k = 0; k < 2; ++k) dst[n][k] = *(const PG8_LAS bf16x8*)(lds + PG8_SB(b, h) + boff + n * 2048 + k * 1024); } while (0)
; #define PG8_WAIT_V(n) asm volatile("s_waitcnt vmcnt(" #n ")" ::: "memory")
; template <class Epi, class Sched, bool ALIGN_EPI = false, bool SP2 = false>
; __device__ __forceinline__ void gemm_phase(PG8_LAS unsigned char* lds, const Gemm g, const Sched& S, const Epi& E, int wid0) {
;     ...
;         for (int t = 0; t < nt; t += 2) {
;             const bool last = (t == nt - 2);
;             const char* a1 = cA + (size_t)(t + 1) * kstep;
;             const char* a2 = last ? nA : cA + (size_t)(t + 2) * kstep; const char* b2 = last ? nB : cB + (size_t)(t + 2) * kstep;
;             const char* a3 = a2 + kstep; const char* b3 = b2 + kstep;
;             if (last && has_next) S.a_ready(nxt);
;             if constexpr (Epi::HAS_MID) { if (t == Epi::MID_T) E.mid(acc, cur, wr, fr); }
;             unsigned vA_[2] = {voffA[0], voffA[1]}, vB_[2] = {voffB[0], voffB[1]};
;             asm volatile("" : "+v"(vA_[0]), "+v"(vA_[1]), "+v"(vB_[0]), "+v"(vB_[1]));
;             if constexpr (SP2) {
;             PG8_LDB(B0, 0, 0); PG8_LDB(B1, 0, 1); PG8_SCHED; PG8_LDA(At, 0, 0); PG8_STAGE(PG8_SA(1, 1), a1 + hstepA, vA_);
;             PG8_WAIT_V(8); PG8_WAIT_L(0); PG8_BAR; PG8_MMA(0, 0, At, B0); PG8_MMA(0, 1, At, B1); PG8_BAR; PG8_SCHED;
;             PG8_LDA(At, 0, 1); PG8_STAGE(PG8_SB(0, 0), b2, vB_); PG8_STAGE(PG8_SB(0, 1), b2 + hstep, vB_); PG8_STAGE(PG8_SA(0, 0), a2, vA_);
;             PG8_WAIT_V(8); PG8_WAIT_L(0); PG8_BAR; PG8_MMA(1, 0, At, B0); PG8_MMA(1, 1, At, B1); PG8_BAR; PG8_SCHED;
.LBB13_2163:
	v_mov_b32_e32 v202, v150
	v_mov_b32_e32 v203, v152
	v_mov_b32_e32 v204, v154
	v_mov_b32_e32 v205, v148
	ds_read_b128 v[128:131], v153
	ds_read_b128 v[132:135], v153 offset:1024
	ds_read_b128 v[136:139], v153 offset:2048
	ds_read_b128 v[140:143], v153 offset:3072
	ds_read_b128 v[144:147], v155
	ds_read_b128 v[158:161], v155 offset:1024
	ds_read_b128 v[162:165], v155 offset:2048
	ds_read_b128 v[166:169], v155 offset:3072
	s_add_u32 s26, s24, 0x100
	s_addc_u32 s27, s25, 0
	s_cmp_eq_u32 s53, 60
	s_cselect_b32 s34, s49, s26
	s_cselect_b32 s35, s11, s27
	s_cselect_b32 s30, s50, s51
	s_cselect_b32 s31, s13, s52
	s_add_u32 s28, s34, 0x80
	s_addc_u32 s29, s35, 0
	s_add_u32 s24, s24, 0x100080
	s_addc_u32 s25, s25, 0
	s_add_i32 m0, s21, 0xc000
	ds_read_b128 v[170:173], v156
	ds_read_b128 v[174:177], v156 offset:1024
	ds_read_b128 v[178:181], v156 offset:2048
	ds_read_b128 v[182:185], v156 offset:3072
	ds_read_b128 v[186:189], v156 offset:4096
	ds_read_b128 v[190:193], v156 offset:5120
	ds_read_b128 v[194:197], v156 offset:6144
	ds_read_b128 v[198:201], v156 offset:7168
	s_nop 0
	global_load_lds_dwordx4 v205, s[24:25]
	s_add_i32 m0, s21, 0xe000
	s_nop 0
	global_load_lds_dwordx4 v203, s[24:25]
	s_waitcnt vmcnt(8)
	s_waitcnt lgkmcnt(0)
	s_barrier
	s_setprio 1
	s_waitcnt lgkmcnt(0)
	v_mfma_f32_16x16x32_bf16 v[124:127], v[128:131], v[170:173], v[124:127]
	v_mfma_f32_16x16x32_bf16 v[120:123], v[136:139], v[170:173], v[120:123]
	v_mfma_f32_16x16x32_bf16 v[116:119], v[128:131], v[178:181], v[116:119]
	v_mfma_f32_16x16x32_bf16 v[112:115], v[136:139], v[178:181], v[112:115]
	v_mfma_f32_16x16x32_bf16 v[108:111], v[128:131], v[186:189], v[108:111]
	v_mfma_f32_16x16x32_bf16 v[104:107], v[136:139], v[186:189], v[104:107]
	v_mfma_f32_16x16x32_bf16 v[100:103], v[128:131], v[194:197], v[100:103]
	v_mfma_f32_16x16x32_bf16 v[96:99], v[136:139], v[194:197], v[96:99]
	v_mfma_f32_16x16x32_bf16 v[124:127], v[132:135], v[174:177], v[124:127]
	v_mfma_f32_16x16x32_bf16 v[120:123], v[140:143], v[174:177], v[120:123]
	v_mfma_f32_16x16x32_bf16 v[116:119], v[132:135], v[182:185], v[116:119]
	v_mfma_f32_16x16x32_bf16 v[112:115], v[140:143], v[182:185], v[112:115]
	v_mfma_f32_16x16x32_bf16 v[108:111], v[132:135], v[190:193], v[108:111]
	v_mfma_f32_16x16x32_bf16 v[104:107], v[140:143], v[190:193], v[104:107]
	v_mfma_f32_16x16x32_bf16 v[100:103], v[132:135], v[198:201], v[100:103]
	v_mfma_f32_16x16x32_bf16 v[96:99], v[140:143], v[198:201], v[96:99]
	s_setprio 0
	s_setprio 1
	v_mfma_f32_16x16x32_bf16 v[60:63], v[144:147], v[170:173], v[60:63]
	v_mfma_f32_16x16x32_bf16 v[56:59], v[162:165], v[170:173], v[56:59]
	v_mfma_f32_16x16x32_bf16 v[52:55], v[144:147], v[178:181], v[52:55]
	v_mfma_f32_16x16x32_bf16 v[48:51], v[162:165], v[178:181], v[48:51]
	v_mfma_f32_16x16x32_bf16 v[44:47], v[144:147], v[186:189], v[44:47]
	v_mfma_f32_16x16x32_bf16 v[40:43], v[162:165], v[186:189], v[40:43]
	v_mfma_f32_16x16x32_bf16 v[36:39], v[144:147], v[194:197], v[36:39]
	v_mfma_f32_16x16x32_bf16 v[32:35], v[162:165], v[194:197], v[32:35]
	v_mfma_f32_16x16x32_bf16 v[60:63], v[158:161], v[174:177], v[60:63]
	v_mfma_f32_16x16x32_bf16 v[56:59], v[166:169], v[174:177], v[56:59]
	v_mfma_f32_16x16x32_bf16 v[52:55], v[158:161], v[182:185], v[52:55]
	v_mfma_f32_16x16x32_bf16 v[48:51], v[166:169], v[182:185], v[48:51]
	s_setprio 2
	s_barrier
	v_mfma_f32_16x16x32_bf16 v[44:47], v[158:161], v[190:193], v[44:47]
	v_mfma_f32_16x16x32_bf16 v[40:43], v[166:169], v[190:193], v[40:43]
	v_mfma_f32_16x16x32_bf16 v[36:39], v[158:161], v[198:201], v[36:39]
	v_mfma_f32_16x16x32_bf16 v[32:35], v[166:169], v[198:201], v[32:35]
	s_setprio 0
	s_add_i32 s54, s47, s33
	s_mov_b64 s[24:25], s[30:31]
	s_mov_b32 m0, s54
	ds_read_b128 v[170:173], v156 offset:16384
	ds_read_b128 v[174:177], v156 offset:17408
	ds_read_b128 v[178:181], v156 offset:18432
	ds_read_b128 v[182:185], v156 offset:19456
	ds_read_b128 v[186:189], v156 offset:20480
	ds_read_b128 v[190:193], v156 offset:21504
	ds_read_b128 v[194:197], v156 offset:22528
	ds_read_b128 v[198:201], v156 offset:23552
	s_nop 0
	global_load_lds_dwordx4 v202, s[24:25]
	s_add_i32 m0, s54, 0x2000
	s_nop 0
	global_load_lds_dwordx4 v204, s[24:25]
	s_add_u32 s24, s30, 0x100000
	s_addc_u32 s25, s31, 0
	s_add_i32 s54, s48, s33
	s_mov_b32 m0, s54
	s_nop 0
	global_load_lds_dwordx4 v202, s[24:25]
	s_add_i32 m0, s54, 0x2000
	s_nop 0
	global_load_lds_dwordx4 v204, s[24:25]
	s_mov_b64 s[24:25], s[34:35]
	s_mov_b32 m0, s21
	s_nop 0
	global_load_lds_dwordx4 v205, s[24:25]
	s_mov_b32 m0, s23
	s_nop 0
	global_load_lds_dwordx4 v203, s[24:25]
	s_waitcnt vmcnt(8)
	s_waitcnt lgkmcnt(0)
	s_barrier
	s_setprio 1
	s_waitcnt lgkmcnt(0)
	v_mfma_f32_16x16x32_bf16 v[92:95], v[128:131], v[170:173], v[92:95]
	v_mfma_f32_16x16x32_bf16 v[88:91], v[136:139], v[170:173], v[88:91]
	v_mfma_f32_16x16x32_bf16 v[84:87], v[128:131], v[178:181], v[84:87]
	v_mfma_f32_16x16x32_bf16 v[80:83], v[136:139], v[178:181], v[80:83]
	v_mfma_f32_16x16x32_bf16 v[76:79], v[128:131], v[186:189], v[76:79]
	v_mfma_f32_16x16x32_bf16 v[72:75], v[136:139], v[186:189], v[72:75]
	v_mfma_f32_16x16x32_bf16 v[68:71], v[128:131], v[194:197], v[68:71]
	v_mfma_f32_16x16x32_bf16 v[64:67], v[136:139], v[194:197], v[64:67]
	v_mfma_f32_16x16x32_bf16 v[92:95], v[132:135], v[174:177], v[92:95]
	v_mfma_f32_16x16x32_bf16 v[88:91], v[140:143], v[174:177], v[88:91]
	v_mfma_f32_16x16x32_bf16 v[84:87], v[132:135], v[182:185], v[84:87]
	v_mfma_f32_16x16x32_bf16 v[80:83], v[140:143], v[182:185], v[80:83]
	v_mfma_f32_16x16x32_bf16 v[76:79], v[132:135], v[190:193], v[76:79]
	v_mfma_f32_16x16x32_bf16 v[72:75], v[140:143], v[190:193], v[72:75]
	v_mfma_f32_16x16x32_bf16 v[68:71], v[132:135], v[198:201], v[68:71]
	v_mfma_f32_16x16x32_bf16 v[64:67], v[140:143], v[198:201], v[64:67]
	s_setprio 0
	s_setprio 1
	v_mfma_f32_16x16x32_bf16 v[28:31], v[144:147], v[170:173], v[28:31]
	v_mfma_f32_16x16x32_bf16 v[24:27], v[162:165], v[170:173], v[24:27]
	v_mfma_f32_16x16x32_bf16 v[20:23], v[144:147], v[178:181], v[20:23]
	v_mfma_f32_16x16x32_bf16 v[16:19], v[162:165], v[178:181], v[16:19]
	v_mfma_f32_16x16x32_bf16 v[12:15], v[144:147], v[186:189], v[12:15]
	v_mfma_f32_16x16x32_bf16 v[8:11], v[162:165], v[186:189], v[8:11]
	v_mfma_f32_16x16x32_bf16 v[4:7], v[144:147], v[194:197], v[4:7]
	v_mfma_f32_16x16x32_bf16 v[0:3], v[162:165], v[194:197], v[0:3]
	v_mfma_f32_16x16x32_bf16 v[28:31], v[158:161], v[174:177], v[28:31]
	v_mfma_f32_16x16x32_bf16 v[24:27], v[166:169], v[174:177], v[24:27]
	v_mfma_f32_16x16x32_bf16 v[20:23], v[158:161], v[182:185], v[20:23]
	v_mfma_f32_16x16x32_bf16 v[16:19], v[166:169], v[182:185], v[16:19]
	s_setprio 2
	s_barrier
; #define PG8_STAGE(bufoff, gbase, voff) do { const char* gb_ = (const char*)(gbase); asm volatile("" : "+s"(gb_));     \
;         _Pragma("unroll") for (int _i = 0; _i < 2; ++_i) \
;         __builtin_amdgcn_global_load_lds((const unsigned*)(gb_ + (voff)[_i]), (PG8_LAS unsigned*)(lds + (bufoff) + ldsw + _i * 8192), 16, 0, 0); } while (0)
; #define PG8_LDA(dst, b, h) do { _Pragma("unroll") for (int m = 0; m < 4; ++m) _Pragma("unroll") for (int k = 0; k < 2; ++k) dst[m][k] = *(const PG8_LAS bf16x8*)(lds + PG8_SA(b, h) + aoff + m * 2048 + k * 1024); } while (0)
; #define PG8_LDB(dst, b, h) do { _Pragma("unroll") for (int n = 0; n < 2; ++n) _Pragma("unroll") for (int k = 0; k < 2; ++k) dst[n][k] = *(const PG8_LAS bf16x8*)(lds + PG8_SB(b, h) + boff + n * 2048 + k * 1024); } while (0)
; #define PG8_MMA(ai, bj, At, Bt) do { __builtin_amdgcn_s_setprio(1); _Pragma("unroll") for (int m = 0; m < 4; ++m) _Pragma("unroll") for (int n = 0; n < 2; ++n) _Pragma("unroll") for (int k = 0; k < 2; ++k) \
;         acc[ai][bj][m][n] = __builtin_amdgcn_mfma_f32_16x16x32_bf16(Bt[n][k], At[m][k], acc[ai][bj][m][n], 0, 0, 0); __builtin_amdgcn_s_setprio(0); } while (0)
; #define PG8_WAIT_V(n) asm volatile("s_waitcnt vmcnt(" #n ")" ::: "memory")
; #define PG8_WAIT_L(n) asm volatile("s_waitcnt lgkmcnt(" #n ")" ::: "memory")
; #define PG8_BAR __builtin_amdgcn_s_barrier()
; #define PG8_SCHED __builtin_amdgcn_sched_barrier(0)
; template <class Epi, class Sched, bool ALIGN_EPI = false, bool SP2 = false>
; __device__ __forceinline__ void gemm_phase(PG8_LAS unsigned char* lds, const Gemm g, const Sched& S, const Epi& E, int wid0) {
;     ...
;             PG8_WAIT_V(8); PG8_WAIT_L(0); PG8_BAR; PG8_MMA(1, 0, At, B0); PG8_MMA(1, 1, At, B1); PG8_BAR; PG8_SCHED;
;             PG8_LDB(B0, 1, 0); PG8_LDB(B1, 1, 1); PG8_SCHED; PG8_LDA(At, 1, 0); PG8_STAGE(PG8_SA(0, 1), a2 + hstepA, vA_);
;             PG8_WAIT_V(8); PG8_WAIT_L(0); PG8_BAR; PG8_MMA(0, 0, At, B0); PG8_MMA(0, 1, At, B1); PG8_BAR; PG8_SCHED;
	v_mfma_f32_16x16x32_bf16 v[12:15], v[158:161], v[190:193], v[12:15]
	v_mfma_f32_16x16x32_bf16 v[8:11], v[166:169], v[190:193], v[8:11]
	v_mfma_f32_16x16x32_bf16 v[4:7], v[158:161], v[198:201], v[4:7]
	v_mfma_f32_16x16x32_bf16 v[0:3], v[166:169], v[198:201], v[0:3]
	s_setprio 0
	s_add_i32 s54, 0, 0x18000
	s_add_i32 s55, 0, 0x1c000
	v_add_u32_e32 v140, s54, v149
	v_add_u32_e32 v166, s55, v149
	ds_read_b128 v[128:131], v140
	ds_read_b128 v[132:135], v140 offset:1024
	ds_read_b128 v[136:139], v140 offset:2048
	ds_read_b128 v[140:143], v140 offset:3072
	ds_read_b128 v[144:147], v166
	ds_read_b128 v[158:161], v166 offset:1024
	ds_read_b128 v[162:165], v166 offset:2048
	ds_read_b128 v[166:169], v166 offset:3072
	s_add_u32 s24, s34, 0x100000
	s_addc_u32 s25, s35, 0
	s_mov_b32 m0, s40
	ds_read_b128 v[170:173], v156 offset:32768
	ds_read_b128 v[174:177], v156 offset:33792
	ds_read_b128 v[178:181], v156 offset:34816
	ds_read_b128 v[182:185], v156 offset:35840
	ds_read_b128 v[186:189], v156 offset:36864
	ds_read_b128 v[190:193], v156 offset:37888
	ds_read_b128 v[194:197], v156 offset:38912
	ds_read_b128 v[198:201], v156 offset:39936
	s_nop 0
	global_load_lds_dwordx4 v205, s[24:25]
	s_mov_b32 m0, s41
	s_nop 0
	global_load_lds_dwordx4 v203, s[24:25]
	s_waitcnt vmcnt(8)
	s_waitcnt lgkmcnt(0)
	s_barrier
	s_setprio 1
	s_waitcnt lgkmcnt(0)
	v_mfma_f32_16x16x32_bf16 v[124:127], v[128:131], v[170:173], v[124:127]
	v_mfma_f32_16x16x32_bf16 v[120:123], v[136:139], v[170:173], v[120:123]
	v_mfma_f32_16x16x32_bf16 v[116:119], v[128:131], v[178:181], v[116:119]
	v_mfma_f32_16x16x32_bf16 v[112:115], v[136:139], v[178:181], v[112:115]
	v_mfma_f32_16x16x32_bf16 v[108:111], v[128:131], v[186:189], v[108:111]
	v_mfma_f32_16x16x32_bf16 v[104:107], v[136:139], v[186:189], v[104:107]
	v_mfma_f32_16x16x32_bf16 v[100:103], v[128:131], v[194:197], v[100:103]
	v_mfma_f32_16x16x32_bf16 v[96:99], v[136:139], v[194:197], v[96:99]
	v_mfma_f32_16x16x32_bf16 v[124:127], v[132:135], v[174:177], v[124:127]
	v_mfma_f32_16x16x32_bf16 v[120:123], v[140:143], v[174:177], v[120:123]
	v_mfma_f32_16x16x32_bf16 v[116:119], v[132:135], v[182:185], v[116:119]
	v_mfma_f32_16x16x32_bf16 v[112:115], v[140:143], v[182:185], v[112:115]
	v_mfma_f32_16x16x32_bf16 v[108:111], v[132:135], v[190:193], v[108:111]
	v_mfma_f32_16x16x32_bf16 v[104:107], v[140:143], v[190:193], v[104:107]
	v_mfma_f32_16x16x32_bf16 v[100:103], v[132:135], v[198:201], v[100:103]
	v_mfma_f32_16x16x32_bf16 v[96:99], v[140:143], v[198:201], v[96:99]
	s_setprio 0
	s_setprio 1
	v_mfma_f32_16x16x32_bf16 v[60:63], v[144:147], v[170:173], v[60:63]
	v_mfma_f32_16x16x32_bf16 v[56:59], v[162:165], v[170:173], v[56:59]
	v_mfma_f32_16x16x32_bf16 v[52:55], v[144:147], v[178:181], v[52:55]
	v_mfma_f32_16x16x32_bf16 v[48:51], v[162:165], v[178:181], v[48:51]
	v_mfma_f32_16x16x32_bf16 v[44:47], v[144:147], v[186:189], v[44:47]
	v_mfma_f32_16x16x32_bf16 v[40:43], v[162:165], v[186:189], v[40:43]
	v_mfma_f32_16x16x32_bf16 v[36:39], v[144:147], v[194:197], v[36:39]
	v_mfma_f32_16x16x32_bf16 v[32:35], v[162:165], v[194:197], v[32:35]
	v_mfma_f32_16x16x32_bf16 v[60:63], v[158:161], v[174:177], v[60:63]
	v_mfma_f32_16x16x32_bf16 v[56:59], v[166:169], v[174:177], v[56:59]
	v_mfma_f32_16x16x32_bf16 v[52:55], v[158:161], v[182:185], v[52:55]
	v_mfma_f32_16x16x32_bf16 v[48:51], v[166:169], v[182:185], v[48:51]
	s_setprio 2
	s_barrier
; #define PG8_STAGE(bufoff, gbase, voff) do { const char* gb_ = (const char*)(gbase); asm volatile("" : "+s"(gb_));     \
;         _Pragma("unroll") for (int _i = 0; _i < 2; ++_i) \
;         __builtin_amdgcn_global_load_lds((const unsigned*)(gb_ + (voff)[_i]), (PG8_LAS unsigned*)(lds + (bufoff) + ldsw + _i * 8192), 16, 0, 0); } while (0)
; #define PG8_LDA(dst, b, h) do { _Pragma("unroll") for (int m = 0; m < 4; ++m) _Pragma("unroll") for (int k = 0; k < 2; ++k) dst[m][k] = *(const PG8_LAS bf16x8*)(lds + PG8_SA(b, h) + aoff + m * 2048 + k * 1024); } while (0)
; #define PG8_MMA(ai, bj, At, Bt) do { __builtin_amdgcn_s_setprio(1); _Pragma("unroll") for (int m = 0; m < 4; ++m) _Pragma("unroll") for (int n = 0; n < 2; ++n) _Pragma("unroll") for (int k = 0; k < 2; ++k) \
;         acc[ai][bj][m][n] = __builtin_amdgcn_mfma_f32_16x16x32_bf16(Bt[n][k], At[m][k], acc[ai][bj][m][n], 0, 0, 0); __builtin_amdgcn_s_setprio(0); } while (0)
; #define PG8_WAIT_V(n) asm volatile("s_waitcnt vmcnt(" #n ")" ::: "memory")
; #define PG8_WAIT_L(n) asm volatile("s_waitcnt lgkmcnt(" #n ")" ::: "memory")
; #define PG8_BAR __builtin_amdgcn_s_barrier()
; #define PG8_SCHED __builtin_amdgcn_sched_barrier(0)
; template <class Epi, class Sched, bool ALIGN_EPI = false, bool SP2 = false>
; __device__ __forceinline__ void gemm_phase(PG8_LAS unsigned char* lds, const Gemm g, const Sched& S, const Epi& E, int wid0) {
;     ...
;             PG8_WAIT_V(8); PG8_WAIT_L(0); PG8_BAR; PG8_MMA(0, 0, At, B0); PG8_MMA(0, 1, At, B1); PG8_BAR; PG8_SCHED;
;             PG8_LDA(At, 1, 1); PG8_STAGE(PG8_SB(1, 0), b3, vB_); PG8_STAGE(PG8_SB(1, 1), b3 + hstep, vB_); PG8_STAGE(PG8_SA(1, 0), a3, vA_);
;             PG8_WAIT_V(8); PG8_WAIT_L(0); PG8_BAR; PG8_MMA(1, 0, At, B0); PG8_MMA(1, 1, At, B1); PG8_BAR; PG8_SCHED;
	v_mfma_f32_16x16x32_bf16 v[44:47], v[158:161], v[190:193], v[44:47]
	v_mfma_f32_16x16x32_bf16 v[40:43], v[166:169], v[190:193], v[40:43]
	v_mfma_f32_16x16x32_bf16 v[36:39], v[158:161], v[198:201], v[36:39]
	v_mfma_f32_16x16x32_bf16 v[32:35], v[166:169], v[198:201], v[32:35]
	s_setprio 0
	s_add_u32 s24, s30, 0x80
	s_addc_u32 s25, s31, 0
	s_add_i32 s34, s54, s33
	s_mov_b32 m0, s34
	ds_read_b128 v[170:173], v156 offset:49152
	ds_read_b128 v[174:177], v156 offset:50176
	ds_read_b128 v[178:181], v156 offset:51200
	ds_read_b128 v[182:185], v156 offset:52224
	ds_read_b128 v[186:189], v156 offset:53248
	ds_read_b128 v[190:193], v156 offset:54272
	ds_read_b128 v[194:197], v156 offset:55296
	ds_read_b128 v[198:201], v156 offset:56320
	s_nop 0
	global_load_lds_dwordx4 v202, s[24:25]
	s_add_i32 m0, s34, 0x2000
	s_nop 0
	global_load_lds_dwordx4 v204, s[24:25]
	s_add_u32 s24, s30, 0x100080
	s_addc_u32 s25, s31, 0
	s_add_i32 s30, s55, s33
	s_mov_b32 m0, s30
	s_nop 0
	global_load_lds_dwordx4 v202, s[24:25]
	s_add_i32 m0, s30, 0x2000
	s_nop 0
	global_load_lds_dwordx4 v204, s[24:25]
	s_mov_b32 m0, s45
	s_nop 0
	global_load_lds_dwordx4 v205, s[28:29]
	s_mov_b32 m0, s46
	s_nop 0
	global_load_lds_dwordx4 v203, s[28:29]
	s_waitcnt vmcnt(8)
	s_waitcnt lgkmcnt(0)
	s_barrier
	s_setprio 1
	s_waitcnt lgkmcnt(0)
	v_mfma_f32_16x16x32_bf16 v[92:95], v[128:131], v[170:173], v[92:95]
	v_mfma_f32_16x16x32_bf16 v[88:91], v[136:139], v[170:173], v[88:91]
	v_mfma_f32_16x16x32_bf16 v[84:87], v[128:131], v[178:181], v[84:87]
	v_mfma_f32_16x16x32_bf16 v[80:83], v[136:139], v[178:181], v[80:83]
	v_mfma_f32_16x16x32_bf16 v[76:79], v[128:131], v[186:189], v[76:79]
	v_mfma_f32_16x16x32_bf16 v[72:75], v[136:139], v[186:189], v[72:75]
	v_mfma_f32_16x16x32_bf16 v[68:71], v[128:131], v[194:197], v[68:71]
	v_mfma_f32_16x16x32_bf16 v[64:67], v[136:139], v[194:197], v[64:67]
	v_mfma_f32_16x16x32_bf16 v[92:95], v[132:135], v[174:177], v[92:95]
	v_mfma_f32_16x16x32_bf16 v[88:91], v[140:143], v[174:177], v[88:91]
	v_mfma_f32_16x16x32_bf16 v[84:87], v[132:135], v[182:185], v[84:87]
	v_mfma_f32_16x16x32_bf16 v[80:83], v[140:143], v[182:185], v[80:83]
	v_mfma_f32_16x16x32_bf16 v[76:79], v[132:135], v[190:193], v[76:79]
	v_mfma_f32_16x16x32_bf16 v[72:75], v[140:143], v[190:193], v[72:75]
	v_mfma_f32_16x16x32_bf16 v[68:71], v[132:135], v[198:201], v[68:71]
	v_mfma_f32_16x16x32_bf16 v[64:67], v[140:143], v[198:201], v[64:67]
	s_setprio 0
	s_setprio 1
	v_mfma_f32_16x16x32_bf16 v[28:31], v[144:147], v[170:173], v[28:31]
	v_mfma_f32_16x16x32_bf16 v[24:27], v[162:165], v[170:173], v[24:27]
	v_mfma_f32_16x16x32_bf16 v[20:23], v[144:147], v[178:181], v[20:23]
	v_mfma_f32_16x16x32_bf16 v[16:19], v[162:165], v[178:181], v[16:19]
	v_mfma_f32_16x16x32_bf16 v[12:15], v[144:147], v[186:189], v[12:15]
	v_mfma_f32_16x16x32_bf16 v[8:11], v[162:165], v[186:189], v[8:11]
	v_mfma_f32_16x16x32_bf16 v[4:7], v[144:147], v[194:197], v[4:7]
	v_mfma_f32_16x16x32_bf16 v[0:3], v[162:165], v[194:197], v[0:3]
	v_mfma_f32_16x16x32_bf16 v[28:31], v[158:161], v[174:177], v[28:31]
	v_mfma_f32_16x16x32_bf16 v[24:27], v[166:169], v[174:177], v[24:27]
	v_mfma_f32_16x16x32_bf16 v[20:23], v[158:161], v[182:185], v[20:23]
	v_mfma_f32_16x16x32_bf16 v[16:19], v[166:169], v[182:185], v[16:19]
	s_setprio 2
	s_barrier
	v_mfma_f32_16x16x32_bf16 v[12:15], v[158:161], v[190:193], v[12:15]
	v_mfma_f32_16x16x32_bf16 v[8:11], v[166:169], v[190:193], v[8:11]
	v_mfma_f32_16x16x32_bf16 v[4:7], v[158:161], v[198:201], v[4:7]
	v_mfma_f32_16x16x32_bf16 v[0:3], v[166:169], v[198:201], v[0:3]
	s_setprio 0
	s_add_i32 s53, s53, 2
	s_add_u32 s51, s51, 0x100
	s_addc_u32 s52, s52, 0
	s_cmp_gt_u32 s53, 61
	s_mov_b64 s[24:25], s[26:27]
	s_cbranch_scc0 .LBB13_2163
	s_and_b64 vcc, exec, s[8:9]
	s_cbranch_vccz .LBB13_2166
	s_barrier
